# merged K-loops + peeled first trip + redundant canonicalizing v_max folded into the -20 clamp (377 sites in the GEMM epilogues)
# speedup vs baseline: 1.0252x; 1.0011x over previous
; #define PG8_STAGE(bufoff, gbase, voff) do { _Pragma("unroll") for (int _i = 0; _i < 2; ++_i) \
;         __builtin_amdgcn_global_load_lds((const unsigned*)((const char*)(gbase) + (voff)[_i]), (PG8_LAS unsigned*)(lds + (bufoff) + ldsw + _i * 8192), 16, 0, 0); } while (0)
; #define PG8_LDA(dst, b, h) do { _Pragma("unroll") for (int m = 0; m < 4; ++m) _Pragma("unroll") for (int k = 0; k < 2; ++k) dst[m][k] = *(const PG8_LAS bf16x8*)(lds + PG8_SA(b, h) + aoff + m * 2048 + k * 1024); } while (0)
; #define PG8_LDB(dst, b, h) do { _Pragma("unroll") for (int n = 0; n < 2; ++n) _Pragma("unroll") for (int k = 0; k < 2; ++k) dst[n][k] = *(const PG8_LAS bf16x8*)(lds + PG8_SB(b, h) + boff + n * 2048 + k * 1024); } while (0)
; #define PG8_MMA(ai, bj, At, Bt) do { __builtin_amdgcn_s_setprio(1); _Pragma("unroll") for (int m = 0; m < 4; ++m) _Pragma("unroll") for (int n = 0; n < 2; ++n) _Pragma("unroll") for (int k = 0; k < 2; ++k) \
;         acc[ai][bj][m][n] = __builtin_amdgcn_mfma_f32_16x16x32_bf16(Bt[n][k], At[m][k], acc[ai][bj][m][n], 0, 0, 0); __builtin_amdgcn_s_setprio(0); } while (0)
; #define PG8_WAIT_V(n) asm volatile("s_waitcnt vmcnt(" #n ")" ::: "memory")
; #define PG8_WAIT_L(n) asm volatile("s_waitcnt lgkmcnt(" #n ")" ::: "memory")
; template <class Epi, class Sched>
; __device__ __forceinline__ void gemm_phase(PG8_LAS unsigned char* lds, const Gemm g, const Sched& S, const Epi& E) {
;     ...
;             const bool last = (t == nt - 2);
;             const char* a1 = cA + (size_t)(t + 1) * kstep;
;             const char* a2 = last ? nA : cA + (size_t)(t + 2) * kstep; const char* b2 = last ? nB : cB + (size_t)(t + 2) * kstep;
;             const char* a3 = a2 + kstep; const char* b3 = b2 + kstep;
;             if (last && has_next) S.a_ready(nxt);
;             PG8_LDB(B0, 0, 0); PG8_SCHED; PG8_LDA(At, 0, 0); PG8_STAGE(PG8_SA(1, 1), a1 + hstep, voffA);
;             PG8_WAIT_L(8); PG8_BAR; PG8_WAIT_L(0); PG8_MMA(0, 0, At, B0); PG8_BAR; PG8_SCHED;
;             PG8_LDB(B1, 0, 1); PG8_STAGE(PG8_SB(0, 0), b2, voffB);
;             PG8_BAR; PG8_WAIT_L(0); PG8_MMA(0, 1, At, B1); PG8_BAR;
;             PG8_LDA(At, 0, 1); PG8_STAGE(PG8_SA(0, 0), a2, voffA);
;             PG8_BAR; PG8_WAIT_L(0); PG8_MMA(1, 0, At, B0); PG8_BAR; PG8_SCHED;
;             PG8_STAGE(PG8_SB(0, 1), b2 + hstep, voffB);
;             PG8_WAIT_V(6); PG8_BAR; PG8_MMA(1, 1, At, B1); PG8_BAR;
.LBB0_195:
	ds_read_b128 v[144:147], v151
	ds_read_b128 v[156:159], v151 offset:1024
	ds_read_b128 v[160:163], v151 offset:2048
	ds_read_b128 v[166:169], v151 offset:3072
	s_add_u32 s30, s28, 0xfffc0080
	s_addc_u32 s31, s29, -1
	s_cmp_eq_u32 s58, 12
	s_cselect_b32 s35, s17, s31
	s_cselect_b32 s34, s54, s30
	s_cselect_b32 s31, s15, s57
	s_cselect_b32 s30, s55, s56
	v_lshl_add_u64 v[174:175], s[28:29], 0, v[136:137]
	s_add_i32 m0, s27, 0xc000
	ds_read_b128 v[170:173], v153
	ds_read_b128 v[182:185], v153 offset:1024
	ds_read_b128 v[190:193], v153 offset:2048
	ds_read_b128 v[194:197], v153 offset:3072
	ds_read_b128 v[198:201], v153 offset:4096
	ds_read_b128 v[202:205], v153 offset:5120
	ds_read_b128 v[206:209], v153 offset:6144
	ds_read_b128 v[210:213], v153 offset:7168
	global_load_lds_dwordx4 v[174:175], off
	v_lshl_add_u64 v[174:175], s[28:29], 0, v[138:139]
	s_add_i32 m0, s27, 0xe000
	s_nop 0
	global_load_lds_dwordx4 v[174:175], off
	s_waitcnt lgkmcnt(8)
	ds_read_b128 v[214:217], v154
	ds_read_b128 v[218:221], v154 offset:1024
	ds_read_b128 v[222:225], v154 offset:2048
	ds_read_b128 v[226:229], v154 offset:3072
	s_waitcnt vmcnt(8) lgkmcnt(0)
	s_barrier
	v_mfma_f32_16x16x32_bf16 v[124:127], v[144:147], v[170:173], v[124:127]
	v_mfma_f32_16x16x32_bf16 v[120:123], v[160:163], v[170:173], v[120:123]
	v_mfma_f32_16x16x32_bf16 v[108:111], v[144:147], v[190:193], v[108:111]
	v_mfma_f32_16x16x32_bf16 v[104:107], v[160:163], v[190:193], v[104:107]
	v_mfma_f32_16x16x32_bf16 v[92:95], v[144:147], v[198:201], v[92:95]
	v_mfma_f32_16x16x32_bf16 v[88:91], v[160:163], v[198:201], v[88:91]
	v_mfma_f32_16x16x32_bf16 v[76:79], v[144:147], v[206:209], v[76:79]
	v_mfma_f32_16x16x32_bf16 v[72:75], v[160:163], v[206:209], v[72:75]
	v_mfma_f32_16x16x32_bf16 v[124:127], v[156:159], v[182:185], v[124:127]
	v_mfma_f32_16x16x32_bf16 v[120:123], v[166:169], v[182:185], v[120:123]
	v_mfma_f32_16x16x32_bf16 v[108:111], v[156:159], v[194:197], v[108:111]
	v_mfma_f32_16x16x32_bf16 v[104:107], v[166:169], v[194:197], v[104:107]
	v_mfma_f32_16x16x32_bf16 v[92:95], v[156:159], v[202:205], v[92:95]
	v_mfma_f32_16x16x32_bf16 v[88:91], v[166:169], v[202:205], v[88:91]
	v_mfma_f32_16x16x32_bf16 v[76:79], v[156:159], v[210:213], v[76:79]
	v_mfma_f32_16x16x32_bf16 v[72:75], v[166:169], v[210:213], v[72:75]
	v_mfma_f32_16x16x32_bf16 v[116:119], v[214:217], v[170:173], v[116:119]
	v_mfma_f32_16x16x32_bf16 v[112:115], v[222:225], v[170:173], v[112:115]
	v_mfma_f32_16x16x32_bf16 v[100:103], v[214:217], v[190:193], v[100:103]
	v_mfma_f32_16x16x32_bf16 v[96:99], v[222:225], v[190:193], v[96:99]
	v_mfma_f32_16x16x32_bf16 v[84:87], v[214:217], v[198:201], v[84:87]
	v_mfma_f32_16x16x32_bf16 v[80:83], v[222:225], v[198:201], v[80:83]
	v_mfma_f32_16x16x32_bf16 v[68:71], v[214:217], v[206:209], v[68:71]
	v_mfma_f32_16x16x32_bf16 v[64:67], v[222:225], v[206:209], v[64:67]
	v_mfma_f32_16x16x32_bf16 v[116:119], v[218:221], v[182:185], v[116:119]
	v_mfma_f32_16x16x32_bf16 v[112:115], v[226:229], v[182:185], v[112:115]
	v_mfma_f32_16x16x32_bf16 v[100:103], v[218:221], v[194:197], v[100:103]
	v_mfma_f32_16x16x32_bf16 v[96:99], v[226:229], v[194:197], v[96:99]
	v_mfma_f32_16x16x32_bf16 v[84:87], v[218:221], v[202:205], v[84:87]
	v_mfma_f32_16x16x32_bf16 v[80:83], v[226:229], v[202:205], v[80:83]
	v_mfma_f32_16x16x32_bf16 v[68:71], v[218:221], v[210:213], v[68:71]
	v_mfma_f32_16x16x32_bf16 v[64:67], v[226:229], v[210:213], v[64:67]
	s_barrier
	ds_read_b128 v[170:173], v153 offset:16384
	ds_read_b128 v[182:185], v153 offset:17408
	ds_read_b128 v[190:193], v153 offset:18432
	ds_read_b128 v[194:197], v153 offset:19456
	ds_read_b128 v[198:201], v153 offset:20480
	ds_read_b128 v[202:205], v153 offset:21504
	ds_read_b128 v[206:209], v153 offset:22528
	ds_read_b128 v[210:213], v153 offset:23552
	s_add_i32 s59, s50, s40
	v_lshl_add_u64 v[174:175], s[30:31], 0, v[132:133]
	s_mov_b32 m0, s59
	s_nop 0
	global_load_lds_dwordx4 v[174:175], off
	v_lshl_add_u64 v[178:179], s[30:31], 0, v[128:129]
	s_add_i32 m0, s59, 0x2000
	s_nop 0
	global_load_lds_dwordx4 v[178:179], off
	s_nop 1
	s_mov_b32 m0, s27
	v_lshl_add_u64 v[186:187], s[34:35], 0, v[134:135]
	global_load_lds_dwordx4 v[186:187], off
	v_lshl_add_u64 v[230:231], s[34:35], 0, v[130:131]
	s_mov_b32 m0, s43
	s_nop 0
	global_load_lds_dwordx4 v[230:231], off
	s_add_u32 s60, s30, 0x40000
	s_addc_u32 s61, s31, 0
	s_add_i32 s59, s51, s40
	v_lshl_add_u64 v[246:247], s[60:61], 0, v[132:133]
	s_mov_b32 m0, s59
	s_nop 0
	global_load_lds_dwordx4 v[246:247], off
	v_lshl_add_u64 v[246:247], s[60:61], 0, v[128:129]
	s_add_i32 m0, s59, 0x2000
	s_nop 0
	global_load_lds_dwordx4 v[246:247], off
	s_waitcnt vmcnt(8) lgkmcnt(0)
	s_barrier
; #define PG8_STAGE(bufoff, gbase, voff) do { _Pragma("unroll") for (int _i = 0; _i < 2; ++_i) \
;         __builtin_amdgcn_global_load_lds((const unsigned*)((const char*)(gbase) + (voff)[_i]), (PG8_LAS unsigned*)(lds + (bufoff) + ldsw + _i * 8192), 16, 0, 0); } while (0)
; #define PG8_LDA(dst, b, h) do { _Pragma("unroll") for (int m = 0; m < 4; ++m) _Pragma("unroll") for (int k = 0; k < 2; ++k) dst[m][k] = *(const PG8_LAS bf16x8*)(lds + PG8_SA(b, h) + aoff + m * 2048 + k * 1024); } while (0)
; #define PG8_LDB(dst, b, h) do { _Pragma("unroll") for (int n = 0; n < 2; ++n) _Pragma("unroll") for (int k = 0; k < 2; ++k) dst[n][k] = *(const PG8_LAS bf16x8*)(lds + PG8_SB(b, h) + boff + n * 2048 + k * 1024); } while (0)
; #define PG8_WAIT_V(n) asm volatile("s_waitcnt vmcnt(" #n ")" ::: "memory")
; #define PG8_WAIT_L(n) asm volatile("s_waitcnt lgkmcnt(" #n ")" ::: "memory")
; #define PG8_BAR __builtin_amdgcn_s_barrier()
; #define PG8_SCHED __builtin_amdgcn_sched_barrier(0)
; template <class Epi, class Sched>
; __device__ __forceinline__ void gemm_phase(PG8_LAS unsigned char* lds, const Gemm g, const Sched& S, const Epi& E) {
;     ...
;             PG8_LDB(B0, 0, 0); PG8_SCHED; PG8_LDA(At, 0, 0); PG8_STAGE(PG8_SA(1, 1), a1 + hstep, voffA);
;             PG8_WAIT_L(8); PG8_BAR; PG8_WAIT_L(0); PG8_MMA(0, 0, At, B0); PG8_BAR; PG8_SCHED;
;             PG8_LDB(B1, 0, 1); PG8_STAGE(PG8_SB(0, 0), b2, voffB);
;             PG8_BAR; PG8_WAIT_L(0); PG8_MMA(0, 1, At, B1); PG8_BAR;
;             PG8_LDA(At, 0, 1); PG8_STAGE(PG8_SA(0, 0), a2, voffA);
;             PG8_BAR; PG8_WAIT_L(0); PG8_MMA(1, 0, At, B0); PG8_BAR; PG8_SCHED;
;             PG8_STAGE(PG8_SB(0, 1), b2 + hstep, voffB);
;             PG8_WAIT_V(6); PG8_BAR; PG8_MMA(1, 1, At, B1); PG8_BAR;
;             PG8_LDB(B0, 1, 0); PG8_SCHED; PG8_LDA(At, 1, 0); PG8_STAGE(PG8_SA(0, 1), a2 + hstep, voffA);
;             PG8_WAIT_L(8); PG8_BAR; PG8_WAIT_L(0); PG8_MMA(0, 0, At, B0); PG8_BAR; PG8_SCHED;
;             PG8_LDB(B1, 1, 1); PG8_STAGE(PG8_SB(1, 0), b3, voffB);
;             PG8_BAR; PG8_WAIT_L(0); PG8_MMA(0, 1, At, B1); PG8_BAR;
;             PG8_LDA(At, 1, 1); PG8_STAGE(PG8_SA(1, 0), a3, voffA);
;             PG8_BAR; PG8_WAIT_L(0); PG8_MMA(1, 0, At, B0); PG8_BAR; PG8_SCHED;
;             PG8_STAGE(PG8_SB(1, 1), b3 + hstep, voffB);
;             PG8_WAIT_V(6); PG8_BAR; PG8_MMA(1, 1, At, B1); PG8_BAR;
	v_mfma_f32_16x16x32_bf16 v[60:63], v[144:147], v[170:173], v[60:63]
	v_mfma_f32_16x16x32_bf16 v[56:59], v[160:163], v[170:173], v[56:59]
	v_mfma_f32_16x16x32_bf16 v[44:47], v[144:147], v[190:193], v[44:47]
	v_mfma_f32_16x16x32_bf16 v[40:43], v[160:163], v[190:193], v[40:43]
	v_mfma_f32_16x16x32_bf16 v[28:31], v[144:147], v[198:201], v[28:31]
	v_mfma_f32_16x16x32_bf16 v[24:27], v[160:163], v[198:201], v[24:27]
	v_mfma_f32_16x16x32_bf16 v[12:15], v[144:147], v[206:209], v[12:15]
	v_mfma_f32_16x16x32_bf16 v[8:11], v[160:163], v[206:209], v[8:11]
	v_mfma_f32_16x16x32_bf16 v[60:63], v[156:159], v[182:185], v[60:63]
	v_mfma_f32_16x16x32_bf16 v[56:59], v[166:169], v[182:185], v[56:59]
	v_mfma_f32_16x16x32_bf16 v[44:47], v[156:159], v[194:197], v[44:47]
	v_mfma_f32_16x16x32_bf16 v[40:43], v[166:169], v[194:197], v[40:43]
	v_mfma_f32_16x16x32_bf16 v[28:31], v[156:159], v[202:205], v[28:31]
	v_mfma_f32_16x16x32_bf16 v[24:27], v[166:169], v[202:205], v[24:27]
	v_mfma_f32_16x16x32_bf16 v[12:15], v[156:159], v[210:213], v[12:15]
	v_mfma_f32_16x16x32_bf16 v[8:11], v[166:169], v[210:213], v[8:11]
	v_mfma_f32_16x16x32_bf16 v[52:55], v[214:217], v[170:173], v[52:55]
	v_mfma_f32_16x16x32_bf16 v[48:51], v[222:225], v[170:173], v[48:51]
	v_mfma_f32_16x16x32_bf16 v[36:39], v[214:217], v[190:193], v[36:39]
	v_mfma_f32_16x16x32_bf16 v[32:35], v[222:225], v[190:193], v[32:35]
	v_mfma_f32_16x16x32_bf16 v[20:23], v[214:217], v[198:201], v[20:23]
	v_mfma_f32_16x16x32_bf16 v[16:19], v[222:225], v[198:201], v[16:19]
	v_mfma_f32_16x16x32_bf16 v[4:7], v[214:217], v[206:209], v[4:7]
	v_mfma_f32_16x16x32_bf16 v[0:3], v[222:225], v[206:209], v[0:3]
	v_mfma_f32_16x16x32_bf16 v[52:55], v[218:221], v[182:185], v[52:55]
	v_mfma_f32_16x16x32_bf16 v[48:51], v[226:229], v[182:185], v[48:51]
	v_mfma_f32_16x16x32_bf16 v[36:39], v[218:221], v[194:197], v[36:39]
	v_mfma_f32_16x16x32_bf16 v[32:35], v[226:229], v[194:197], v[32:35]
	v_mfma_f32_16x16x32_bf16 v[20:23], v[218:221], v[202:205], v[20:23]
	v_mfma_f32_16x16x32_bf16 v[16:19], v[226:229], v[202:205], v[16:19]
	v_mfma_f32_16x16x32_bf16 v[4:7], v[218:221], v[210:213], v[4:7]
	v_mfma_f32_16x16x32_bf16 v[0:3], v[226:229], v[210:213], v[0:3]
	s_barrier
	s_add_i32 s59, 0, 0x18000
	v_add_u32_e32 v155, s59, v149
	ds_read_b128 v[144:147], v155
	ds_read_b128 v[156:159], v155 offset:1024
	ds_read_b128 v[160:163], v155 offset:2048
	ds_read_b128 v[166:169], v155 offset:3072
	s_add_u32 s34, s34, 0x40000
	s_addc_u32 s35, s35, 0
	s_mov_b32 m0, s44
	v_lshl_add_u64 v[214:215], s[34:35], 0, v[134:135]
	ds_read_b128 v[170:173], v153 offset:32768
	ds_read_b128 v[182:185], v153 offset:33792
	ds_read_b128 v[190:193], v153 offset:34816
	ds_read_b128 v[194:197], v153 offset:35840
	ds_read_b128 v[198:201], v153 offset:36864
	ds_read_b128 v[202:205], v153 offset:37888
	ds_read_b128 v[206:209], v153 offset:38912
	ds_read_b128 v[210:213], v153 offset:39936
	global_load_lds_dwordx4 v[214:215], off
	v_lshl_add_u64 v[214:215], s[34:35], 0, v[130:131]
	s_mov_b32 m0, s45
	s_nop 0
	global_load_lds_dwordx4 v[214:215], off
	s_add_i32 s34, 0, 0x1c000
	v_add_u32_e32 v155, s34, v149
	s_waitcnt lgkmcnt(8)
	ds_read_b128 v[214:217], v155
	ds_read_b128 v[218:221], v155 offset:1024
	ds_read_b128 v[222:225], v155 offset:2048
	ds_read_b128 v[226:229], v155 offset:3072
	s_waitcnt vmcnt(8) lgkmcnt(0)
	s_barrier
	v_mfma_f32_16x16x32_bf16 v[124:127], v[144:147], v[170:173], v[124:127]
	v_mfma_f32_16x16x32_bf16 v[120:123], v[160:163], v[170:173], v[120:123]
	v_mfma_f32_16x16x32_bf16 v[108:111], v[144:147], v[190:193], v[108:111]
	v_mfma_f32_16x16x32_bf16 v[104:107], v[160:163], v[190:193], v[104:107]
	v_mfma_f32_16x16x32_bf16 v[92:95], v[144:147], v[198:201], v[92:95]
	v_mfma_f32_16x16x32_bf16 v[88:91], v[160:163], v[198:201], v[88:91]
	v_mfma_f32_16x16x32_bf16 v[76:79], v[144:147], v[206:209], v[76:79]
	v_mfma_f32_16x16x32_bf16 v[72:75], v[160:163], v[206:209], v[72:75]
	v_mfma_f32_16x16x32_bf16 v[124:127], v[156:159], v[182:185], v[124:127]
	v_mfma_f32_16x16x32_bf16 v[120:123], v[166:169], v[182:185], v[120:123]
	v_mfma_f32_16x16x32_bf16 v[108:111], v[156:159], v[194:197], v[108:111]
	v_mfma_f32_16x16x32_bf16 v[104:107], v[166:169], v[194:197], v[104:107]
	v_mfma_f32_16x16x32_bf16 v[92:95], v[156:159], v[202:205], v[92:95]
	v_mfma_f32_16x16x32_bf16 v[88:91], v[166:169], v[202:205], v[88:91]
	v_mfma_f32_16x16x32_bf16 v[76:79], v[156:159], v[210:213], v[76:79]
	v_mfma_f32_16x16x32_bf16 v[72:75], v[166:169], v[210:213], v[72:75]
	v_mfma_f32_16x16x32_bf16 v[116:119], v[214:217], v[170:173], v[116:119]
	v_mfma_f32_16x16x32_bf16 v[112:115], v[222:225], v[170:173], v[112:115]
	v_mfma_f32_16x16x32_bf16 v[100:103], v[214:217], v[190:193], v[100:103]
	v_mfma_f32_16x16x32_bf16 v[96:99], v[222:225], v[190:193], v[96:99]
	v_mfma_f32_16x16x32_bf16 v[84:87], v[214:217], v[198:201], v[84:87]
	v_mfma_f32_16x16x32_bf16 v[80:83], v[222:225], v[198:201], v[80:83]
	v_mfma_f32_16x16x32_bf16 v[68:71], v[214:217], v[206:209], v[68:71]
	v_mfma_f32_16x16x32_bf16 v[64:67], v[222:225], v[206:209], v[64:67]
	v_mfma_f32_16x16x32_bf16 v[116:119], v[218:221], v[182:185], v[116:119]
	v_mfma_f32_16x16x32_bf16 v[112:115], v[226:229], v[182:185], v[112:115]
	v_mfma_f32_16x16x32_bf16 v[100:103], v[218:221], v[194:197], v[100:103]
	v_mfma_f32_16x16x32_bf16 v[96:99], v[226:229], v[194:197], v[96:99]
	v_mfma_f32_16x16x32_bf16 v[84:87], v[218:221], v[202:205], v[84:87]
	v_mfma_f32_16x16x32_bf16 v[80:83], v[226:229], v[202:205], v[80:83]
	v_mfma_f32_16x16x32_bf16 v[68:71], v[218:221], v[210:213], v[68:71]
	v_mfma_f32_16x16x32_bf16 v[64:67], v[226:229], v[210:213], v[64:67]
	s_barrier
; __device__ __forceinline__ unsigned cvt_pk_bf16(float lo, float hi) { unsigned r; asm volatile("v_cvt_pk_bf16_f32 %0, %1, %2" : "=v"(r) : "v"(lo), "v"(hi)); return r; }
; #define PG8_STAGE(bufoff, gbase, voff) do { _Pragma("unroll") for (int _i = 0; _i < 2; ++_i) \
;         __builtin_amdgcn_global_load_lds((const unsigned*)((const char*)(gbase) + (voff)[_i]), (PG8_LAS unsigned*)(lds + (bufoff) + ldsw + _i * 8192), 16, 0, 0); } while (0)
; #define PG8_LDA(dst, b, h) do { _Pragma("unroll") for (int m = 0; m < 4; ++m) _Pragma("unroll") for (int k = 0; k < 2; ++k) dst[m][k] = *(const PG8_LAS bf16x8*)(lds + PG8_SA(b, h) + aoff + m * 2048 + k * 1024); } while (0)
; #define PG8_WAIT_V(n) asm volatile("s_waitcnt vmcnt(" #n ")" ::: "memory")
;     __device__ __forceinline__ void operator()(const f32x4 (&acc)[2][2][4][2], const Unit& u, int wr, int wc, int fr, int fq) const {
;         const int row0 = u.pm * BM + wr * 64 + fr, col0 = u.pn * HALF + wc * 32 + 8 * fq;
; #pragma unroll
;         for (int ai = 0; ai < 2; ++ai)
; #pragma unroll
;             for (int m = 0; m < 4; ++m) { bf16_t* rowp = O + (size_t)(row0 + ai * HALF + m * 16) * ldc + col0;
;                 f32x4 v0, v1;
; #pragma unroll
;                 for (int j = 0; j < 1; ++j) { v0 = acc[ai][0][m][0] * sigmoid4(acc[ai][0][m][0]) * acc[ai][1][m][0]; v1 = acc[ai][0][m][1] * sigmoid4(acc[ai][0][m][1]) * acc[ai][1][m][1]; }
;                 u32x4 w; w.x = cvt_pk_bf16(v0[0], v0[1]); w.y = cvt_pk_bf16(v0[2], v0[3]); w.z = cvt_pk_bf16(v1[0], v1[1]); w.w = cvt_pk_bf16(v1[2], v1[3]);
;                 *(u32x4*)rowp = w; }
; template <class Epi, class Sched>
; __device__ __forceinline__ void gemm_phase(PG8_LAS unsigned char* lds, const Gemm g, const Sched& S, const Epi& E) {
;     ...
;             PG8_LDB(B0, 1, 0); PG8_SCHED; PG8_LDA(At, 1, 0); PG8_STAGE(PG8_SA(0, 1), a2 + hstep, voffA);
;             PG8_WAIT_L(8); PG8_BAR; PG8_WAIT_L(0); PG8_MMA(0, 0, At, B0); PG8_BAR; PG8_SCHED;
;             PG8_LDB(B1, 1, 1); PG8_STAGE(PG8_SB(1, 0), b3, voffB);
;             PG8_BAR; PG8_WAIT_L(0); PG8_MMA(0, 1, At, B1); PG8_BAR;
;             PG8_LDA(At, 1, 1); PG8_STAGE(PG8_SA(1, 0), a3, voffA);
;             PG8_BAR; PG8_WAIT_L(0); PG8_MMA(1, 0, At, B0); PG8_BAR; PG8_SCHED;
;             PG8_STAGE(PG8_SB(1, 1), b3 + hstep, voffB);
;             PG8_WAIT_V(6); PG8_BAR; PG8_MMA(1, 1, At, B1); PG8_BAR;
	ds_read_b128 v[170:173], v153 offset:49152
	ds_read_b128 v[182:185], v153 offset:50176
	ds_read_b128 v[190:193], v153 offset:51200
	ds_read_b128 v[194:197], v153 offset:52224
	ds_read_b128 v[198:201], v153 offset:53248
	ds_read_b128 v[202:205], v153 offset:54272
	ds_read_b128 v[206:209], v153 offset:55296
	ds_read_b128 v[210:213], v153 offset:56320
	s_add_i32 s35, s59, s40
	v_lshl_add_u64 v[174:175], v[174:175], 0, s[10:11]
	s_mov_b32 m0, s35
	s_nop 0
	global_load_lds_dwordx4 v[174:175], off
	v_lshl_add_u64 v[174:175], v[178:179], 0, s[10:11]
	s_add_i32 m0, s35, 0x2000
	s_nop 0
	global_load_lds_dwordx4 v[174:175], off
	s_nop 1
	s_mov_b32 m0, s47
	v_lshl_add_u64 v[174:175], v[186:187], 0, s[10:11]
	global_load_lds_dwordx4 v[174:175], off
	v_lshl_add_u64 v[174:175], v[230:231], 0, s[10:11]
	s_mov_b32 m0, s48
	s_nop 0
	global_load_lds_dwordx4 v[174:175], off
	s_add_u32 s30, s30, 0x40080
	s_addc_u32 s31, s31, 0
	s_add_i32 s34, s34, s40
	v_lshl_add_u64 v[246:247], s[30:31], 0, v[132:133]
	s_mov_b32 m0, s34
	s_nop 0
	global_load_lds_dwordx4 v[246:247], off
	v_lshl_add_u64 v[246:247], s[30:31], 0, v[128:129]
	s_add_i32 m0, s34, 0x2000
	s_nop 0
	global_load_lds_dwordx4 v[246:247], off
	s_waitcnt vmcnt(8) lgkmcnt(0)
	s_barrier
	v_mfma_f32_16x16x32_bf16 v[60:63], v[144:147], v[170:173], v[60:63]
	v_mfma_f32_16x16x32_bf16 v[56:59], v[160:163], v[170:173], v[56:59]
	v_mfma_f32_16x16x32_bf16 v[44:47], v[144:147], v[190:193], v[44:47]
	v_mfma_f32_16x16x32_bf16 v[40:43], v[160:163], v[190:193], v[40:43]
	v_mfma_f32_16x16x32_bf16 v[28:31], v[144:147], v[198:201], v[28:31]
	v_mfma_f32_16x16x32_bf16 v[24:27], v[160:163], v[198:201], v[24:27]
	v_mfma_f32_16x16x32_bf16 v[12:15], v[144:147], v[206:209], v[12:15]
	v_mfma_f32_16x16x32_bf16 v[8:11], v[160:163], v[206:209], v[8:11]
	v_mfma_f32_16x16x32_bf16 v[60:63], v[156:159], v[182:185], v[60:63]
	v_mfma_f32_16x16x32_bf16 v[56:59], v[166:169], v[182:185], v[56:59]
	v_mfma_f32_16x16x32_bf16 v[44:47], v[156:159], v[194:197], v[44:47]
	v_mfma_f32_16x16x32_bf16 v[40:43], v[166:169], v[194:197], v[40:43]
	v_mfma_f32_16x16x32_bf16 v[28:31], v[156:159], v[202:205], v[28:31]
	v_mfma_f32_16x16x32_bf16 v[24:27], v[166:169], v[202:205], v[24:27]
	v_mfma_f32_16x16x32_bf16 v[12:15], v[156:159], v[210:213], v[12:15]
	v_mfma_f32_16x16x32_bf16 v[8:11], v[166:169], v[210:213], v[8:11]
	v_mfma_f32_16x16x32_bf16 v[52:55], v[214:217], v[170:173], v[52:55]
	v_mfma_f32_16x16x32_bf16 v[48:51], v[222:225], v[170:173], v[48:51]
	v_mfma_f32_16x16x32_bf16 v[36:39], v[214:217], v[190:193], v[36:39]
	v_mfma_f32_16x16x32_bf16 v[32:35], v[222:225], v[190:193], v[32:35]
	v_mfma_f32_16x16x32_bf16 v[20:23], v[214:217], v[198:201], v[20:23]
	v_mfma_f32_16x16x32_bf16 v[16:19], v[222:225], v[198:201], v[16:19]
	v_mfma_f32_16x16x32_bf16 v[4:7], v[214:217], v[206:209], v[4:7]
	v_mfma_f32_16x16x32_bf16 v[0:3], v[222:225], v[206:209], v[0:3]
	v_mfma_f32_16x16x32_bf16 v[52:55], v[218:221], v[182:185], v[52:55]
	v_mfma_f32_16x16x32_bf16 v[48:51], v[226:229], v[182:185], v[48:51]
	v_mfma_f32_16x16x32_bf16 v[36:39], v[218:221], v[194:197], v[36:39]
	v_mfma_f32_16x16x32_bf16 v[32:35], v[226:229], v[194:197], v[32:35]
	v_mfma_f32_16x16x32_bf16 v[20:23], v[218:221], v[202:205], v[20:23]
	v_mfma_f32_16x16x32_bf16 v[16:19], v[226:229], v[202:205], v[16:19]
	v_mfma_f32_16x16x32_bf16 v[4:7], v[218:221], v[210:213], v[4:7]
	v_mfma_f32_16x16x32_bf16 v[0:3], v[226:229], v[210:213], v[0:3]
	s_barrier
	s_add_i32 s58, s58, 2
	s_add_u32 s28, s28, 0x100
	s_addc_u32 s29, s29, 0
	s_add_u32 s56, s56, 0x100
	s_addc_u32 s57, s57, 0
	s_cmp_gt_u32 s58, 13
	s_cbranch_scc0 .LBB0_195
	v_max_f32_e32 v144, 0xc1a00000, v124
	v_mul_f32_e32 v144, 0xbfb8aa3b, v144
	v_exp_f32_e32 v157, v144
	v_max_f32_e32 v144, 0xc1a00000, v125
	v_mul_f32_e32 v144, 0xbfb8aa3b, v144
	v_exp_f32_e32 v156, v144
	v_max_f32_e32 v144, 0xc1a00000, v126
	v_mul_f32_e32 v144, 0xbfb8aa3b, v144
	v_exp_f32_e32 v159, v144
	v_max_f32_e32 v144, 0xc1a00000, v127
	v_mul_f32_e32 v144, 0xbfb8aa3b, v144
	v_exp_f32_e32 v158, v144
	v_pk_add_f32 v[156:157], v[156:157], 1.0 op_sel_hi:[1,0]
	v_lshl_or_b32 v146, s53, 7, v150
	v_mov_b32_e32 v160, v157
	v_pk_add_f32 v[158:159], v[158:159], 1.0 op_sel_hi:[1,0]
	v_mov_b32_e32 v162, v156
	v_mov_b32_e32 v161, v159
	v_mov_b32_e32 v163, v158
	v_pk_mul_f32 v[160:161], v[160:161], v[162:163]
	v_lshl_add_u32 v155, s26, 8, v148
	v_mul_f32_e32 v162, v160, v161
	v_rcp_f32_e32 v166, v162
	v_ashrrev_i32_e32 v147, 31, v146
	v_mov_b64_e32 v[144:145], s[4:5]
	v_mad_i64_i32 v[162:163], s[28:29], v155, s52, v[144:145]
	v_mul_f32_e32 v160, v160, v166
	v_mul_f32_e32 v164, v161, v166
	v_pk_mul_f32 v[158:159], v[158:159], v[160:161] op_sel_hi:[1,0]
	v_max_f32_e32 v160, 0xc1a00000, v120
	v_max_f32_e32 v166, 0xc1a00000, v122
	v_mul_f32_e32 v160, 0xbfb8aa3b, v160
	v_mul_f32_e32 v166, 0xbfb8aa3b, v166
	v_exp_f32_e32 v161, v160
	v_exp_f32_e32 v167, v166
	v_max_f32_e32 v160, 0xc1a00000, v121
	v_max_f32_e32 v166, 0xc1a00000, v123
	v_mul_f32_e32 v160, 0xbfb8aa3b, v160
	v_mul_f32_e32 v166, 0xbfb8aa3b, v166
	v_exp_f32_e32 v160, v160
	v_exp_f32_e32 v166, v166
	v_pk_mul_f32 v[156:157], v[156:157], v[164:165] op_sel_hi:[1,0]
	v_pk_mul_f32 v[126:127], v[126:127], v[158:159]
	v_pk_mul_f32 v[124:125], v[124:125], v[156:157]
	v_pk_add_f32 v[156:157], v[160:161], 1.0 op_sel_hi:[1,0]
	v_pk_add_f32 v[160:161], v[166:167], 1.0 op_sel_hi:[1,0]
	v_mov_b32_e32 v166, v157
	v_mov_b32_e32 v167, v161
	v_mov_b32_e32 v168, v156
	v_mov_b32_e32 v169, v160
	v_pk_mul_f32 v[166:167], v[166:167], v[168:169]
	v_pk_mul_f32 v[118:119], v[126:127], v[118:119]
	v_mul_f32_e32 v164, v166, v167
	v_rcp_f32_e32 v164, v164
; __device__ __forceinline__ unsigned cvt_pk_bf16(float lo, float hi) { unsigned r; asm volatile("v_cvt_pk_bf16_f32 %0, %1, %2" : "=v"(r) : "v"(lo), "v"(hi)); return r; }
; __device__ __forceinline__ f32x4 sigmoid4(f32x4 x) {
;     f32x4 d;
; #pragma unroll
;     for (int j = 0; j < 4; ++j) d[j] = 1.0f + __expf(-fmaxf(x[j], -20.0f));
;     const float p01 = d[0] * d[1], p23 = d[2] * d[3], r = __builtin_amdgcn_rcpf(p01 * p23), r01 = r * p23, r23 = r * p01;
;     return (f32x4){r01 * d[1], r01 * d[0], r23 * d[3], r23 * d[2]};
;     __device__ __forceinline__ void operator()(const f32x4 (&acc)[2][2][4][2], const Unit& u, int wr, int wc, int fr, int fq) const {
;         const int row0 = u.pm * BM + wr * 64 + fr, col0 = u.pn * HALF + wc * 32 + 8 * fq;
; #pragma unroll
;         for (int ai = 0; ai < 2; ++ai)
; #pragma unroll
;             for (int m = 0; m < 4; ++m) { bf16_t* rowp = O + (size_t)(row0 + ai * HALF + m * 16) * ldc + col0;
;                 f32x4 v0, v1;
; #pragma unroll
;                 for (int j = 0; j < 1; ++j) { v0 = acc[ai][0][m][0] * sigmoid4(acc[ai][0][m][0]) * acc[ai][1][m][0]; v1 = acc[ai][0][m][1] * sigmoid4(acc[ai][0][m][1]) * acc[ai][1][m][1]; }
;                 u32x4 w; w.x = cvt_pk_bf16(v0[0], v0[1]); w.y = cvt_pk_bf16(v0[2], v0[3]); w.z = cvt_pk_bf16(v1[0], v1[1]); w.w = cvt_pk_bf16(v1[2], v1[3]);
;                 *(u32x4*)rowp = w; }
	v_pk_mul_f32 v[116:117], v[124:125], v[116:117]
	v_lshlrev_b64 v[146:147], 1, v[146:147]
	v_lshl_add_u64 v[162:163], v[162:163], 0, v[146:147]
	v_mul_f32_e32 v124, v167, v164
	v_mul_f32_e32 v126, v166, v164
	v_pk_mul_f32 v[126:127], v[160:161], v[126:127] op_sel_hi:[1,0]
	v_pk_mul_f32 v[124:125], v[156:157], v[124:125] op_sel_hi:[1,0]
	v_pk_mul_f32 v[122:123], v[122:123], v[126:127]
	v_pk_mul_f32 v[120:121], v[120:121], v[124:125]
	v_pk_mul_f32 v[122:123], v[122:123], v[114:115]
	v_pk_mul_f32 v[114:115], v[120:121], v[112:113]
	v_cvt_pk_bf16_f32 v112, v116, v117
	v_cvt_pk_bf16_f32 v113, v118, v119
	v_max_f32_e32 v116, 0xc1a00000, v108
	v_max_f32_e32 v118, 0xc1a00000, v110
	v_mul_f32_e32 v116, 0xbfb8aa3b, v116
	v_mul_f32_e32 v118, 0xbfb8aa3b, v118
	v_exp_f32_e32 v117, v116
	v_exp_f32_e32 v119, v118
	v_max_f32_e32 v116, 0xc1a00000, v109
	v_max_f32_e32 v118, 0xc1a00000, v111
	v_mul_f32_e32 v116, 0xbfb8aa3b, v116
	v_mul_f32_e32 v118, 0xbfb8aa3b, v118
	v_exp_f32_e32 v116, v116
	v_exp_f32_e32 v118, v118
	v_cvt_pk_bf16_f32 v114, v114, v115
	v_cvt_pk_bf16_f32 v115, v122, v123
	global_store_dwordx4 v[162:163], v[112:115], off
	v_or_b32_e32 v120, 16, v155
	s_and_b64 vcc, exec, s[2:3]
	v_pk_add_f32 v[112:113], v[116:117], 1.0 op_sel_hi:[1,0]
	v_pk_add_f32 v[114:115], v[118:119], 1.0 op_sel_hi:[1,0]
	v_mov_b32_e32 v116, v113
	v_mov_b32_e32 v117, v115
	v_mov_b32_e32 v118, v112
	v_mov_b32_e32 v119, v114
	v_pk_mul_f32 v[116:117], v[116:117], v[118:119]
	s_mov_b32 s53, s14
	v_mul_f32_e32 v118, v116, v117
	v_rcp_f32_e32 v121, v118
	v_mad_i64_i32 v[118:119], s[28:29], v120, s52, v[144:145]
	v_lshl_add_u64 v[118:119], v[118:119], 0, v[146:147]
	v_mul_f32_e32 v116, v116, v121
	v_mul_f32_e32 v120, v117, v121
	v_pk_mul_f32 v[114:115], v[114:115], v[116:117] op_sel_hi:[1,0]
	v_max_f32_e32 v116, 0xc1a00000, v104
	v_max_f32_e32 v121, 0xc1a00000, v106
	v_mul_f32_e32 v116, 0xbfb8aa3b, v116
	v_mul_f32_e32 v121, 0xbfb8aa3b, v121
	v_exp_f32_e32 v117, v116
	v_exp_f32_e32 v123, v121
	v_max_f32_e32 v116, 0xc1a00000, v105
	v_max_f32_e32 v121, 0xc1a00000, v107
	v_mul_f32_e32 v116, 0xbfb8aa3b, v116
	v_mul_f32_e32 v121, 0xbfb8aa3b, v121
	v_exp_f32_e32 v116, v116
	v_exp_f32_e32 v122, v121
	v_pk_mul_f32 v[112:113], v[112:113], v[120:121] op_sel_hi:[1,0]
	v_pk_mul_f32 v[110:111], v[110:111], v[114:115]
	v_pk_mul_f32 v[108:109], v[108:109], v[112:113]
	v_pk_add_f32 v[112:113], v[116:117], 1.0 op_sel_hi:[1,0]
	v_pk_add_f32 v[116:117], v[122:123], 1.0 op_sel_hi:[1,0]
	v_mov_b32_e32 v120, v113
	v_mov_b32_e32 v121, v117
	v_mov_b32_e32 v122, v112
	v_mov_b32_e32 v123, v116
	v_pk_mul_f32 v[120:121], v[120:121], v[122:123]
	v_pk_mul_f32 v[102:103], v[110:111], v[102:103]
	v_mul_f32_e32 v122, v120, v121
	v_rcp_f32_e32 v122, v122
	v_pk_mul_f32 v[100:101], v[108:109], v[100:101]
	s_mov_b32 s26, s16
	s_mov_b64 s[30:31], s[24:25]
	v_mul_f32_e32 v108, v121, v122
	v_mul_f32_e32 v110, v120, v122
	v_pk_mul_f32 v[110:111], v[116:117], v[110:111] op_sel_hi:[1,0]
	v_pk_mul_f32 v[108:109], v[112:113], v[108:109] op_sel_hi:[1,0]
	v_pk_mul_f32 v[106:107], v[106:107], v[110:111]
	v_pk_mul_f32 v[104:105], v[104:105], v[108:109]
	v_pk_mul_f32 v[106:107], v[106:107], v[98:99]
	v_pk_mul_f32 v[98:99], v[104:105], v[96:97]
	v_cvt_pk_bf16_f32 v96, v100, v101
	v_cvt_pk_bf16_f32 v97, v102, v103
	v_max_f32_e32 v100, 0xc1a00000, v92
	v_max_f32_e32 v102, 0xc1a00000, v94
	v_mul_f32_e32 v100, 0xbfb8aa3b, v100
	v_mul_f32_e32 v102, 0xbfb8aa3b, v102
	v_exp_f32_e32 v101, v100
	v_exp_f32_e32 v103, v102
	v_max_f32_e32 v100, 0xc1a00000, v93
	v_max_f32_e32 v102, 0xc1a00000, v95
	v_mul_f32_e32 v100, 0xbfb8aa3b, v100
	v_mul_f32_e32 v102, 0xbfb8aa3b, v102
	v_exp_f32_e32 v100, v100
	v_exp_f32_e32 v102, v102
	v_cvt_pk_bf16_f32 v98, v98, v99
	v_cvt_pk_bf16_f32 v99, v106, v107
	global_store_dwordx4 v[118:119], v[96:99], off
	v_or_b32_e32 v104, 32, v155
	s_nop 0
	v_pk_add_f32 v[96:97], v[100:101], 1.0 op_sel_hi:[1,0]
	v_pk_add_f32 v[98:99], v[102:103], 1.0 op_sel_hi:[1,0]
	v_mov_b32_e32 v100, v97
	v_mov_b32_e32 v101, v99
	v_mov_b32_e32 v102, v96
	v_mov_b32_e32 v103, v98
	v_pk_mul_f32 v[100:101], v[100:101], v[102:103]
	s_nop 0
	v_mul_f32_e32 v102, v100, v101
	v_rcp_f32_e32 v105, v102
	v_mad_i64_i32 v[102:103], s[28:29], v104, s52, v[144:145]
	v_lshl_add_u64 v[102:103], v[102:103], 0, v[146:147]
	v_mul_f32_e32 v100, v100, v105
	v_mul_f32_e32 v104, v101, v105
	v_pk_mul_f32 v[98:99], v[98:99], v[100:101] op_sel_hi:[1,0]
	v_max_f32_e32 v100, 0xc1a00000, v88
	v_max_f32_e32 v105, 0xc1a00000, v90
	v_mul_f32_e32 v100, 0xbfb8aa3b, v100
	v_mul_f32_e32 v105, 0xbfb8aa3b, v105
	v_exp_f32_e32 v101, v100
	v_exp_f32_e32 v107, v105
	v_max_f32_e32 v100, 0xc1a00000, v89
	v_max_f32_e32 v105, 0xc1a00000, v91
	v_mul_f32_e32 v100, 0xbfb8aa3b, v100
	v_mul_f32_e32 v105, 0xbfb8aa3b, v105
	v_exp_f32_e32 v100, v100
	v_exp_f32_e32 v106, v105
	v_pk_mul_f32 v[96:97], v[96:97], v[104:105] op_sel_hi:[1,0]
	v_pk_mul_f32 v[94:95], v[94:95], v[98:99]
	v_pk_mul_f32 v[92:93], v[92:93], v[96:97]
	v_pk_add_f32 v[96:97], v[100:101], 1.0 op_sel_hi:[1,0]
	v_pk_add_f32 v[100:101], v[106:107], 1.0 op_sel_hi:[1,0]
	v_mov_b32_e32 v104, v97
	v_mov_b32_e32 v105, v101
	v_mov_b32_e32 v106, v96
	v_mov_b32_e32 v107, v100
	v_pk_mul_f32 v[104:105], v[104:105], v[106:107]
	v_pk_mul_f32 v[86:87], v[94:95], v[86:87]
	v_mul_f32_e32 v106, v104, v105
	v_rcp_f32_e32 v106, v106
	v_pk_mul_f32 v[84:85], v[92:93], v[84:85]
	v_mul_f32_e32 v92, v105, v106
	v_mul_f32_e32 v94, v104, v106
	v_pk_mul_f32 v[94:95], v[100:101], v[94:95] op_sel_hi:[1,0]
	v_pk_mul_f32 v[92:93], v[96:97], v[92:93] op_sel_hi:[1,0]
	v_pk_mul_f32 v[90:91], v[90:91], v[94:95]
	v_pk_mul_f32 v[88:89], v[88:89], v[92:93]
; __device__ __forceinline__ unsigned cvt_pk_bf16(float lo, float hi) { unsigned r; asm volatile("v_cvt_pk_bf16_f32 %0, %1, %2" : "=v"(r) : "v"(lo), "v"(hi)); return r; }
; __device__ __forceinline__ f32x4 sigmoid4(f32x4 x) {
;     f32x4 d;
; #pragma unroll
;     for (int j = 0; j < 4; ++j) d[j] = 1.0f + __expf(-fmaxf(x[j], -20.0f));
;     const float p01 = d[0] * d[1], p23 = d[2] * d[3], r = __builtin_amdgcn_rcpf(p01 * p23), r01 = r * p23, r23 = r * p01;
;     return (f32x4){r01 * d[1], r01 * d[0], r23 * d[3], r23 * d[2]};
;     __device__ __forceinline__ void operator()(const f32x4 (&acc)[2][2][4][2], const Unit& u, int wr, int wc, int fr, int fq) const {
;         const int row0 = u.pm * BM + wr * 64 + fr, col0 = u.pn * HALF + wc * 32 + 8 * fq;
; #pragma unroll
;         for (int ai = 0; ai < 2; ++ai)
; #pragma unroll
;             for (int m = 0; m < 4; ++m) { bf16_t* rowp = O + (size_t)(row0 + ai * HALF + m * 16) * ldc + col0;
;                 f32x4 v0, v1;
; #pragma unroll
;                 for (int j = 0; j < 1; ++j) { v0 = acc[ai][0][m][0] * sigmoid4(acc[ai][0][m][0]) * acc[ai][1][m][0]; v1 = acc[ai][0][m][1] * sigmoid4(acc[ai][0][m][1]) * acc[ai][1][m][1]; }
;                 u32x4 w; w.x = cvt_pk_bf16(v0[0], v0[1]); w.y = cvt_pk_bf16(v0[2], v0[3]); w.z = cvt_pk_bf16(v1[0], v1[1]); w.w = cvt_pk_bf16(v1[2], v1[3]);
;                 *(u32x4*)rowp = w; }
	v_pk_mul_f32 v[90:91], v[90:91], v[82:83]
	v_pk_mul_f32 v[82:83], v[88:89], v[80:81]
	v_cvt_pk_bf16_f32 v80, v84, v85
	v_cvt_pk_bf16_f32 v81, v86, v87
	v_max_f32_e32 v84, 0xc1a00000, v76
	v_max_f32_e32 v86, 0xc1a00000, v78
	v_mul_f32_e32 v84, 0xbfb8aa3b, v84
	v_mul_f32_e32 v86, 0xbfb8aa3b, v86
	v_exp_f32_e32 v85, v84
	v_exp_f32_e32 v87, v86
	v_max_f32_e32 v84, 0xc1a00000, v77
	v_max_f32_e32 v86, 0xc1a00000, v79
	v_mul_f32_e32 v84, 0xbfb8aa3b, v84
	v_mul_f32_e32 v86, 0xbfb8aa3b, v86
	v_exp_f32_e32 v84, v84
	v_exp_f32_e32 v86, v86
	v_cvt_pk_bf16_f32 v82, v82, v83
	v_cvt_pk_bf16_f32 v83, v90, v91
	global_store_dwordx4 v[102:103], v[80:83], off
	v_or_b32_e32 v88, 48, v155
	s_nop 0
	v_pk_add_f32 v[80:81], v[84:85], 1.0 op_sel_hi:[1,0]
	v_pk_add_f32 v[82:83], v[86:87], 1.0 op_sel_hi:[1,0]
	v_mov_b32_e32 v84, v81
	v_mov_b32_e32 v85, v83
	v_mov_b32_e32 v86, v80
	v_mov_b32_e32 v87, v82
	v_pk_mul_f32 v[84:85], v[84:85], v[86:87]
	s_nop 0
	v_mul_f32_e32 v86, v84, v85
	v_rcp_f32_e32 v89, v86
	v_mad_i64_i32 v[86:87], s[28:29], v88, s52, v[144:145]
	v_lshl_add_u64 v[86:87], v[86:87], 0, v[146:147]
	v_mul_f32_e32 v84, v84, v89
	v_mul_f32_e32 v88, v85, v89
	v_pk_mul_f32 v[82:83], v[82:83], v[84:85] op_sel_hi:[1,0]
	v_max_f32_e32 v84, 0xc1a00000, v72
	v_max_f32_e32 v89, 0xc1a00000, v74
	v_mul_f32_e32 v84, 0xbfb8aa3b, v84
	v_mul_f32_e32 v89, 0xbfb8aa3b, v89
	v_exp_f32_e32 v85, v84
	v_exp_f32_e32 v91, v89
	v_max_f32_e32 v84, 0xc1a00000, v73
	v_max_f32_e32 v89, 0xc1a00000, v75
	v_mul_f32_e32 v84, 0xbfb8aa3b, v84
	v_mul_f32_e32 v89, 0xbfb8aa3b, v89
	v_exp_f32_e32 v84, v84
	v_exp_f32_e32 v90, v89
	v_pk_mul_f32 v[80:81], v[80:81], v[88:89] op_sel_hi:[1,0]
	v_pk_mul_f32 v[78:79], v[78:79], v[82:83]
	v_pk_mul_f32 v[76:77], v[76:77], v[80:81]
	v_pk_add_f32 v[80:81], v[84:85], 1.0 op_sel_hi:[1,0]
	v_pk_add_f32 v[84:85], v[90:91], 1.0 op_sel_hi:[1,0]
	v_mov_b32_e32 v88, v81
	v_mov_b32_e32 v89, v85
	v_mov_b32_e32 v90, v80
	v_mov_b32_e32 v91, v84
	v_pk_mul_f32 v[88:89], v[88:89], v[90:91]
	v_pk_mul_f32 v[70:71], v[78:79], v[70:71]
	v_mul_f32_e32 v90, v88, v89
	v_rcp_f32_e32 v90, v90
	v_pk_mul_f32 v[68:69], v[76:77], v[68:69]
	v_mul_f32_e32 v76, v89, v90
	v_mul_f32_e32 v78, v88, v90
	v_pk_mul_f32 v[78:79], v[84:85], v[78:79] op_sel_hi:[1,0]
	v_pk_mul_f32 v[76:77], v[80:81], v[76:77] op_sel_hi:[1,0]
	v_pk_mul_f32 v[74:75], v[74:75], v[78:79]
	v_pk_mul_f32 v[72:73], v[72:73], v[76:77]
	v_pk_mul_f32 v[74:75], v[74:75], v[66:67]
	v_pk_mul_f32 v[66:67], v[72:73], v[64:65]
	v_cvt_pk_bf16_f32 v64, v68, v69
	v_cvt_pk_bf16_f32 v65, v70, v71
	v_max_f32_e32 v68, 0xc1a00000, v60
	v_max_f32_e32 v70, 0xc1a00000, v62
	v_mul_f32_e32 v68, 0xbfb8aa3b, v68
	v_mul_f32_e32 v70, 0xbfb8aa3b, v70
	v_exp_f32_e32 v69, v68
	v_exp_f32_e32 v71, v70
	v_max_f32_e32 v68, 0xc1a00000, v61
	v_max_f32_e32 v70, 0xc1a00000, v63
	v_mul_f32_e32 v68, 0xbfb8aa3b, v68
	v_mul_f32_e32 v70, 0xbfb8aa3b, v70
	v_exp_f32_e32 v68, v68
	v_exp_f32_e32 v70, v70
	v_cvt_pk_bf16_f32 v66, v66, v67
	v_cvt_pk_bf16_f32 v67, v74, v75
	global_store_dwordx4 v[86:87], v[64:67], off
	v_add_u32_e32 v72, 0x80, v155
	s_nop 0
	v_pk_add_f32 v[64:65], v[68:69], 1.0 op_sel_hi:[1,0]
	v_pk_add_f32 v[66:67], v[70:71], 1.0 op_sel_hi:[1,0]
	v_mov_b32_e32 v68, v65
	v_mov_b32_e32 v69, v67
	v_mov_b32_e32 v70, v64
	v_mov_b32_e32 v71, v66
	v_pk_mul_f32 v[68:69], v[68:69], v[70:71]
	s_nop 0
	v_mul_f32_e32 v70, v68, v69
	v_rcp_f32_e32 v73, v70
	v_mad_i64_i32 v[70:71], s[28:29], v72, s52, v[144:145]
	v_lshl_add_u64 v[70:71], v[70:71], 0, v[146:147]
	v_mul_f32_e32 v68, v68, v73
	v_mul_f32_e32 v72, v69, v73
	v_pk_mul_f32 v[66:67], v[66:67], v[68:69] op_sel_hi:[1,0]
	v_max_f32_e32 v68, 0xc1a00000, v56
	v_max_f32_e32 v73, 0xc1a00000, v58
	v_mul_f32_e32 v68, 0xbfb8aa3b, v68
	v_mul_f32_e32 v73, 0xbfb8aa3b, v73
	v_exp_f32_e32 v69, v68
	v_exp_f32_e32 v75, v73
	v_max_f32_e32 v68, 0xc1a00000, v57
	v_max_f32_e32 v73, 0xc1a00000, v59
	v_mul_f32_e32 v68, 0xbfb8aa3b, v68
	v_mul_f32_e32 v73, 0xbfb8aa3b, v73
	v_exp_f32_e32 v68, v68
	v_exp_f32_e32 v74, v73
	v_pk_mul_f32 v[64:65], v[64:65], v[72:73] op_sel_hi:[1,0]
	v_pk_mul_f32 v[62:63], v[62:63], v[66:67]
	v_pk_mul_f32 v[60:61], v[60:61], v[64:65]
	v_pk_add_f32 v[64:65], v[68:69], 1.0 op_sel_hi:[1,0]
	v_pk_add_f32 v[68:69], v[74:75], 1.0 op_sel_hi:[1,0]
	v_mov_b32_e32 v72, v65
	v_mov_b32_e32 v73, v69
	v_mov_b32_e32 v74, v64
	v_mov_b32_e32 v75, v68
	v_pk_mul_f32 v[72:73], v[72:73], v[74:75]
	v_pk_mul_f32 v[54:55], v[62:63], v[54:55]
	v_mul_f32_e32 v74, v72, v73
	v_rcp_f32_e32 v74, v74
	v_pk_mul_f32 v[52:53], v[60:61], v[52:53]
	v_mul_f32_e32 v60, v73, v74
	v_mul_f32_e32 v62, v72, v74
	v_pk_mul_f32 v[62:63], v[68:69], v[62:63] op_sel_hi:[1,0]
	v_pk_mul_f32 v[60:61], v[64:65], v[60:61] op_sel_hi:[1,0]
	v_pk_mul_f32 v[58:59], v[58:59], v[62:63]
	v_pk_mul_f32 v[56:57], v[56:57], v[60:61]
	v_pk_mul_f32 v[58:59], v[58:59], v[50:51]
	v_pk_mul_f32 v[50:51], v[56:57], v[48:49]
	v_cvt_pk_bf16_f32 v48, v52, v53
	v_cvt_pk_bf16_f32 v49, v54, v55
	v_max_f32_e32 v52, 0xc1a00000, v44
	v_max_f32_e32 v54, 0xc1a00000, v46
	v_mul_f32_e32 v52, 0xbfb8aa3b, v52
	v_mul_f32_e32 v54, 0xbfb8aa3b, v54
	v_exp_f32_e32 v53, v52
	v_exp_f32_e32 v55, v54
	v_max_f32_e32 v52, 0xc1a00000, v45
	v_max_f32_e32 v54, 0xc1a00000, v47
	v_mul_f32_e32 v52, 0xbfb8aa3b, v52
	v_mul_f32_e32 v54, 0xbfb8aa3b, v54
	v_exp_f32_e32 v52, v52
	v_exp_f32_e32 v54, v54
	v_cvt_pk_bf16_f32 v50, v50, v51
	v_cvt_pk_bf16_f32 v51, v58, v59
	global_store_dwordx4 v[70:71], v[48:51], off
	v_add_u32_e32 v56, 0x90, v155
	s_nop 0
	v_pk_add_f32 v[48:49], v[52:53], 1.0 op_sel_hi:[1,0]
	v_pk_add_f32 v[50:51], v[54:55], 1.0 op_sel_hi:[1,0]
	v_mov_b32_e32 v52, v49
	v_mov_b32_e32 v53, v51
; __device__ __forceinline__ unsigned cvt_pk_bf16(float lo, float hi) { unsigned r; asm volatile("v_cvt_pk_bf16_f32 %0, %1, %2" : "=v"(r) : "v"(lo), "v"(hi)); return r; }
; __device__ __forceinline__ f32x4 sigmoid4(f32x4 x) {
;     f32x4 d;
; #pragma unroll
;     for (int j = 0; j < 4; ++j) d[j] = 1.0f + __expf(-fmaxf(x[j], -20.0f));
;     const float p01 = d[0] * d[1], p23 = d[2] * d[3], r = __builtin_amdgcn_rcpf(p01 * p23), r01 = r * p23, r23 = r * p01;
;     return (f32x4){r01 * d[1], r01 * d[0], r23 * d[3], r23 * d[2]};
;     __device__ __forceinline__ void operator()(const f32x4 (&acc)[2][2][4][2], const Unit& u, int wr, int wc, int fr, int fq) const {
;         const int row0 = u.pm * BM + wr * 64 + fr, col0 = u.pn * HALF + wc * 32 + 8 * fq;
; #pragma unroll
;         for (int ai = 0; ai < 2; ++ai)
; #pragma unroll
;             for (int m = 0; m < 4; ++m) { bf16_t* rowp = O + (size_t)(row0 + ai * HALF + m * 16) * ldc + col0;
;                 f32x4 v0, v1;
; #pragma unroll
;                 for (int j = 0; j < 1; ++j) { v0 = acc[ai][0][m][0] * sigmoid4(acc[ai][0][m][0]) * acc[ai][1][m][0]; v1 = acc[ai][0][m][1] * sigmoid4(acc[ai][0][m][1]) * acc[ai][1][m][1]; }
;                 u32x4 w; w.x = cvt_pk_bf16(v0[0], v0[1]); w.y = cvt_pk_bf16(v0[2], v0[3]); w.z = cvt_pk_bf16(v1[0], v1[1]); w.w = cvt_pk_bf16(v1[2], v1[3]);
;                 *(u32x4*)rowp = w; }
	v_mov_b32_e32 v54, v48
	v_mov_b32_e32 v55, v50
	v_pk_mul_f32 v[52:53], v[52:53], v[54:55]
	s_nop 0
	v_mul_f32_e32 v54, v52, v53
	v_rcp_f32_e32 v57, v54
	v_mad_i64_i32 v[54:55], s[28:29], v56, s52, v[144:145]
	v_lshl_add_u64 v[54:55], v[54:55], 0, v[146:147]
	v_mul_f32_e32 v52, v52, v57
	v_mul_f32_e32 v56, v53, v57
	v_pk_mul_f32 v[50:51], v[50:51], v[52:53] op_sel_hi:[1,0]
	v_max_f32_e32 v52, 0xc1a00000, v40
	v_max_f32_e32 v57, 0xc1a00000, v42
	v_mul_f32_e32 v52, 0xbfb8aa3b, v52
	v_mul_f32_e32 v57, 0xbfb8aa3b, v57
	v_exp_f32_e32 v53, v52
	v_exp_f32_e32 v59, v57
	v_max_f32_e32 v52, 0xc1a00000, v41
	v_max_f32_e32 v57, 0xc1a00000, v43
	v_mul_f32_e32 v52, 0xbfb8aa3b, v52
	v_mul_f32_e32 v57, 0xbfb8aa3b, v57
	v_exp_f32_e32 v52, v52
	v_exp_f32_e32 v58, v57
	v_pk_mul_f32 v[48:49], v[48:49], v[56:57] op_sel_hi:[1,0]
	v_pk_mul_f32 v[46:47], v[46:47], v[50:51]
	v_pk_mul_f32 v[44:45], v[44:45], v[48:49]
	v_pk_add_f32 v[48:49], v[52:53], 1.0 op_sel_hi:[1,0]
	v_pk_add_f32 v[52:53], v[58:59], 1.0 op_sel_hi:[1,0]
	v_mov_b32_e32 v56, v49
	v_mov_b32_e32 v57, v53
	v_mov_b32_e32 v58, v48
	v_mov_b32_e32 v59, v52
	v_pk_mul_f32 v[56:57], v[56:57], v[58:59]
	v_pk_mul_f32 v[38:39], v[46:47], v[38:39]
	v_mul_f32_e32 v58, v56, v57
	v_rcp_f32_e32 v58, v58
	v_pk_mul_f32 v[36:37], v[44:45], v[36:37]
	v_mul_f32_e32 v44, v57, v58
	v_mul_f32_e32 v46, v56, v58
	v_pk_mul_f32 v[46:47], v[52:53], v[46:47] op_sel_hi:[1,0]
	v_pk_mul_f32 v[44:45], v[48:49], v[44:45] op_sel_hi:[1,0]
	v_pk_mul_f32 v[42:43], v[42:43], v[46:47]
	v_pk_mul_f32 v[40:41], v[40:41], v[44:45]
	v_pk_mul_f32 v[42:43], v[42:43], v[34:35]
	v_pk_mul_f32 v[34:35], v[40:41], v[32:33]
	v_cvt_pk_bf16_f32 v32, v36, v37
	v_cvt_pk_bf16_f32 v33, v38, v39
	v_max_f32_e32 v36, 0xc1a00000, v28
	v_max_f32_e32 v38, 0xc1a00000, v30
	v_mul_f32_e32 v36, 0xbfb8aa3b, v36
	v_mul_f32_e32 v38, 0xbfb8aa3b, v38
	v_exp_f32_e32 v37, v36
	v_exp_f32_e32 v39, v38
	v_max_f32_e32 v36, 0xc1a00000, v29
	v_max_f32_e32 v38, 0xc1a00000, v31
	v_mul_f32_e32 v36, 0xbfb8aa3b, v36
	v_mul_f32_e32 v38, 0xbfb8aa3b, v38
	v_exp_f32_e32 v36, v36
	v_exp_f32_e32 v38, v38
	v_cvt_pk_bf16_f32 v34, v34, v35
	v_cvt_pk_bf16_f32 v35, v42, v43
	global_store_dwordx4 v[54:55], v[32:35], off
	v_add_u32_e32 v40, 0xa0, v155
	s_nop 0
	v_pk_add_f32 v[32:33], v[36:37], 1.0 op_sel_hi:[1,0]
	v_pk_add_f32 v[34:35], v[38:39], 1.0 op_sel_hi:[1,0]
	v_mov_b32_e32 v36, v33
	v_mov_b32_e32 v37, v35
	v_mov_b32_e32 v38, v32
	v_mov_b32_e32 v39, v34
	v_pk_mul_f32 v[36:37], v[36:37], v[38:39]
	s_nop 0
	v_mul_f32_e32 v38, v36, v37
	v_rcp_f32_e32 v41, v38
	v_mad_i64_i32 v[38:39], s[28:29], v40, s52, v[144:145]
	v_lshl_add_u64 v[38:39], v[38:39], 0, v[146:147]
	v_mul_f32_e32 v36, v36, v41
	v_mul_f32_e32 v40, v37, v41
	v_pk_mul_f32 v[34:35], v[34:35], v[36:37] op_sel_hi:[1,0]
	v_max_f32_e32 v36, 0xc1a00000, v24
	v_max_f32_e32 v41, 0xc1a00000, v26
	v_mul_f32_e32 v36, 0xbfb8aa3b, v36
	v_mul_f32_e32 v41, 0xbfb8aa3b, v41
	v_exp_f32_e32 v37, v36
	v_exp_f32_e32 v43, v41
	v_max_f32_e32 v36, 0xc1a00000, v25
	v_max_f32_e32 v41, 0xc1a00000, v27
	v_mul_f32_e32 v36, 0xbfb8aa3b, v36
	v_mul_f32_e32 v41, 0xbfb8aa3b, v41
	v_exp_f32_e32 v36, v36
	v_exp_f32_e32 v42, v41
	v_pk_mul_f32 v[32:33], v[32:33], v[40:41] op_sel_hi:[1,0]
	v_pk_mul_f32 v[30:31], v[30:31], v[34:35]
	v_pk_mul_f32 v[28:29], v[28:29], v[32:33]
	v_pk_add_f32 v[32:33], v[36:37], 1.0 op_sel_hi:[1,0]
	v_pk_add_f32 v[36:37], v[42:43], 1.0 op_sel_hi:[1,0]
	v_mov_b32_e32 v40, v33
	v_mov_b32_e32 v41, v37
	v_mov_b32_e32 v42, v32
	v_mov_b32_e32 v43, v36
	v_pk_mul_f32 v[40:41], v[40:41], v[42:43]
	v_pk_mul_f32 v[22:23], v[30:31], v[22:23]
	v_mul_f32_e32 v42, v40, v41
	v_rcp_f32_e32 v42, v42
	v_pk_mul_f32 v[20:21], v[28:29], v[20:21]
	v_mul_f32_e32 v28, v41, v42
	v_mul_f32_e32 v30, v40, v42
	v_pk_mul_f32 v[30:31], v[36:37], v[30:31] op_sel_hi:[1,0]
	v_pk_mul_f32 v[28:29], v[32:33], v[28:29] op_sel_hi:[1,0]
	v_pk_mul_f32 v[26:27], v[26:27], v[30:31]
	v_pk_mul_f32 v[24:25], v[24:25], v[28:29]
	v_pk_mul_f32 v[26:27], v[26:27], v[18:19]
	v_pk_mul_f32 v[18:19], v[24:25], v[16:17]
	v_cvt_pk_bf16_f32 v16, v20, v21
	v_cvt_pk_bf16_f32 v17, v22, v23
	v_max_f32_e32 v20, 0xc1a00000, v12
	v_max_f32_e32 v22, 0xc1a00000, v14
	v_mul_f32_e32 v20, 0xbfb8aa3b, v20
	v_mul_f32_e32 v22, 0xbfb8aa3b, v22
	v_exp_f32_e32 v21, v20
	v_exp_f32_e32 v23, v22
	v_max_f32_e32 v20, 0xc1a00000, v13
	v_max_f32_e32 v22, 0xc1a00000, v15
	v_mul_f32_e32 v20, 0xbfb8aa3b, v20
	v_mul_f32_e32 v22, 0xbfb8aa3b, v22
	v_exp_f32_e32 v20, v20
	v_exp_f32_e32 v22, v22
	v_cvt_pk_bf16_f32 v18, v18, v19
	v_cvt_pk_bf16_f32 v19, v26, v27
	global_store_dwordx4 v[38:39], v[16:19], off
	v_add_u32_e32 v24, 0xb0, v155
	s_nop 0
	v_pk_add_f32 v[16:17], v[20:21], 1.0 op_sel_hi:[1,0]
	v_pk_add_f32 v[18:19], v[22:23], 1.0 op_sel_hi:[1,0]
	v_mov_b32_e32 v20, v17
	v_mov_b32_e32 v21, v19
	v_mov_b32_e32 v22, v16
	v_mov_b32_e32 v23, v18
	v_pk_mul_f32 v[20:21], v[20:21], v[22:23]
	s_nop 0
	v_mul_f32_e32 v22, v20, v21
	v_rcp_f32_e32 v25, v22
	v_mad_i64_i32 v[22:23], s[28:29], v24, s52, v[144:145]
	v_lshl_add_u64 v[22:23], v[22:23], 0, v[146:147]
	v_mul_f32_e32 v20, v20, v25
	v_mul_f32_e32 v24, v21, v25
	v_pk_mul_f32 v[18:19], v[18:19], v[20:21] op_sel_hi:[1,0]
	v_max_f32_e32 v20, 0xc1a00000, v8
	v_max_f32_e32 v25, 0xc1a00000, v10
	v_mul_f32_e32 v20, 0xbfb8aa3b, v20
	v_mul_f32_e32 v25, 0xbfb8aa3b, v25
	v_exp_f32_e32 v21, v20
	v_exp_f32_e32 v27, v25
	v_max_f32_e32 v20, 0xc1a00000, v9
	v_max_f32_e32 v25, 0xc1a00000, v11
	v_mul_f32_e32 v20, 0xbfb8aa3b, v20
	v_mul_f32_e32 v25, 0xbfb8aa3b, v25
	v_exp_f32_e32 v20, v20
	v_exp_f32_e32 v26, v25
	v_pk_mul_f32 v[16:17], v[16:17], v[24:25] op_sel_hi:[1,0]
	v_pk_mul_f32 v[14:15], v[14:15], v[18:19]
	v_pk_mul_f32 v[12:13], v[12:13], v[16:17]
	v_pk_add_f32 v[16:17], v[20:21], 1.0 op_sel_hi:[1,0]
	v_pk_add_f32 v[20:21], v[26:27], 1.0 op_sel_hi:[1,0]
	v_mov_b32_e32 v24, v17
	v_mov_b32_e32 v25, v21
	v_mov_b32_e32 v26, v16
	v_mov_b32_e32 v27, v20
	v_pk_mul_f32 v[24:25], v[24:25], v[26:27]
	v_pk_mul_f32 v[6:7], v[14:15], v[6:7]
	v_mul_f32_e32 v26, v24, v25
	v_rcp_f32_e32 v26, v26
	v_pk_mul_f32 v[4:5], v[12:13], v[4:5]
	s_mov_b64 s[28:29], s[18:19]
	v_mul_f32_e32 v12, v25, v26
	v_mul_f32_e32 v14, v24, v26
	v_pk_mul_f32 v[14:15], v[20:21], v[14:15] op_sel_hi:[1,0]
	v_pk_mul_f32 v[12:13], v[16:17], v[12:13] op_sel_hi:[1,0]
	v_pk_mul_f32 v[10:11], v[10:11], v[14:15]
	v_pk_mul_f32 v[8:9], v[8:9], v[12:13]
	v_pk_mul_f32 v[10:11], v[10:11], v[2:3]
	v_pk_mul_f32 v[2:3], v[8:9], v[0:1]
	v_cvt_pk_bf16_f32 v0, v4, v5
	v_cvt_pk_bf16_f32 v1, v6, v7
	s_nop 0
	v_cvt_pk_bf16_f32 v2, v2, v3
	v_cvt_pk_bf16_f32 v3, v10, v11
	global_store_dwordx4 v[22:23], v[0:3], off
	s_cbranch_vccz .LBB0_192
	s_waitcnt vmcnt(0)
	s_cmpk_gt_u32 s37, 0xff
	s_cbranch_scc1 .LBB0_199
	s_barrier

; __device__ __forceinline__ f32x4 sigmoid4(f32x4 x) {
;     f32x4 d;
; #pragma unroll
;     for (int j = 0; j < 4; ++j) d[j] = 1.0f + __expf(-fmaxf(x[j], -20.0f));
;     const float p01 = d[0] * d[1], p23 = d[2] * d[3], r = __builtin_amdgcn_rcpf(p01 * p23), r01 = r * p23, r23 = r * p01;
;     return (f32x4){r01 * d[1], r01 * d[0], r23 * d[3], r23 * d[2]};
;     __device__ __forceinline__ void operator()(const f32x4 (&acc)[2][2][4][2], const Unit& u, int wr, int wc, int fr, int fq) const {
;     ...
;                 for (int bj = 0; bj < 2; ++bj) { f32x4 v0 = acc[ai][bj][m][0] + bv[bj][0], v1 = acc[ai][bj][m][1] + bv[bj][1];
;                     if (act == 1) {
; #pragma unroll
;                         for (int j = 0; j < 1; ++j) { v0 = v0 * sigmoid4(v0); v1 = v1 * sigmoid4(v1); } }
.LBB0_434:
	s_andn2_b64 vcc, exec, s[0:1]
	s_cbranch_vccnz .LBB0_436
	v_max_f32_e32 v144, 0xc1a00000, v140
	v_max_f32_e32 v146, 0xc1a00000, v142
	v_mul_f32_e32 v144, 0xbfb8aa3b, v144
	v_mul_f32_e32 v146, 0xbfb8aa3b, v146
	v_exp_f32_e32 v145, v144
	v_exp_f32_e32 v147, v146
	v_max_f32_e32 v144, 0xc1a00000, v141
	v_max_f32_e32 v146, 0xc1a00000, v143
	v_mul_f32_e32 v144, 0xbfb8aa3b, v144
	v_mul_f32_e32 v146, 0xbfb8aa3b, v146
	v_exp_f32_e32 v144, v144
	v_exp_f32_e32 v146, v146
	v_pk_add_f32 v[144:145], v[144:145], 1.0 op_sel_hi:[1,0]
	v_pk_add_f32 v[146:147], v[146:147], 1.0 op_sel_hi:[1,0]
	v_mov_b32_e32 v148, v145
	v_mov_b32_e32 v149, v147
	v_mov_b32_e32 v150, v144
	v_mov_b32_e32 v151, v146
	v_pk_mul_f32 v[148:149], v[148:149], v[150:151]
	s_nop 0
	v_mul_f32_e32 v150, v148, v149
	v_rcp_f32_e32 v151, v150
	s_nop 0
	v_mul_f32_e32 v150, v149, v151
	v_max_f32_e32 v149, 0xc1a00000, v136
	v_mul_f32_e32 v149, 0xbfb8aa3b, v149
	v_exp_f32_e32 v175, v149
	v_max_f32_e32 v149, 0xc1a00000, v137
	v_mul_f32_e32 v149, 0xbfb8aa3b, v149
	v_exp_f32_e32 v174, v149
	v_max_f32_e32 v149, 0xc1a00000, v138
	v_mul_f32_e32 v149, 0xbfb8aa3b, v149
	v_exp_f32_e32 v183, v149
	v_max_f32_e32 v149, 0xc1a00000, v139
	v_mul_f32_e32 v149, 0xbfb8aa3b, v149
	v_exp_f32_e32 v182, v149
	v_mul_f32_e32 v148, v148, v151
	v_pk_mul_f32 v[144:145], v[144:145], v[150:151] op_sel_hi:[1,0]
	v_pk_add_f32 v[150:151], v[174:175], 1.0 op_sel_hi:[1,0]
	v_pk_add_f32 v[174:175], v[182:183], 1.0 op_sel_hi:[1,0]
	v_mov_b32_e32 v182, v151
	v_mov_b32_e32 v183, v175
	v_mov_b32_e32 v184, v150
	v_mov_b32_e32 v185, v174
	v_pk_mul_f32 v[182:183], v[182:183], v[184:185]
	v_pk_mul_f32 v[144:145], v[140:141], v[144:145]
	v_mul_f32_e32 v149, v182, v183
	v_rcp_f32_e32 v149, v149
	s_nop 0
	v_pk_mul_f32 v[146:147], v[146:147], v[148:149] op_sel_hi:[1,0]
	s_nop 0
	v_pk_mul_f32 v[146:147], v[142:143], v[146:147]
	v_mul_f32_e32 v140, v183, v149
	v_mul_f32_e32 v142, v182, v149
	v_pk_mul_f32 v[140:141], v[150:151], v[140:141] op_sel_hi:[1,0]
	v_pk_mul_f32 v[142:143], v[174:175], v[142:143] op_sel_hi:[1,0]
	v_pk_mul_f32 v[148:149], v[136:137], v[140:141]
	v_pk_mul_f32 v[150:151], v[138:139], v[142:143]

; __device__ __forceinline__ f32x4 sigmoid4(f32x4 x) {
;     f32x4 d;
; #pragma unroll
;     for (int j = 0; j < 4; ++j) d[j] = 1.0f + __expf(-fmaxf(x[j], -20.0f));
;     const float p01 = d[0] * d[1], p23 = d[2] * d[3], r = __builtin_amdgcn_rcpf(p01 * p23), r01 = r * p23, r23 = r * p01;
;     return (f32x4){r01 * d[1], r01 * d[0], r23 * d[3], r23 * d[2]};
;     __device__ __forceinline__ void operator()(const f32x4 (&acc)[2][2][4][2], const Unit& u, int wr, int wc, int fr, int fq) const {
;     ...
;                 for (int bj = 0; bj < 2; ++bj) { f32x4 v0 = acc[ai][bj][m][0] + bv[bj][0], v1 = acc[ai][bj][m][1] + bv[bj][1];
;                     if (act == 1) {
; #pragma unroll
;                         for (int j = 0; j < 1; ++j) { v0 = v0 * sigmoid4(v0); v1 = v1 * sigmoid4(v1); } }
.LBB0_440:
	s_andn2_b64 vcc, exec, s[0:1]
	s_cbranch_vccnz .LBB0_442
	v_max_f32_e32 v136, 0xc1a00000, v132
	v_max_f32_e32 v138, 0xc1a00000, v134
	v_mul_f32_e32 v136, 0xbfb8aa3b, v136
	v_mul_f32_e32 v138, 0xbfb8aa3b, v138
	v_exp_f32_e32 v137, v136
	v_exp_f32_e32 v139, v138
	v_max_f32_e32 v136, 0xc1a00000, v133
	v_max_f32_e32 v138, 0xc1a00000, v135
	v_mul_f32_e32 v136, 0xbfb8aa3b, v136
	v_mul_f32_e32 v138, 0xbfb8aa3b, v138
	v_exp_f32_e32 v136, v136
	v_exp_f32_e32 v138, v138
	v_pk_add_f32 v[136:137], v[136:137], 1.0 op_sel_hi:[1,0]
	v_pk_add_f32 v[138:139], v[138:139], 1.0 op_sel_hi:[1,0]
	v_mov_b32_e32 v140, v137
	v_mov_b32_e32 v141, v139
	v_mov_b32_e32 v142, v136
	v_mov_b32_e32 v143, v138
	v_pk_mul_f32 v[140:141], v[140:141], v[142:143]
	s_nop 0
	v_mul_f32_e32 v142, v140, v141
	v_rcp_f32_e32 v143, v142
	s_nop 0
	v_mul_f32_e32 v142, v141, v143
	v_max_f32_e32 v141, 0xc1a00000, v128
	v_mul_f32_e32 v141, 0xbfb8aa3b, v141
	v_exp_f32_e32 v145, v141
	v_max_f32_e32 v141, 0xc1a00000, v129
	v_mul_f32_e32 v141, 0xbfb8aa3b, v141
	v_exp_f32_e32 v144, v141
	v_max_f32_e32 v141, 0xc1a00000, v130
	v_mul_f32_e32 v141, 0xbfb8aa3b, v141
	v_exp_f32_e32 v147, v141
	v_max_f32_e32 v141, 0xc1a00000, v131
	v_mul_f32_e32 v141, 0xbfb8aa3b, v141
	v_exp_f32_e32 v146, v141
	v_mul_f32_e32 v140, v140, v143
	v_pk_mul_f32 v[136:137], v[136:137], v[142:143] op_sel_hi:[1,0]
	v_pk_add_f32 v[142:143], v[144:145], 1.0 op_sel_hi:[1,0]
	v_pk_add_f32 v[144:145], v[146:147], 1.0 op_sel_hi:[1,0]
	v_mov_b32_e32 v146, v143
	v_mov_b32_e32 v147, v145
	v_mov_b32_e32 v148, v142
	v_mov_b32_e32 v149, v144
	v_pk_mul_f32 v[146:147], v[146:147], v[148:149]
	v_pk_mul_f32 v[136:137], v[132:133], v[136:137]
	v_mul_f32_e32 v141, v146, v147
	v_rcp_f32_e32 v141, v141
	s_nop 0
	v_pk_mul_f32 v[138:139], v[138:139], v[140:141] op_sel_hi:[1,0]
	s_nop 0
	v_pk_mul_f32 v[138:139], v[134:135], v[138:139]
	v_mul_f32_e32 v132, v147, v141
	v_mul_f32_e32 v134, v146, v141
	v_pk_mul_f32 v[132:133], v[142:143], v[132:133] op_sel_hi:[1,0]
	v_pk_mul_f32 v[134:135], v[144:145], v[134:135] op_sel_hi:[1,0]
	v_pk_mul_f32 v[140:141], v[128:129], v[132:133]
	v_pk_mul_f32 v[142:143], v[130:131], v[134:135]

; __device__ __forceinline__ f32x4 sigmoid4(f32x4 x) {
;     f32x4 d;
; #pragma unroll
;     for (int j = 0; j < 4; ++j) d[j] = 1.0f + __expf(-fmaxf(x[j], -20.0f));
;     const float p01 = d[0] * d[1], p23 = d[2] * d[3], r = __builtin_amdgcn_rcpf(p01 * p23), r01 = r * p23, r23 = r * p01;
;     return (f32x4){r01 * d[1], r01 * d[0], r23 * d[3], r23 * d[2]};
;     __device__ __forceinline__ void operator()(const f32x4 (&acc)[2][2][4][2], const Unit& u, int wr, int wc, int fr, int fq) const {
;     ...
;                 for (int bj = 0; bj < 2; ++bj) { f32x4 v0 = acc[ai][bj][m][0] + bv[bj][0], v1 = acc[ai][bj][m][1] + bv[bj][1];
;                     if (act == 1) {
; #pragma unroll
;                         for (int j = 0; j < 1; ++j) { v0 = v0 * sigmoid4(v0); v1 = v1 * sigmoid4(v1); } }
.LBB0_446:
	s_andn2_b64 vcc, exec, s[0:1]
	s_cbranch_vccnz .LBB0_448
	v_max_f32_e32 v128, 0xc1a00000, v124
	v_max_f32_e32 v130, 0xc1a00000, v126
	v_mul_f32_e32 v128, 0xbfb8aa3b, v128
	v_mul_f32_e32 v130, 0xbfb8aa3b, v130
	v_exp_f32_e32 v129, v128
	v_exp_f32_e32 v131, v130
	v_max_f32_e32 v128, 0xc1a00000, v125
	v_max_f32_e32 v130, 0xc1a00000, v127
	v_mul_f32_e32 v128, 0xbfb8aa3b, v128
	v_mul_f32_e32 v130, 0xbfb8aa3b, v130
	v_exp_f32_e32 v128, v128
	v_exp_f32_e32 v130, v130
	v_pk_add_f32 v[128:129], v[128:129], 1.0 op_sel_hi:[1,0]
	v_pk_add_f32 v[130:131], v[130:131], 1.0 op_sel_hi:[1,0]
	v_mov_b32_e32 v132, v129
	v_mov_b32_e32 v133, v131
	v_mov_b32_e32 v134, v128
	v_mov_b32_e32 v135, v130
	v_pk_mul_f32 v[132:133], v[132:133], v[134:135]
	s_nop 0
	v_mul_f32_e32 v134, v132, v133
	v_rcp_f32_e32 v135, v134
	s_nop 0
	v_mul_f32_e32 v134, v133, v135
	v_max_f32_e32 v133, 0xc1a00000, v120
	v_mul_f32_e32 v133, 0xbfb8aa3b, v133
	v_exp_f32_e32 v137, v133
	v_max_f32_e32 v133, 0xc1a00000, v121
	v_mul_f32_e32 v133, 0xbfb8aa3b, v133
	v_exp_f32_e32 v136, v133
	v_max_f32_e32 v133, 0xc1a00000, v122
	v_mul_f32_e32 v133, 0xbfb8aa3b, v133
	v_exp_f32_e32 v139, v133
	v_max_f32_e32 v133, 0xc1a00000, v123
	v_mul_f32_e32 v133, 0xbfb8aa3b, v133
	v_exp_f32_e32 v138, v133
	v_mul_f32_e32 v132, v132, v135
	v_pk_mul_f32 v[128:129], v[128:129], v[134:135] op_sel_hi:[1,0]
	v_pk_add_f32 v[134:135], v[136:137], 1.0 op_sel_hi:[1,0]
	v_pk_add_f32 v[136:137], v[138:139], 1.0 op_sel_hi:[1,0]
	v_mov_b32_e32 v138, v135
	v_mov_b32_e32 v139, v137
	v_mov_b32_e32 v140, v134
	v_mov_b32_e32 v141, v136
	v_pk_mul_f32 v[138:139], v[138:139], v[140:141]
	v_pk_mul_f32 v[128:129], v[124:125], v[128:129]
	v_mul_f32_e32 v133, v138, v139
	v_rcp_f32_e32 v133, v133
	s_nop 0
	v_pk_mul_f32 v[130:131], v[130:131], v[132:133] op_sel_hi:[1,0]
	s_nop 0
	v_pk_mul_f32 v[130:131], v[126:127], v[130:131]
	v_mul_f32_e32 v124, v139, v133
	v_mul_f32_e32 v126, v138, v133
	v_pk_mul_f32 v[124:125], v[134:135], v[124:125] op_sel_hi:[1,0]
	v_pk_mul_f32 v[126:127], v[136:137], v[126:127] op_sel_hi:[1,0]
	v_pk_mul_f32 v[132:133], v[120:121], v[124:125]
	v_pk_mul_f32 v[134:135], v[122:123], v[126:127]

; __device__ __forceinline__ f32x4 sigmoid4(f32x4 x) {
;     f32x4 d;
; #pragma unroll
;     for (int j = 0; j < 4; ++j) d[j] = 1.0f + __expf(-fmaxf(x[j], -20.0f));
;     const float p01 = d[0] * d[1], p23 = d[2] * d[3], r = __builtin_amdgcn_rcpf(p01 * p23), r01 = r * p23, r23 = r * p01;
;     return (f32x4){r01 * d[1], r01 * d[0], r23 * d[3], r23 * d[2]};
;     __device__ __forceinline__ void operator()(const f32x4 (&acc)[2][2][4][2], const Unit& u, int wr, int wc, int fr, int fq) const {
;     ...
;                 for (int bj = 0; bj < 2; ++bj) { f32x4 v0 = acc[ai][bj][m][0] + bv[bj][0], v1 = acc[ai][bj][m][1] + bv[bj][1];
;                     if (act == 1) {
; #pragma unroll
;                         for (int j = 0; j < 1; ++j) { v0 = v0 * sigmoid4(v0); v1 = v1 * sigmoid4(v1); } }
.LBB0_452:
	s_andn2_b64 vcc, exec, s[0:1]
	s_cbranch_vccnz .LBB0_454
	v_max_f32_e32 v120, 0xc1a00000, v116
	v_max_f32_e32 v122, 0xc1a00000, v118
	v_mul_f32_e32 v120, 0xbfb8aa3b, v120
	v_mul_f32_e32 v122, 0xbfb8aa3b, v122
	v_exp_f32_e32 v121, v120
	v_exp_f32_e32 v123, v122
	v_max_f32_e32 v120, 0xc1a00000, v117
	v_max_f32_e32 v122, 0xc1a00000, v119
	v_mul_f32_e32 v120, 0xbfb8aa3b, v120
	v_mul_f32_e32 v122, 0xbfb8aa3b, v122
	v_exp_f32_e32 v120, v120
	v_exp_f32_e32 v122, v122
	v_pk_add_f32 v[120:121], v[120:121], 1.0 op_sel_hi:[1,0]
	v_pk_add_f32 v[122:123], v[122:123], 1.0 op_sel_hi:[1,0]
	v_mov_b32_e32 v124, v121
	v_mov_b32_e32 v125, v123
	v_mov_b32_e32 v126, v120
	v_mov_b32_e32 v127, v122
	v_pk_mul_f32 v[124:125], v[124:125], v[126:127]
	s_nop 0
	v_mul_f32_e32 v126, v124, v125
	v_rcp_f32_e32 v127, v126
	s_nop 0
	v_mul_f32_e32 v126, v125, v127
	v_max_f32_e32 v125, 0xc1a00000, v112
	v_mul_f32_e32 v125, 0xbfb8aa3b, v125
	v_exp_f32_e32 v129, v125
	v_max_f32_e32 v125, 0xc1a00000, v113
	v_mul_f32_e32 v125, 0xbfb8aa3b, v125
	v_exp_f32_e32 v128, v125
	v_max_f32_e32 v125, 0xc1a00000, v114
	v_mul_f32_e32 v125, 0xbfb8aa3b, v125
	v_exp_f32_e32 v131, v125
	v_max_f32_e32 v125, 0xc1a00000, v115
	v_mul_f32_e32 v125, 0xbfb8aa3b, v125
	v_exp_f32_e32 v130, v125
	v_mul_f32_e32 v124, v124, v127
	v_pk_mul_f32 v[120:121], v[120:121], v[126:127] op_sel_hi:[1,0]
	v_pk_add_f32 v[126:127], v[128:129], 1.0 op_sel_hi:[1,0]
	v_pk_add_f32 v[128:129], v[130:131], 1.0 op_sel_hi:[1,0]
	v_mov_b32_e32 v130, v127
	v_mov_b32_e32 v131, v129
	v_mov_b32_e32 v132, v126
	v_mov_b32_e32 v133, v128
	v_pk_mul_f32 v[130:131], v[130:131], v[132:133]
	v_pk_mul_f32 v[120:121], v[116:117], v[120:121]
	v_mul_f32_e32 v125, v130, v131
	v_rcp_f32_e32 v125, v125
	s_nop 0
	v_pk_mul_f32 v[122:123], v[122:123], v[124:125] op_sel_hi:[1,0]
	s_nop 0
	v_pk_mul_f32 v[122:123], v[118:119], v[122:123]
	v_mul_f32_e32 v116, v131, v125
	v_mul_f32_e32 v118, v130, v125
	v_pk_mul_f32 v[116:117], v[126:127], v[116:117] op_sel_hi:[1,0]
	v_pk_mul_f32 v[118:119], v[128:129], v[118:119] op_sel_hi:[1,0]
	v_pk_mul_f32 v[124:125], v[112:113], v[116:117]
	v_pk_mul_f32 v[126:127], v[114:115], v[118:119]

; __device__ __forceinline__ f32x4 sigmoid4(f32x4 x) {
;     f32x4 d;
; #pragma unroll
;     for (int j = 0; j < 4; ++j) d[j] = 1.0f + __expf(-fmaxf(x[j], -20.0f));
;     const float p01 = d[0] * d[1], p23 = d[2] * d[3], r = __builtin_amdgcn_rcpf(p01 * p23), r01 = r * p23, r23 = r * p01;
;     return (f32x4){r01 * d[1], r01 * d[0], r23 * d[3], r23 * d[2]};
;     __device__ __forceinline__ void operator()(const f32x4 (&acc)[2][2][4][2], const Unit& u, int wr, int wc, int fr, int fq) const {
;     ...
;                 for (int bj = 0; bj < 2; ++bj) { f32x4 v0 = acc[ai][bj][m][0] + bv[bj][0], v1 = acc[ai][bj][m][1] + bv[bj][1];
;                     if (act == 1) {
; #pragma unroll
;                         for (int j = 0; j < 1; ++j) { v0 = v0 * sigmoid4(v0); v1 = v1 * sigmoid4(v1); } }
.LBB0_458:
	s_andn2_b64 vcc, exec, s[0:1]
	s_cbranch_vccnz .LBB0_460
	v_max_f32_e32 v112, 0xc1a00000, v108
	v_max_f32_e32 v114, 0xc1a00000, v110
	v_mul_f32_e32 v112, 0xbfb8aa3b, v112
	v_mul_f32_e32 v114, 0xbfb8aa3b, v114
	v_exp_f32_e32 v113, v112
	v_exp_f32_e32 v115, v114
	v_max_f32_e32 v112, 0xc1a00000, v109
	v_max_f32_e32 v114, 0xc1a00000, v111
	v_mul_f32_e32 v112, 0xbfb8aa3b, v112
	v_mul_f32_e32 v114, 0xbfb8aa3b, v114
	v_exp_f32_e32 v112, v112
	v_exp_f32_e32 v114, v114
	v_pk_add_f32 v[112:113], v[112:113], 1.0 op_sel_hi:[1,0]
	v_pk_add_f32 v[114:115], v[114:115], 1.0 op_sel_hi:[1,0]
	v_mov_b32_e32 v116, v113
	v_mov_b32_e32 v117, v115
	v_mov_b32_e32 v118, v112
	v_mov_b32_e32 v119, v114
	v_pk_mul_f32 v[116:117], v[116:117], v[118:119]
	s_nop 0
	v_mul_f32_e32 v118, v116, v117
	v_rcp_f32_e32 v119, v118
	s_nop 0
	v_mul_f32_e32 v118, v117, v119
	v_max_f32_e32 v117, 0xc1a00000, v104
	v_mul_f32_e32 v117, 0xbfb8aa3b, v117
	v_exp_f32_e32 v121, v117
	v_max_f32_e32 v117, 0xc1a00000, v105
	v_mul_f32_e32 v117, 0xbfb8aa3b, v117
	v_exp_f32_e32 v120, v117
	v_max_f32_e32 v117, 0xc1a00000, v106
	v_mul_f32_e32 v117, 0xbfb8aa3b, v117
	v_exp_f32_e32 v123, v117
	v_max_f32_e32 v117, 0xc1a00000, v107
	v_mul_f32_e32 v117, 0xbfb8aa3b, v117
	v_exp_f32_e32 v122, v117
	v_mul_f32_e32 v116, v116, v119
	v_pk_mul_f32 v[112:113], v[112:113], v[118:119] op_sel_hi:[1,0]
	v_pk_add_f32 v[118:119], v[120:121], 1.0 op_sel_hi:[1,0]
	v_pk_add_f32 v[120:121], v[122:123], 1.0 op_sel_hi:[1,0]
	v_mov_b32_e32 v122, v119
	v_mov_b32_e32 v123, v121
	v_mov_b32_e32 v124, v118
	v_mov_b32_e32 v125, v120
	v_pk_mul_f32 v[122:123], v[122:123], v[124:125]
	v_pk_mul_f32 v[112:113], v[108:109], v[112:113]
	v_mul_f32_e32 v117, v122, v123
	v_rcp_f32_e32 v117, v117
	s_nop 0
	v_pk_mul_f32 v[114:115], v[114:115], v[116:117] op_sel_hi:[1,0]
	s_nop 0
	v_pk_mul_f32 v[114:115], v[110:111], v[114:115]
	v_mul_f32_e32 v108, v123, v117
	v_mul_f32_e32 v110, v122, v117
	v_pk_mul_f32 v[108:109], v[118:119], v[108:109] op_sel_hi:[1,0]
	v_pk_mul_f32 v[110:111], v[120:121], v[110:111] op_sel_hi:[1,0]
	v_pk_mul_f32 v[116:117], v[104:105], v[108:109]
	v_pk_mul_f32 v[118:119], v[106:107], v[110:111]

; __device__ __forceinline__ f32x4 sigmoid4(f32x4 x) {
;     f32x4 d;
; #pragma unroll
;     for (int j = 0; j < 4; ++j) d[j] = 1.0f + __expf(-fmaxf(x[j], -20.0f));
;     const float p01 = d[0] * d[1], p23 = d[2] * d[3], r = __builtin_amdgcn_rcpf(p01 * p23), r01 = r * p23, r23 = r * p01;
;     return (f32x4){r01 * d[1], r01 * d[0], r23 * d[3], r23 * d[2]};
;     __device__ __forceinline__ void operator()(const f32x4 (&acc)[2][2][4][2], const Unit& u, int wr, int wc, int fr, int fq) const {
;     ...
;                 for (int bj = 0; bj < 2; ++bj) { f32x4 v0 = acc[ai][bj][m][0] + bv[bj][0], v1 = acc[ai][bj][m][1] + bv[bj][1];
;                     if (act == 1) {
; #pragma unroll
;                         for (int j = 0; j < 1; ++j) { v0 = v0 * sigmoid4(v0); v1 = v1 * sigmoid4(v1); } }
.LBB0_464:
	s_andn2_b64 vcc, exec, s[0:1]
	s_cbranch_vccnz .LBB0_466
	v_max_f32_e32 v104, 0xc1a00000, v100
	v_max_f32_e32 v106, 0xc1a00000, v102
	v_mul_f32_e32 v104, 0xbfb8aa3b, v104
	v_mul_f32_e32 v106, 0xbfb8aa3b, v106
	v_exp_f32_e32 v105, v104
	v_exp_f32_e32 v107, v106
	v_max_f32_e32 v104, 0xc1a00000, v101
	v_max_f32_e32 v106, 0xc1a00000, v103
	v_mul_f32_e32 v104, 0xbfb8aa3b, v104
	v_mul_f32_e32 v106, 0xbfb8aa3b, v106
	v_exp_f32_e32 v104, v104
	v_exp_f32_e32 v106, v106
	v_pk_add_f32 v[104:105], v[104:105], 1.0 op_sel_hi:[1,0]
	v_pk_add_f32 v[106:107], v[106:107], 1.0 op_sel_hi:[1,0]
	v_mov_b32_e32 v108, v105
	v_mov_b32_e32 v109, v107
	v_mov_b32_e32 v110, v104
	v_mov_b32_e32 v111, v106
	v_pk_mul_f32 v[108:109], v[108:109], v[110:111]
	s_nop 0
	v_mul_f32_e32 v110, v108, v109
	v_rcp_f32_e32 v111, v110
	s_nop 0
	v_mul_f32_e32 v110, v109, v111
	v_max_f32_e32 v109, 0xc1a00000, v96
	v_mul_f32_e32 v109, 0xbfb8aa3b, v109
	v_exp_f32_e32 v113, v109
	v_max_f32_e32 v109, 0xc1a00000, v97
	v_mul_f32_e32 v109, 0xbfb8aa3b, v109
	v_exp_f32_e32 v112, v109
	v_max_f32_e32 v109, 0xc1a00000, v98
	v_mul_f32_e32 v109, 0xbfb8aa3b, v109
	v_exp_f32_e32 v115, v109
	v_max_f32_e32 v109, 0xc1a00000, v99
	v_mul_f32_e32 v109, 0xbfb8aa3b, v109
	v_exp_f32_e32 v114, v109
	v_mul_f32_e32 v108, v108, v111
	v_pk_mul_f32 v[104:105], v[104:105], v[110:111] op_sel_hi:[1,0]
	v_pk_add_f32 v[110:111], v[112:113], 1.0 op_sel_hi:[1,0]
	v_pk_add_f32 v[112:113], v[114:115], 1.0 op_sel_hi:[1,0]
	v_mov_b32_e32 v114, v111
	v_mov_b32_e32 v115, v113
	v_mov_b32_e32 v116, v110
	v_mov_b32_e32 v117, v112
	v_pk_mul_f32 v[114:115], v[114:115], v[116:117]
	v_pk_mul_f32 v[104:105], v[100:101], v[104:105]
	v_mul_f32_e32 v109, v114, v115
	v_rcp_f32_e32 v109, v109
	s_nop 0
	v_pk_mul_f32 v[106:107], v[106:107], v[108:109] op_sel_hi:[1,0]
	s_nop 0
	v_pk_mul_f32 v[106:107], v[102:103], v[106:107]
	v_mul_f32_e32 v100, v115, v109
	v_mul_f32_e32 v102, v114, v109
	v_pk_mul_f32 v[100:101], v[110:111], v[100:101] op_sel_hi:[1,0]
	v_pk_mul_f32 v[102:103], v[112:113], v[102:103] op_sel_hi:[1,0]
	v_pk_mul_f32 v[108:109], v[96:97], v[100:101]
	v_pk_mul_f32 v[110:111], v[98:99], v[102:103]

; __device__ __forceinline__ f32x4 sigmoid4(f32x4 x) {
;     f32x4 d;
; #pragma unroll
;     for (int j = 0; j < 4; ++j) d[j] = 1.0f + __expf(-fmaxf(x[j], -20.0f));
;     const float p01 = d[0] * d[1], p23 = d[2] * d[3], r = __builtin_amdgcn_rcpf(p01 * p23), r01 = r * p23, r23 = r * p01;
;     return (f32x4){r01 * d[1], r01 * d[0], r23 * d[3], r23 * d[2]};
;     __device__ __forceinline__ void operator()(const f32x4 (&acc)[2][2][4][2], const Unit& u, int wr, int wc, int fr, int fq) const {
;     ...
;                 for (int bj = 0; bj < 2; ++bj) { f32x4 v0 = acc[ai][bj][m][0] + bv[bj][0], v1 = acc[ai][bj][m][1] + bv[bj][1];
;                     if (act == 1) {
; #pragma unroll
;                         for (int j = 0; j < 1; ++j) { v0 = v0 * sigmoid4(v0); v1 = v1 * sigmoid4(v1); } }
.LBB0_470:
	s_andn2_b64 vcc, exec, s[0:1]
	s_cbranch_vccnz .LBB0_472
	v_max_f32_e32 v96, 0xc1a00000, v92
	v_max_f32_e32 v98, 0xc1a00000, v94
	v_mul_f32_e32 v96, 0xbfb8aa3b, v96
	v_mul_f32_e32 v98, 0xbfb8aa3b, v98
	v_exp_f32_e32 v97, v96
	v_exp_f32_e32 v99, v98
	v_max_f32_e32 v96, 0xc1a00000, v93
	v_max_f32_e32 v98, 0xc1a00000, v95
	v_mul_f32_e32 v96, 0xbfb8aa3b, v96
	v_mul_f32_e32 v98, 0xbfb8aa3b, v98
	v_exp_f32_e32 v96, v96
	v_exp_f32_e32 v98, v98
	v_pk_add_f32 v[96:97], v[96:97], 1.0 op_sel_hi:[1,0]
	v_pk_add_f32 v[98:99], v[98:99], 1.0 op_sel_hi:[1,0]
	v_mov_b32_e32 v100, v97
	v_mov_b32_e32 v101, v99
	v_mov_b32_e32 v102, v96
	v_mov_b32_e32 v103, v98
	v_pk_mul_f32 v[100:101], v[100:101], v[102:103]
	s_nop 0
	v_mul_f32_e32 v102, v100, v101
	v_rcp_f32_e32 v103, v102
	s_nop 0
	v_mul_f32_e32 v102, v101, v103
	v_max_f32_e32 v101, 0xc1a00000, v88
	v_mul_f32_e32 v101, 0xbfb8aa3b, v101
	v_exp_f32_e32 v105, v101
	v_max_f32_e32 v101, 0xc1a00000, v89
	v_mul_f32_e32 v101, 0xbfb8aa3b, v101
	v_exp_f32_e32 v104, v101
	v_max_f32_e32 v101, 0xc1a00000, v90
	v_mul_f32_e32 v101, 0xbfb8aa3b, v101
	v_exp_f32_e32 v107, v101
	v_max_f32_e32 v101, 0xc1a00000, v91
	v_mul_f32_e32 v101, 0xbfb8aa3b, v101
	v_exp_f32_e32 v106, v101
	v_mul_f32_e32 v100, v100, v103
	v_pk_mul_f32 v[96:97], v[96:97], v[102:103] op_sel_hi:[1,0]
	v_pk_add_f32 v[102:103], v[104:105], 1.0 op_sel_hi:[1,0]
	v_pk_add_f32 v[104:105], v[106:107], 1.0 op_sel_hi:[1,0]
	v_mov_b32_e32 v106, v103
	v_mov_b32_e32 v107, v105
	v_mov_b32_e32 v108, v102
	v_mov_b32_e32 v109, v104
	v_pk_mul_f32 v[106:107], v[106:107], v[108:109]
	v_pk_mul_f32 v[96:97], v[92:93], v[96:97]
	v_mul_f32_e32 v101, v106, v107
	v_rcp_f32_e32 v101, v101
	s_nop 0
	v_pk_mul_f32 v[98:99], v[98:99], v[100:101] op_sel_hi:[1,0]
	s_nop 0
	v_pk_mul_f32 v[98:99], v[94:95], v[98:99]
	v_mul_f32_e32 v92, v107, v101
	v_mul_f32_e32 v94, v106, v101
	v_pk_mul_f32 v[92:93], v[102:103], v[92:93] op_sel_hi:[1,0]
	v_pk_mul_f32 v[94:95], v[104:105], v[94:95] op_sel_hi:[1,0]
	v_pk_mul_f32 v[100:101], v[88:89], v[92:93]
	v_pk_mul_f32 v[102:103], v[90:91], v[94:95]

; __device__ __forceinline__ f32x4 sigmoid4(f32x4 x) {
;     f32x4 d;
; #pragma unroll
;     for (int j = 0; j < 4; ++j) d[j] = 1.0f + __expf(-fmaxf(x[j], -20.0f));
;     const float p01 = d[0] * d[1], p23 = d[2] * d[3], r = __builtin_amdgcn_rcpf(p01 * p23), r01 = r * p23, r23 = r * p01;
;     return (f32x4){r01 * d[1], r01 * d[0], r23 * d[3], r23 * d[2]};
;     __device__ __forceinline__ void operator()(const f32x4 (&acc)[2][2][4][2], const Unit& u, int wr, int wc, int fr, int fq) const {
;     ...
;                 for (int bj = 0; bj < 2; ++bj) { f32x4 v0 = acc[ai][bj][m][0] + bv[bj][0], v1 = acc[ai][bj][m][1] + bv[bj][1];
;                     if (act == 1) {
; #pragma unroll
;                         for (int j = 0; j < 1; ++j) { v0 = v0 * sigmoid4(v0); v1 = v1 * sigmoid4(v1); } }
.LBB0_476:
	s_andn2_b64 vcc, exec, s[0:1]
	s_cbranch_vccnz .LBB0_478
	v_max_f32_e32 v88, 0xc1a00000, v84
	v_max_f32_e32 v90, 0xc1a00000, v86
	v_mul_f32_e32 v88, 0xbfb8aa3b, v88
	v_mul_f32_e32 v90, 0xbfb8aa3b, v90
	v_exp_f32_e32 v89, v88
	v_exp_f32_e32 v91, v90
	v_max_f32_e32 v88, 0xc1a00000, v85
	v_max_f32_e32 v90, 0xc1a00000, v87
	v_mul_f32_e32 v88, 0xbfb8aa3b, v88
	v_mul_f32_e32 v90, 0xbfb8aa3b, v90
	v_exp_f32_e32 v88, v88
	v_exp_f32_e32 v90, v90
	v_pk_add_f32 v[88:89], v[88:89], 1.0 op_sel_hi:[1,0]
	v_pk_add_f32 v[90:91], v[90:91], 1.0 op_sel_hi:[1,0]
	v_mov_b32_e32 v92, v89
	v_mov_b32_e32 v93, v91
	v_mov_b32_e32 v94, v88
	v_mov_b32_e32 v95, v90
	v_pk_mul_f32 v[92:93], v[92:93], v[94:95]
	s_nop 0
	v_mul_f32_e32 v94, v92, v93
	v_rcp_f32_e32 v95, v94
	s_nop 0
	v_mul_f32_e32 v94, v93, v95
	v_max_f32_e32 v93, 0xc1a00000, v80
	v_mul_f32_e32 v93, 0xbfb8aa3b, v93
	v_exp_f32_e32 v97, v93
	v_max_f32_e32 v93, 0xc1a00000, v81
	v_mul_f32_e32 v93, 0xbfb8aa3b, v93
	v_exp_f32_e32 v96, v93
	v_max_f32_e32 v93, 0xc1a00000, v82
	v_mul_f32_e32 v93, 0xbfb8aa3b, v93
	v_exp_f32_e32 v99, v93
	v_max_f32_e32 v93, 0xc1a00000, v83
	v_mul_f32_e32 v93, 0xbfb8aa3b, v93
	v_exp_f32_e32 v98, v93
	v_mul_f32_e32 v92, v92, v95
	v_pk_mul_f32 v[88:89], v[88:89], v[94:95] op_sel_hi:[1,0]
	v_pk_add_f32 v[94:95], v[96:97], 1.0 op_sel_hi:[1,0]
	v_pk_add_f32 v[96:97], v[98:99], 1.0 op_sel_hi:[1,0]
	v_mov_b32_e32 v98, v95
	v_mov_b32_e32 v99, v97
	v_mov_b32_e32 v100, v94
	v_mov_b32_e32 v101, v96
	v_pk_mul_f32 v[98:99], v[98:99], v[100:101]
	v_pk_mul_f32 v[88:89], v[84:85], v[88:89]
	v_mul_f32_e32 v93, v98, v99
	v_rcp_f32_e32 v93, v93
	s_nop 0
	v_pk_mul_f32 v[90:91], v[90:91], v[92:93] op_sel_hi:[1,0]
	s_nop 0
	v_pk_mul_f32 v[90:91], v[86:87], v[90:91]
	v_mul_f32_e32 v84, v99, v93
	v_mul_f32_e32 v86, v98, v93
	v_pk_mul_f32 v[84:85], v[94:95], v[84:85] op_sel_hi:[1,0]
	v_pk_mul_f32 v[86:87], v[96:97], v[86:87] op_sel_hi:[1,0]
	v_pk_mul_f32 v[92:93], v[80:81], v[84:85]
	v_pk_mul_f32 v[94:95], v[82:83], v[86:87]

; __device__ __forceinline__ f32x4 sigmoid4(f32x4 x) {
;     f32x4 d;
; #pragma unroll
;     for (int j = 0; j < 4; ++j) d[j] = 1.0f + __expf(-fmaxf(x[j], -20.0f));
;     const float p01 = d[0] * d[1], p23 = d[2] * d[3], r = __builtin_amdgcn_rcpf(p01 * p23), r01 = r * p23, r23 = r * p01;
;     return (f32x4){r01 * d[1], r01 * d[0], r23 * d[3], r23 * d[2]};
;     __device__ __forceinline__ void operator()(const f32x4 (&acc)[2][2][4][2], const Unit& u, int wr, int wc, int fr, int fq) const {
;     ...
;                 for (int bj = 0; bj < 2; ++bj) { f32x4 v0 = acc[ai][bj][m][0] + bv[bj][0], v1 = acc[ai][bj][m][1] + bv[bj][1];
;                     if (act == 1) {
; #pragma unroll
;                         for (int j = 0; j < 1; ++j) { v0 = v0 * sigmoid4(v0); v1 = v1 * sigmoid4(v1); } }
.LBB0_482:
	s_andn2_b64 vcc, exec, s[0:1]
	s_cbranch_vccnz .LBB0_484
	v_max_f32_e32 v80, 0xc1a00000, v76
	v_max_f32_e32 v82, 0xc1a00000, v78
	v_mul_f32_e32 v80, 0xbfb8aa3b, v80
	v_mul_f32_e32 v82, 0xbfb8aa3b, v82
	v_exp_f32_e32 v81, v80
	v_exp_f32_e32 v83, v82
	v_max_f32_e32 v80, 0xc1a00000, v77
	v_max_f32_e32 v82, 0xc1a00000, v79
	v_mul_f32_e32 v80, 0xbfb8aa3b, v80
	v_mul_f32_e32 v82, 0xbfb8aa3b, v82
	v_exp_f32_e32 v80, v80
	v_exp_f32_e32 v82, v82
	v_pk_add_f32 v[80:81], v[80:81], 1.0 op_sel_hi:[1,0]
	v_pk_add_f32 v[82:83], v[82:83], 1.0 op_sel_hi:[1,0]
	v_mov_b32_e32 v84, v81
	v_mov_b32_e32 v85, v83
	v_mov_b32_e32 v86, v80
	v_mov_b32_e32 v87, v82
	v_pk_mul_f32 v[84:85], v[84:85], v[86:87]
	s_nop 0
	v_mul_f32_e32 v86, v84, v85
	v_rcp_f32_e32 v87, v86
	s_nop 0
	v_mul_f32_e32 v86, v85, v87
	v_max_f32_e32 v85, 0xc1a00000, v72
	v_mul_f32_e32 v85, 0xbfb8aa3b, v85
	v_exp_f32_e32 v89, v85
	v_max_f32_e32 v85, 0xc1a00000, v73
	v_mul_f32_e32 v85, 0xbfb8aa3b, v85
	v_exp_f32_e32 v88, v85
	v_max_f32_e32 v85, 0xc1a00000, v74
	v_mul_f32_e32 v85, 0xbfb8aa3b, v85
	v_exp_f32_e32 v91, v85
	v_max_f32_e32 v85, 0xc1a00000, v75
	v_mul_f32_e32 v85, 0xbfb8aa3b, v85
	v_exp_f32_e32 v90, v85
	v_mul_f32_e32 v84, v84, v87
	v_pk_mul_f32 v[80:81], v[80:81], v[86:87] op_sel_hi:[1,0]
	v_pk_add_f32 v[86:87], v[88:89], 1.0 op_sel_hi:[1,0]
	v_pk_add_f32 v[88:89], v[90:91], 1.0 op_sel_hi:[1,0]
	v_mov_b32_e32 v90, v87
	v_mov_b32_e32 v91, v89
	v_mov_b32_e32 v92, v86
	v_mov_b32_e32 v93, v88
	v_pk_mul_f32 v[90:91], v[90:91], v[92:93]
	v_pk_mul_f32 v[80:81], v[76:77], v[80:81]
	v_mul_f32_e32 v85, v90, v91
	v_rcp_f32_e32 v85, v85
	s_nop 0
	v_pk_mul_f32 v[82:83], v[82:83], v[84:85] op_sel_hi:[1,0]
	s_nop 0
	v_pk_mul_f32 v[82:83], v[78:79], v[82:83]
	v_mul_f32_e32 v76, v91, v85
	v_mul_f32_e32 v78, v90, v85
	v_pk_mul_f32 v[76:77], v[86:87], v[76:77] op_sel_hi:[1,0]
	v_pk_mul_f32 v[78:79], v[88:89], v[78:79] op_sel_hi:[1,0]
	v_pk_mul_f32 v[84:85], v[72:73], v[76:77]
	v_pk_mul_f32 v[86:87], v[74:75], v[78:79]

; __device__ __forceinline__ f32x4 sigmoid4(f32x4 x) {
;     f32x4 d;
; #pragma unroll
;     for (int j = 0; j < 4; ++j) d[j] = 1.0f + __expf(-fmaxf(x[j], -20.0f));
;     const float p01 = d[0] * d[1], p23 = d[2] * d[3], r = __builtin_amdgcn_rcpf(p01 * p23), r01 = r * p23, r23 = r * p01;
;     return (f32x4){r01 * d[1], r01 * d[0], r23 * d[3], r23 * d[2]};
;     __device__ __forceinline__ void operator()(const f32x4 (&acc)[2][2][4][2], const Unit& u, int wr, int wc, int fr, int fq) const {
;     ...
;                 for (int bj = 0; bj < 2; ++bj) { f32x4 v0 = acc[ai][bj][m][0] + bv[bj][0], v1 = acc[ai][bj][m][1] + bv[bj][1];
;                     if (act == 1) {
; #pragma unroll
;                         for (int j = 0; j < 1; ++j) { v0 = v0 * sigmoid4(v0); v1 = v1 * sigmoid4(v1); } }
.LBB0_488:
	s_andn2_b64 vcc, exec, s[0:1]
	s_cbranch_vccnz .LBB0_490
	v_max_f32_e32 v72, 0xc1a00000, v68
	v_max_f32_e32 v74, 0xc1a00000, v70
	v_mul_f32_e32 v72, 0xbfb8aa3b, v72
	v_mul_f32_e32 v74, 0xbfb8aa3b, v74
	v_exp_f32_e32 v73, v72
	v_exp_f32_e32 v75, v74
	v_max_f32_e32 v72, 0xc1a00000, v69
	v_max_f32_e32 v74, 0xc1a00000, v71
	v_mul_f32_e32 v72, 0xbfb8aa3b, v72
	v_mul_f32_e32 v74, 0xbfb8aa3b, v74
	v_exp_f32_e32 v72, v72
	v_exp_f32_e32 v74, v74
	v_pk_add_f32 v[72:73], v[72:73], 1.0 op_sel_hi:[1,0]
	v_pk_add_f32 v[74:75], v[74:75], 1.0 op_sel_hi:[1,0]
	v_mov_b32_e32 v76, v73
	v_mov_b32_e32 v77, v75
	v_mov_b32_e32 v78, v72
	v_mov_b32_e32 v79, v74
	v_pk_mul_f32 v[76:77], v[76:77], v[78:79]
	s_nop 0
	v_mul_f32_e32 v78, v76, v77
	v_rcp_f32_e32 v79, v78
	s_nop 0
	v_mul_f32_e32 v78, v77, v79
	v_max_f32_e32 v77, 0xc1a00000, v64
	v_mul_f32_e32 v77, 0xbfb8aa3b, v77
	v_exp_f32_e32 v81, v77
	v_max_f32_e32 v77, 0xc1a00000, v65
	v_mul_f32_e32 v77, 0xbfb8aa3b, v77
	v_exp_f32_e32 v80, v77
	v_max_f32_e32 v77, 0xc1a00000, v66
	v_mul_f32_e32 v77, 0xbfb8aa3b, v77
	v_exp_f32_e32 v83, v77
	v_max_f32_e32 v77, 0xc1a00000, v67
	v_mul_f32_e32 v77, 0xbfb8aa3b, v77
	v_exp_f32_e32 v82, v77
	v_mul_f32_e32 v76, v76, v79
	v_pk_mul_f32 v[72:73], v[72:73], v[78:79] op_sel_hi:[1,0]
	v_pk_add_f32 v[78:79], v[80:81], 1.0 op_sel_hi:[1,0]
	v_pk_add_f32 v[80:81], v[82:83], 1.0 op_sel_hi:[1,0]
	v_mov_b32_e32 v82, v79
	v_mov_b32_e32 v83, v81
	v_mov_b32_e32 v84, v78
	v_mov_b32_e32 v85, v80
	v_pk_mul_f32 v[82:83], v[82:83], v[84:85]
	v_pk_mul_f32 v[72:73], v[68:69], v[72:73]
	v_mul_f32_e32 v77, v82, v83
	v_rcp_f32_e32 v77, v77
	s_nop 0
	v_pk_mul_f32 v[74:75], v[74:75], v[76:77] op_sel_hi:[1,0]
	s_nop 0
	v_pk_mul_f32 v[74:75], v[70:71], v[74:75]
	v_mul_f32_e32 v68, v83, v77
	v_mul_f32_e32 v70, v82, v77
	v_pk_mul_f32 v[68:69], v[78:79], v[68:69] op_sel_hi:[1,0]
	v_pk_mul_f32 v[70:71], v[80:81], v[70:71] op_sel_hi:[1,0]
	v_pk_mul_f32 v[76:77], v[64:65], v[68:69]
	v_pk_mul_f32 v[78:79], v[66:67], v[70:71]

; __device__ __forceinline__ f32x4 sigmoid4(f32x4 x) {
;     f32x4 d;
; #pragma unroll
;     for (int j = 0; j < 4; ++j) d[j] = 1.0f + __expf(-fmaxf(x[j], -20.0f));
;     const float p01 = d[0] * d[1], p23 = d[2] * d[3], r = __builtin_amdgcn_rcpf(p01 * p23), r01 = r * p23, r23 = r * p01;
;     return (f32x4){r01 * d[1], r01 * d[0], r23 * d[3], r23 * d[2]};
;     __device__ __forceinline__ void operator()(const f32x4 (&acc)[2][2][4][2], const Unit& u, int wr, int wc, int fr, int fq) const {
;     ...
;                 for (int bj = 0; bj < 2; ++bj) { f32x4 v0 = acc[ai][bj][m][0] + bv[bj][0], v1 = acc[ai][bj][m][1] + bv[bj][1];
;                     if (act == 1) {
; #pragma unroll
;                         for (int j = 0; j < 1; ++j) { v0 = v0 * sigmoid4(v0); v1 = v1 * sigmoid4(v1); } }
.LBB0_494:
	s_andn2_b64 vcc, exec, s[0:1]
	s_cbranch_vccnz .LBB0_496
	v_max_f32_e32 v64, 0xc1a00000, v60
	v_max_f32_e32 v66, 0xc1a00000, v62
	v_mul_f32_e32 v64, 0xbfb8aa3b, v64
	v_mul_f32_e32 v66, 0xbfb8aa3b, v66
	v_exp_f32_e32 v65, v64
	v_exp_f32_e32 v67, v66
	v_max_f32_e32 v64, 0xc1a00000, v61
	v_max_f32_e32 v66, 0xc1a00000, v63
	v_mul_f32_e32 v64, 0xbfb8aa3b, v64
	v_mul_f32_e32 v66, 0xbfb8aa3b, v66
	v_exp_f32_e32 v64, v64
	v_exp_f32_e32 v66, v66
	v_pk_add_f32 v[64:65], v[64:65], 1.0 op_sel_hi:[1,0]
	v_pk_add_f32 v[66:67], v[66:67], 1.0 op_sel_hi:[1,0]
	v_mov_b32_e32 v68, v65
	v_mov_b32_e32 v69, v67
	v_mov_b32_e32 v70, v64
	v_mov_b32_e32 v71, v66
	v_pk_mul_f32 v[68:69], v[68:69], v[70:71]
	s_nop 0
	v_mul_f32_e32 v70, v68, v69
	v_rcp_f32_e32 v71, v70
	s_nop 0
	v_mul_f32_e32 v70, v69, v71
	v_max_f32_e32 v69, 0xc1a00000, v56
	v_mul_f32_e32 v69, 0xbfb8aa3b, v69
	v_exp_f32_e32 v73, v69
	v_max_f32_e32 v69, 0xc1a00000, v57
	v_mul_f32_e32 v69, 0xbfb8aa3b, v69
	v_exp_f32_e32 v72, v69
	v_max_f32_e32 v69, 0xc1a00000, v58
	v_mul_f32_e32 v69, 0xbfb8aa3b, v69
	v_exp_f32_e32 v75, v69
	v_max_f32_e32 v69, 0xc1a00000, v59
	v_mul_f32_e32 v69, 0xbfb8aa3b, v69
	v_exp_f32_e32 v74, v69
	v_mul_f32_e32 v68, v68, v71
	v_pk_mul_f32 v[64:65], v[64:65], v[70:71] op_sel_hi:[1,0]
	v_pk_add_f32 v[70:71], v[72:73], 1.0 op_sel_hi:[1,0]
	v_pk_add_f32 v[72:73], v[74:75], 1.0 op_sel_hi:[1,0]
	v_mov_b32_e32 v74, v71
	v_mov_b32_e32 v75, v73
	v_mov_b32_e32 v76, v70
	v_mov_b32_e32 v77, v72
	v_pk_mul_f32 v[74:75], v[74:75], v[76:77]
	v_pk_mul_f32 v[64:65], v[60:61], v[64:65]
	v_mul_f32_e32 v69, v74, v75
	v_rcp_f32_e32 v69, v69
	s_nop 0
	v_pk_mul_f32 v[66:67], v[66:67], v[68:69] op_sel_hi:[1,0]
	s_nop 0
	v_pk_mul_f32 v[66:67], v[62:63], v[66:67]
	v_mul_f32_e32 v60, v75, v69
	v_mul_f32_e32 v62, v74, v69
	v_pk_mul_f32 v[60:61], v[70:71], v[60:61] op_sel_hi:[1,0]
	v_pk_mul_f32 v[62:63], v[72:73], v[62:63] op_sel_hi:[1,0]
	v_pk_mul_f32 v[68:69], v[56:57], v[60:61]
	v_pk_mul_f32 v[70:71], v[58:59], v[62:63]

; __device__ __forceinline__ f32x4 sigmoid4(f32x4 x) {
;     f32x4 d;
; #pragma unroll
;     for (int j = 0; j < 4; ++j) d[j] = 1.0f + __expf(-fmaxf(x[j], -20.0f));
;     const float p01 = d[0] * d[1], p23 = d[2] * d[3], r = __builtin_amdgcn_rcpf(p01 * p23), r01 = r * p23, r23 = r * p01;
;     return (f32x4){r01 * d[1], r01 * d[0], r23 * d[3], r23 * d[2]};
;     __device__ __forceinline__ void operator()(const f32x4 (&acc)[2][2][4][2], const Unit& u, int wr, int wc, int fr, int fq) const {
;     ...
;                 for (int bj = 0; bj < 2; ++bj) { f32x4 v0 = acc[ai][bj][m][0] + bv[bj][0], v1 = acc[ai][bj][m][1] + bv[bj][1];
;                     if (act == 1) {
; #pragma unroll
;                         for (int j = 0; j < 1; ++j) { v0 = v0 * sigmoid4(v0); v1 = v1 * sigmoid4(v1); } }
.LBB0_500:
	s_andn2_b64 vcc, exec, s[0:1]
	s_cbranch_vccnz .LBB0_502
	v_max_f32_e32 v56, 0xc1a00000, v52
	v_max_f32_e32 v58, 0xc1a00000, v54
	v_mul_f32_e32 v56, 0xbfb8aa3b, v56
	v_mul_f32_e32 v58, 0xbfb8aa3b, v58
	v_exp_f32_e32 v57, v56
	v_exp_f32_e32 v59, v58
	v_max_f32_e32 v56, 0xc1a00000, v53
	v_max_f32_e32 v58, 0xc1a00000, v55
	v_mul_f32_e32 v56, 0xbfb8aa3b, v56
	v_mul_f32_e32 v58, 0xbfb8aa3b, v58
	v_exp_f32_e32 v56, v56
	v_exp_f32_e32 v58, v58
	v_pk_add_f32 v[56:57], v[56:57], 1.0 op_sel_hi:[1,0]
	v_pk_add_f32 v[58:59], v[58:59], 1.0 op_sel_hi:[1,0]
	v_mov_b32_e32 v60, v57
	v_mov_b32_e32 v61, v59
	v_mov_b32_e32 v62, v56
	v_mov_b32_e32 v63, v58
	v_pk_mul_f32 v[60:61], v[60:61], v[62:63]
	s_nop 0
	v_mul_f32_e32 v62, v60, v61
	v_rcp_f32_e32 v63, v62
	s_nop 0
	v_mul_f32_e32 v62, v61, v63
	v_max_f32_e32 v61, 0xc1a00000, v48
	v_mul_f32_e32 v61, 0xbfb8aa3b, v61
	v_exp_f32_e32 v65, v61
	v_max_f32_e32 v61, 0xc1a00000, v49
	v_mul_f32_e32 v61, 0xbfb8aa3b, v61
	v_exp_f32_e32 v64, v61
	v_max_f32_e32 v61, 0xc1a00000, v50
	v_mul_f32_e32 v61, 0xbfb8aa3b, v61
	v_exp_f32_e32 v67, v61
	v_max_f32_e32 v61, 0xc1a00000, v51
	v_mul_f32_e32 v61, 0xbfb8aa3b, v61
	v_exp_f32_e32 v66, v61
	v_mul_f32_e32 v60, v60, v63
	v_pk_mul_f32 v[56:57], v[56:57], v[62:63] op_sel_hi:[1,0]
	v_pk_add_f32 v[62:63], v[64:65], 1.0 op_sel_hi:[1,0]
	v_pk_add_f32 v[64:65], v[66:67], 1.0 op_sel_hi:[1,0]
	v_mov_b32_e32 v66, v63
	v_mov_b32_e32 v67, v65
	v_mov_b32_e32 v68, v62
	v_mov_b32_e32 v69, v64
	v_pk_mul_f32 v[66:67], v[66:67], v[68:69]
	v_pk_mul_f32 v[56:57], v[52:53], v[56:57]
	v_mul_f32_e32 v61, v66, v67
	v_rcp_f32_e32 v61, v61
	s_nop 0
	v_pk_mul_f32 v[58:59], v[58:59], v[60:61] op_sel_hi:[1,0]
	s_nop 0
	v_pk_mul_f32 v[58:59], v[54:55], v[58:59]
	v_mul_f32_e32 v52, v67, v61
	v_mul_f32_e32 v54, v66, v61
	v_pk_mul_f32 v[52:53], v[62:63], v[52:53] op_sel_hi:[1,0]
	v_pk_mul_f32 v[54:55], v[64:65], v[54:55] op_sel_hi:[1,0]
	v_pk_mul_f32 v[60:61], v[48:49], v[52:53]
	v_pk_mul_f32 v[62:63], v[50:51], v[54:55]

; __device__ __forceinline__ f32x4 sigmoid4(f32x4 x) {
;     f32x4 d;
; #pragma unroll
;     for (int j = 0; j < 4; ++j) d[j] = 1.0f + __expf(-fmaxf(x[j], -20.0f));
;     const float p01 = d[0] * d[1], p23 = d[2] * d[3], r = __builtin_amdgcn_rcpf(p01 * p23), r01 = r * p23, r23 = r * p01;
;     return (f32x4){r01 * d[1], r01 * d[0], r23 * d[3], r23 * d[2]};
;     __device__ __forceinline__ void operator()(const f32x4 (&acc)[2][2][4][2], const Unit& u, int wr, int wc, int fr, int fq) const {
;     ...
;                 for (int bj = 0; bj < 2; ++bj) { f32x4 v0 = acc[ai][bj][m][0] + bv[bj][0], v1 = acc[ai][bj][m][1] + bv[bj][1];
;                     if (act == 1) {
; #pragma unroll
;                         for (int j = 0; j < 1; ++j) { v0 = v0 * sigmoid4(v0); v1 = v1 * sigmoid4(v1); } }
.LBB0_506:
	s_andn2_b64 vcc, exec, s[0:1]
	s_cbranch_vccnz .LBB0_508
	v_max_f32_e32 v48, 0xc1a00000, v36
	v_max_f32_e32 v50, 0xc1a00000, v38
	v_mul_f32_e32 v48, 0xbfb8aa3b, v48
	v_mul_f32_e32 v50, 0xbfb8aa3b, v50
	v_exp_f32_e32 v49, v48
	v_exp_f32_e32 v51, v50
	v_max_f32_e32 v48, 0xc1a00000, v37
	v_max_f32_e32 v50, 0xc1a00000, v39
	v_mul_f32_e32 v48, 0xbfb8aa3b, v48
	v_mul_f32_e32 v50, 0xbfb8aa3b, v50
	v_exp_f32_e32 v48, v48
	v_exp_f32_e32 v50, v50
	v_pk_add_f32 v[48:49], v[48:49], 1.0 op_sel_hi:[1,0]
	v_pk_add_f32 v[50:51], v[50:51], 1.0 op_sel_hi:[1,0]
	v_mov_b32_e32 v52, v49
	v_mov_b32_e32 v53, v51
	v_mov_b32_e32 v54, v48
	v_mov_b32_e32 v55, v50
	v_pk_mul_f32 v[52:53], v[52:53], v[54:55]
	s_nop 0
	v_mul_f32_e32 v54, v52, v53
	v_rcp_f32_e32 v55, v54
	s_nop 0
	v_mul_f32_e32 v54, v53, v55
	v_max_f32_e32 v53, 0xc1a00000, v32
	v_mul_f32_e32 v53, 0xbfb8aa3b, v53
	v_exp_f32_e32 v57, v53
	v_max_f32_e32 v53, 0xc1a00000, v33
	v_mul_f32_e32 v53, 0xbfb8aa3b, v53
	v_exp_f32_e32 v56, v53
	v_max_f32_e32 v53, 0xc1a00000, v34
	v_mul_f32_e32 v53, 0xbfb8aa3b, v53
	v_exp_f32_e32 v59, v53
	v_max_f32_e32 v53, 0xc1a00000, v35
	v_mul_f32_e32 v53, 0xbfb8aa3b, v53
	v_exp_f32_e32 v58, v53
	v_mul_f32_e32 v52, v52, v55
	v_pk_mul_f32 v[48:49], v[48:49], v[54:55] op_sel_hi:[1,0]
	v_pk_add_f32 v[54:55], v[56:57], 1.0 op_sel_hi:[1,0]
	v_pk_add_f32 v[56:57], v[58:59], 1.0 op_sel_hi:[1,0]
	v_mov_b32_e32 v58, v55
	v_mov_b32_e32 v59, v57
	v_mov_b32_e32 v60, v54
	v_mov_b32_e32 v61, v56
	v_pk_mul_f32 v[58:59], v[58:59], v[60:61]
	v_pk_mul_f32 v[48:49], v[36:37], v[48:49]
	v_mul_f32_e32 v53, v58, v59
	v_rcp_f32_e32 v53, v53
	s_nop 0
	v_pk_mul_f32 v[50:51], v[50:51], v[52:53] op_sel_hi:[1,0]
	s_nop 0
	v_pk_mul_f32 v[50:51], v[38:39], v[50:51]
	v_mul_f32_e32 v36, v59, v53
	v_mul_f32_e32 v38, v58, v53
	v_pk_mul_f32 v[36:37], v[54:55], v[36:37] op_sel_hi:[1,0]
	v_pk_mul_f32 v[38:39], v[56:57], v[38:39] op_sel_hi:[1,0]
	v_pk_mul_f32 v[52:53], v[32:33], v[36:37]
	v_pk_mul_f32 v[54:55], v[34:35], v[38:39]

; __device__ __forceinline__ f32x4 sigmoid4(f32x4 x) {
;     f32x4 d;
; #pragma unroll
;     for (int j = 0; j < 4; ++j) d[j] = 1.0f + __expf(-fmaxf(x[j], -20.0f));
;     const float p01 = d[0] * d[1], p23 = d[2] * d[3], r = __builtin_amdgcn_rcpf(p01 * p23), r01 = r * p23, r23 = r * p01;
;     return (f32x4){r01 * d[1], r01 * d[0], r23 * d[3], r23 * d[2]};
;     __device__ __forceinline__ void operator()(const f32x4 (&acc)[2][2][4][2], const Unit& u, int wr, int wc, int fr, int fq) const {
;     ...
;                 for (int bj = 0; bj < 2; ++bj) { f32x4 v0 = acc[ai][bj][m][0] + bv[bj][0], v1 = acc[ai][bj][m][1] + bv[bj][1];
;                     if (act == 1) {
; #pragma unroll
;                         for (int j = 0; j < 1; ++j) { v0 = v0 * sigmoid4(v0); v1 = v1 * sigmoid4(v1); } }
.LBB0_512:
	s_andn2_b64 vcc, exec, s[0:1]
	s_cbranch_vccnz .LBB0_514
	v_max_f32_e32 v32, 0xc1a00000, v20
	v_max_f32_e32 v34, 0xc1a00000, v22
	v_mul_f32_e32 v32, 0xbfb8aa3b, v32
	v_mul_f32_e32 v34, 0xbfb8aa3b, v34
	v_exp_f32_e32 v33, v32
	v_exp_f32_e32 v35, v34
	v_max_f32_e32 v32, 0xc1a00000, v21
	v_max_f32_e32 v34, 0xc1a00000, v23
	v_mul_f32_e32 v32, 0xbfb8aa3b, v32
	v_mul_f32_e32 v34, 0xbfb8aa3b, v34
	v_exp_f32_e32 v32, v32
	v_exp_f32_e32 v34, v34
	v_pk_add_f32 v[32:33], v[32:33], 1.0 op_sel_hi:[1,0]
	v_pk_add_f32 v[34:35], v[34:35], 1.0 op_sel_hi:[1,0]
	v_mov_b32_e32 v36, v33
	v_mov_b32_e32 v37, v35
	v_mov_b32_e32 v38, v32
	v_mov_b32_e32 v39, v34
	v_pk_mul_f32 v[36:37], v[36:37], v[38:39]
	s_nop 0
	v_mul_f32_e32 v38, v36, v37
	v_rcp_f32_e32 v39, v38
	s_nop 0
	v_mul_f32_e32 v38, v37, v39
	v_max_f32_e32 v37, 0xc1a00000, v16
	v_mul_f32_e32 v37, 0xbfb8aa3b, v37
	v_exp_f32_e32 v49, v37
	v_max_f32_e32 v37, 0xc1a00000, v17
	v_mul_f32_e32 v37, 0xbfb8aa3b, v37
	v_exp_f32_e32 v48, v37
	v_max_f32_e32 v37, 0xc1a00000, v18
	v_mul_f32_e32 v37, 0xbfb8aa3b, v37
	v_exp_f32_e32 v51, v37
	v_max_f32_e32 v37, 0xc1a00000, v19
	v_mul_f32_e32 v37, 0xbfb8aa3b, v37
	v_exp_f32_e32 v50, v37
	v_mul_f32_e32 v36, v36, v39
	v_pk_mul_f32 v[32:33], v[32:33], v[38:39] op_sel_hi:[1,0]
	v_pk_add_f32 v[38:39], v[48:49], 1.0 op_sel_hi:[1,0]
	v_pk_add_f32 v[48:49], v[50:51], 1.0 op_sel_hi:[1,0]
	v_mov_b32_e32 v50, v39
	v_mov_b32_e32 v51, v49
	v_mov_b32_e32 v52, v38
	v_mov_b32_e32 v53, v48
	v_pk_mul_f32 v[50:51], v[50:51], v[52:53]
	v_pk_mul_f32 v[32:33], v[20:21], v[32:33]
	v_mul_f32_e32 v37, v50, v51
	v_rcp_f32_e32 v37, v37
	s_nop 0
	v_pk_mul_f32 v[34:35], v[34:35], v[36:37] op_sel_hi:[1,0]
	s_nop 0
	v_pk_mul_f32 v[34:35], v[22:23], v[34:35]
	v_mul_f32_e32 v20, v51, v37
	v_mul_f32_e32 v22, v50, v37
	v_pk_mul_f32 v[20:21], v[38:39], v[20:21] op_sel_hi:[1,0]
	v_pk_mul_f32 v[22:23], v[48:49], v[22:23] op_sel_hi:[1,0]
	v_pk_mul_f32 v[36:37], v[16:17], v[20:21]
	v_pk_mul_f32 v[38:39], v[18:19], v[22:23]

; __device__ __forceinline__ f32x4 sigmoid4(f32x4 x) {
;     f32x4 d;
; #pragma unroll
;     for (int j = 0; j < 4; ++j) d[j] = 1.0f + __expf(-fmaxf(x[j], -20.0f));
;     const float p01 = d[0] * d[1], p23 = d[2] * d[3], r = __builtin_amdgcn_rcpf(p01 * p23), r01 = r * p23, r23 = r * p01;
;     return (f32x4){r01 * d[1], r01 * d[0], r23 * d[3], r23 * d[2]};
;     __device__ __forceinline__ void operator()(const f32x4 (&acc)[2][2][4][2], const Unit& u, int wr, int wc, int fr, int fq) const {
;     ...
;                 for (int bj = 0; bj < 2; ++bj) { f32x4 v0 = acc[ai][bj][m][0] + bv[bj][0], v1 = acc[ai][bj][m][1] + bv[bj][1];
;                     if (act == 1) {
; #pragma unroll
;                         for (int j = 0; j < 1; ++j) { v0 = v0 * sigmoid4(v0); v1 = v1 * sigmoid4(v1); } }
.LBB0_518:
	s_andn2_b64 vcc, exec, s[0:1]
	s_cbranch_vccnz .LBB0_520
	v_max_f32_e32 v16, 0xc1a00000, v12
	v_max_f32_e32 v18, 0xc1a00000, v14
	v_mul_f32_e32 v16, 0xbfb8aa3b, v16
	v_mul_f32_e32 v18, 0xbfb8aa3b, v18
	v_exp_f32_e32 v17, v16
	v_exp_f32_e32 v19, v18
	v_max_f32_e32 v16, 0xc1a00000, v13
	v_max_f32_e32 v18, 0xc1a00000, v15
	v_mul_f32_e32 v16, 0xbfb8aa3b, v16
	v_mul_f32_e32 v18, 0xbfb8aa3b, v18
	v_exp_f32_e32 v16, v16
	v_exp_f32_e32 v18, v18
	v_pk_add_f32 v[16:17], v[16:17], 1.0 op_sel_hi:[1,0]
	v_pk_add_f32 v[18:19], v[18:19], 1.0 op_sel_hi:[1,0]
	v_mov_b32_e32 v20, v17
	v_mov_b32_e32 v21, v19
	v_mov_b32_e32 v22, v16
	v_mov_b32_e32 v23, v18
	v_pk_mul_f32 v[20:21], v[20:21], v[22:23]
	s_nop 0
	v_mul_f32_e32 v22, v20, v21
	v_rcp_f32_e32 v23, v22
	s_nop 0
	v_mul_f32_e32 v22, v21, v23
	v_max_f32_e32 v21, 0xc1a00000, v8
	v_mul_f32_e32 v21, 0xbfb8aa3b, v21
	v_exp_f32_e32 v33, v21
	v_max_f32_e32 v21, 0xc1a00000, v9
	v_mul_f32_e32 v21, 0xbfb8aa3b, v21
	v_exp_f32_e32 v32, v21
	v_max_f32_e32 v21, 0xc1a00000, v10
	v_mul_f32_e32 v21, 0xbfb8aa3b, v21
	v_exp_f32_e32 v35, v21
	v_max_f32_e32 v21, 0xc1a00000, v11
	v_mul_f32_e32 v21, 0xbfb8aa3b, v21
	v_exp_f32_e32 v34, v21
	v_mul_f32_e32 v20, v20, v23
	v_pk_mul_f32 v[16:17], v[16:17], v[22:23] op_sel_hi:[1,0]
	v_pk_add_f32 v[22:23], v[32:33], 1.0 op_sel_hi:[1,0]
	v_pk_add_f32 v[32:33], v[34:35], 1.0 op_sel_hi:[1,0]
	v_mov_b32_e32 v34, v23
	v_mov_b32_e32 v35, v33
	v_mov_b32_e32 v36, v22
	v_mov_b32_e32 v37, v32
	v_pk_mul_f32 v[34:35], v[34:35], v[36:37]
	v_pk_mul_f32 v[16:17], v[12:13], v[16:17]
	v_mul_f32_e32 v21, v34, v35
	v_rcp_f32_e32 v21, v21
	s_nop 0
	v_pk_mul_f32 v[18:19], v[18:19], v[20:21] op_sel_hi:[1,0]
	s_nop 0
	v_pk_mul_f32 v[18:19], v[14:15], v[18:19]
	v_mul_f32_e32 v12, v35, v21
	v_mul_f32_e32 v14, v34, v21
	v_pk_mul_f32 v[12:13], v[22:23], v[12:13] op_sel_hi:[1,0]
	v_pk_mul_f32 v[14:15], v[32:33], v[14:15] op_sel_hi:[1,0]
	v_pk_mul_f32 v[20:21], v[8:9], v[12:13]
	v_pk_mul_f32 v[22:23], v[10:11], v[14:15]

; __device__ __forceinline__ f32x4 sigmoid4(f32x4 x) {
;     f32x4 d;
; #pragma unroll
;     for (int j = 0; j < 4; ++j) d[j] = 1.0f + __expf(-fmaxf(x[j], -20.0f));
;     const float p01 = d[0] * d[1], p23 = d[2] * d[3], r = __builtin_amdgcn_rcpf(p01 * p23), r01 = r * p23, r23 = r * p01;
;     return (f32x4){r01 * d[1], r01 * d[0], r23 * d[3], r23 * d[2]};
;     __device__ __forceinline__ void operator()(const f32x4 (&acc)[2][2][4][2], const Unit& u, int wr, int wc, int fr, int fq) const {
;     ...
;                 for (int bj = 0; bj < 2; ++bj) { f32x4 v0 = acc[ai][bj][m][0] + bv[bj][0], v1 = acc[ai][bj][m][1] + bv[bj][1];
;                     if (act == 1) {
; #pragma unroll
;                         for (int j = 0; j < 1; ++j) { v0 = v0 * sigmoid4(v0); v1 = v1 * sigmoid4(v1); } }
.LBB0_524:
	s_andn2_b64 vcc, exec, s[0:1]
	s_cbranch_vccnz .LBB0_408
	v_max_f32_e32 v8, 0xc1a00000, v4
	v_max_f32_e32 v10, 0xc1a00000, v6
	v_mul_f32_e32 v8, 0xbfb8aa3b, v8
	v_mul_f32_e32 v10, 0xbfb8aa3b, v10
	v_exp_f32_e32 v9, v8
	v_exp_f32_e32 v11, v10
	v_max_f32_e32 v8, 0xc1a00000, v5
	v_max_f32_e32 v10, 0xc1a00000, v7
	v_mul_f32_e32 v8, 0xbfb8aa3b, v8
	v_mul_f32_e32 v10, 0xbfb8aa3b, v10
	v_exp_f32_e32 v8, v8
	v_exp_f32_e32 v10, v10
	v_pk_add_f32 v[8:9], v[8:9], 1.0 op_sel_hi:[1,0]
	v_pk_add_f32 v[10:11], v[10:11], 1.0 op_sel_hi:[1,0]
	v_mov_b32_e32 v12, v9
	v_mov_b32_e32 v13, v11
	v_mov_b32_e32 v14, v8
	v_mov_b32_e32 v15, v10
	v_pk_mul_f32 v[12:13], v[12:13], v[14:15]
	s_nop 0
	v_mul_f32_e32 v14, v12, v13
	v_rcp_f32_e32 v15, v14
	s_nop 0
	v_mul_f32_e32 v14, v13, v15
	v_max_f32_e32 v13, 0xc1a00000, v0
	v_mul_f32_e32 v13, 0xbfb8aa3b, v13
	v_exp_f32_e32 v17, v13
	v_max_f32_e32 v13, 0xc1a00000, v1
	v_mul_f32_e32 v13, 0xbfb8aa3b, v13
	v_exp_f32_e32 v16, v13
	v_max_f32_e32 v13, 0xc1a00000, v2
	v_mul_f32_e32 v13, 0xbfb8aa3b, v13
	v_exp_f32_e32 v19, v13
	v_max_f32_e32 v13, 0xc1a00000, v3
	v_mul_f32_e32 v13, 0xbfb8aa3b, v13
	v_exp_f32_e32 v18, v13
	v_mul_f32_e32 v12, v12, v15
	v_pk_mul_f32 v[8:9], v[8:9], v[14:15] op_sel_hi:[1,0]
	v_pk_add_f32 v[14:15], v[16:17], 1.0 op_sel_hi:[1,0]
	v_pk_add_f32 v[16:17], v[18:19], 1.0 op_sel_hi:[1,0]
	v_mov_b32_e32 v18, v15
	v_mov_b32_e32 v19, v17
	v_mov_b32_e32 v20, v14
	v_mov_b32_e32 v21, v16
	v_pk_mul_f32 v[18:19], v[18:19], v[20:21]
	v_pk_mul_f32 v[8:9], v[4:5], v[8:9]
	v_mul_f32_e32 v13, v18, v19
	v_rcp_f32_e32 v13, v13
	s_nop 0
	v_pk_mul_f32 v[10:11], v[10:11], v[12:13] op_sel_hi:[1,0]
	s_nop 0
	v_pk_mul_f32 v[10:11], v[6:7], v[10:11]
	v_mul_f32_e32 v4, v19, v13
	v_mul_f32_e32 v6, v18, v13
	v_pk_mul_f32 v[4:5], v[14:15], v[4:5] op_sel_hi:[1,0]
	v_pk_mul_f32 v[6:7], v[16:17], v[6:7] op_sel_hi:[1,0]
	v_pk_mul_f32 v[12:13], v[0:1], v[4:5]
	v_pk_mul_f32 v[14:15], v[2:3], v[6:7]
	s_branch .LBB0_408

; #define PG8_STAGE(bufoff, gbase, voff) do { _Pragma("unroll") for (int _i = 0; _i < 2; ++_i) \
;         __builtin_amdgcn_global_load_lds((const unsigned*)((const char*)(gbase) + (voff)[_i]), (PG8_LAS unsigned*)(lds + (bufoff) + ldsw + _i * 8192), 16, 0, 0); } while (0)
; #define PG8_LDA(dst, b, h) do { _Pragma("unroll") for (int m = 0; m < 4; ++m) _Pragma("unroll") for (int k = 0; k < 2; ++k) dst[m][k] = *(const PG8_LAS bf16x8*)(lds + PG8_SA(b, h) + aoff + m * 2048 + k * 1024); } while (0)
; #define PG8_LDB(dst, b, h) do { _Pragma("unroll") for (int n = 0; n < 2; ++n) _Pragma("unroll") for (int k = 0; k < 2; ++k) dst[n][k] = *(const PG8_LAS bf16x8*)(lds + PG8_SB(b, h) + boff + n * 2048 + k * 1024); } while (0)
; #define PG8_WAIT_V(n) asm volatile("s_waitcnt vmcnt(" #n ")" ::: "memory")
; #define PG8_WAIT_L(n) asm volatile("s_waitcnt lgkmcnt(" #n ")" ::: "memory")
; #define PG8_BAR __builtin_amdgcn_s_barrier()
; #define PG8_SCHED __builtin_amdgcn_sched_barrier(0)
; template <class Epi, class Sched>
; __device__ __forceinline__ void gemm_phase(PG8_LAS unsigned char* lds, const Gemm g, const Sched& S, const Epi& E) {
;     ...
;             PG8_LDB(B0, 0, 0); PG8_SCHED; PG8_LDA(At, 0, 0); PG8_STAGE(PG8_SA(1, 1), a1 + hstep, voffA);
;             PG8_WAIT_L(8); PG8_BAR; PG8_WAIT_L(0); PG8_MMA(0, 0, At, B0); PG8_BAR; PG8_SCHED;
;             PG8_LDB(B1, 0, 1); PG8_STAGE(PG8_SB(0, 0), b2, voffB);
;             PG8_BAR; PG8_WAIT_L(0); PG8_MMA(0, 1, At, B1); PG8_BAR;
;             PG8_LDA(At, 0, 1); PG8_STAGE(PG8_SA(0, 0), a2, voffA);
;             PG8_BAR; PG8_WAIT_L(0); PG8_MMA(1, 0, At, B0); PG8_BAR; PG8_SCHED;
;             PG8_STAGE(PG8_SB(0, 1), b2 + hstep, voffB);
;             PG8_WAIT_V(6); PG8_BAR; PG8_MMA(1, 1, At, B1); PG8_BAR;
;             PG8_LDB(B0, 1, 0); PG8_SCHED; PG8_LDA(At, 1, 0); PG8_STAGE(PG8_SA(0, 1), a2 + hstep, voffA);
;             PG8_WAIT_L(8); PG8_BAR; PG8_WAIT_L(0); PG8_MMA(0, 0, At, B0); PG8_BAR; PG8_SCHED;
;             PG8_LDB(B1, 1, 1); PG8_STAGE(PG8_SB(1, 0), b3, voffB);
;             PG8_BAR; PG8_WAIT_L(0); PG8_MMA(0, 1, At, B1); PG8_BAR;
;             PG8_LDA(At, 1, 1); PG8_STAGE(PG8_SA(1, 0), a3, voffA);
;             PG8_BAR; PG8_WAIT_L(0); PG8_MMA(1, 0, At, B0); PG8_BAR; PG8_SCHED;
;             PG8_STAGE(PG8_SB(1, 1), b3 + hstep, voffB);
;             PG8_WAIT_V(6); PG8_BAR; PG8_MMA(1, 1, At, B1); PG8_BAR;
.LBB0_724:
	ds_read_b128 v[144:147], v151
	ds_read_b128 v[156:159], v151 offset:1024
	ds_read_b128 v[160:163], v151 offset:2048
	ds_read_b128 v[166:169], v151 offset:3072
	s_add_u32 s20, s18, 0xfffc0080
	s_addc_u32 s21, s19, -1
	s_cmp_eq_u32 s48, 12
	s_cselect_b32 s23, s5, s21
	s_cselect_b32 s22, s11, s20
	s_cselect_b32 s21, s9, s47
	s_cselect_b32 s20, s45, s46
	v_lshl_add_u64 v[174:175], s[18:19], 0, v[136:137]
	s_add_i32 m0, s17, 0xc000
	ds_read_b128 v[170:173], v153
	ds_read_b128 v[182:185], v153 offset:1024
	ds_read_b128 v[190:193], v153 offset:2048
	ds_read_b128 v[194:197], v153 offset:3072
	ds_read_b128 v[198:201], v153 offset:4096
	ds_read_b128 v[202:205], v153 offset:5120
	ds_read_b128 v[206:209], v153 offset:6144
	ds_read_b128 v[210:213], v153 offset:7168
	global_load_lds_dwordx4 v[174:175], off
	v_lshl_add_u64 v[174:175], s[18:19], 0, v[138:139]
	s_add_i32 m0, s17, 0xe000
	s_nop 0
	global_load_lds_dwordx4 v[174:175], off
	s_waitcnt lgkmcnt(8)
	ds_read_b128 v[214:217], v154
	ds_read_b128 v[218:221], v154 offset:1024
	ds_read_b128 v[222:225], v154 offset:2048
	ds_read_b128 v[226:229], v154 offset:3072
	s_waitcnt vmcnt(8) lgkmcnt(0)
	s_barrier
	v_mfma_f32_16x16x32_bf16 v[124:127], v[144:147], v[170:173], v[124:127]
	v_mfma_f32_16x16x32_bf16 v[120:123], v[160:163], v[170:173], v[120:123]
	v_mfma_f32_16x16x32_bf16 v[108:111], v[144:147], v[190:193], v[108:111]
	v_mfma_f32_16x16x32_bf16 v[104:107], v[160:163], v[190:193], v[104:107]
	v_mfma_f32_16x16x32_bf16 v[92:95], v[144:147], v[198:201], v[92:95]
	v_mfma_f32_16x16x32_bf16 v[88:91], v[160:163], v[198:201], v[88:91]
	v_mfma_f32_16x16x32_bf16 v[76:79], v[144:147], v[206:209], v[76:79]
	v_mfma_f32_16x16x32_bf16 v[72:75], v[160:163], v[206:209], v[72:75]
	v_mfma_f32_16x16x32_bf16 v[124:127], v[156:159], v[182:185], v[124:127]
	v_mfma_f32_16x16x32_bf16 v[120:123], v[166:169], v[182:185], v[120:123]
	v_mfma_f32_16x16x32_bf16 v[108:111], v[156:159], v[194:197], v[108:111]
	v_mfma_f32_16x16x32_bf16 v[104:107], v[166:169], v[194:197], v[104:107]
	v_mfma_f32_16x16x32_bf16 v[92:95], v[156:159], v[202:205], v[92:95]
	v_mfma_f32_16x16x32_bf16 v[88:91], v[166:169], v[202:205], v[88:91]
	v_mfma_f32_16x16x32_bf16 v[76:79], v[156:159], v[210:213], v[76:79]
	v_mfma_f32_16x16x32_bf16 v[72:75], v[166:169], v[210:213], v[72:75]
	v_mfma_f32_16x16x32_bf16 v[116:119], v[214:217], v[170:173], v[116:119]
	v_mfma_f32_16x16x32_bf16 v[112:115], v[222:225], v[170:173], v[112:115]
	v_mfma_f32_16x16x32_bf16 v[100:103], v[214:217], v[190:193], v[100:103]
	v_mfma_f32_16x16x32_bf16 v[96:99], v[222:225], v[190:193], v[96:99]
	v_mfma_f32_16x16x32_bf16 v[84:87], v[214:217], v[198:201], v[84:87]
	v_mfma_f32_16x16x32_bf16 v[80:83], v[222:225], v[198:201], v[80:83]
	v_mfma_f32_16x16x32_bf16 v[68:71], v[214:217], v[206:209], v[68:71]
	v_mfma_f32_16x16x32_bf16 v[64:67], v[222:225], v[206:209], v[64:67]
	v_mfma_f32_16x16x32_bf16 v[116:119], v[218:221], v[182:185], v[116:119]
	v_mfma_f32_16x16x32_bf16 v[112:115], v[226:229], v[182:185], v[112:115]
	v_mfma_f32_16x16x32_bf16 v[100:103], v[218:221], v[194:197], v[100:103]
	v_mfma_f32_16x16x32_bf16 v[96:99], v[226:229], v[194:197], v[96:99]
	v_mfma_f32_16x16x32_bf16 v[84:87], v[218:221], v[202:205], v[84:87]
	v_mfma_f32_16x16x32_bf16 v[80:83], v[226:229], v[202:205], v[80:83]
	v_mfma_f32_16x16x32_bf16 v[68:71], v[218:221], v[210:213], v[68:71]
	v_mfma_f32_16x16x32_bf16 v[64:67], v[226:229], v[210:213], v[64:67]
	s_barrier
	ds_read_b128 v[170:173], v153 offset:16384
	ds_read_b128 v[182:185], v153 offset:17408
	ds_read_b128 v[190:193], v153 offset:18432
	ds_read_b128 v[194:197], v153 offset:19456
	ds_read_b128 v[198:201], v153 offset:20480
	ds_read_b128 v[202:205], v153 offset:21504
	ds_read_b128 v[206:209], v153 offset:22528
	ds_read_b128 v[210:213], v153 offset:23552
	s_add_i32 s49, s42, s30
	v_lshl_add_u64 v[174:175], s[20:21], 0, v[130:131]
	s_mov_b32 m0, s49
	s_nop 0
	global_load_lds_dwordx4 v[174:175], off
	v_lshl_add_u64 v[186:187], s[20:21], 0, v[134:135]
	s_add_i32 m0, s49, 0x2000
	s_nop 0
	global_load_lds_dwordx4 v[186:187], off
	s_nop 1
	s_mov_b32 m0, s17
	v_lshl_add_u64 v[230:231], s[22:23], 0, v[128:129]
	global_load_lds_dwordx4 v[230:231], off
	v_lshl_add_u64 v[232:233], s[22:23], 0, v[132:133]
	s_mov_b32 m0, s31
	s_nop 0
	global_load_lds_dwordx4 v[232:233], off
	s_add_u32 s50, s20, 0x40000
	s_addc_u32 s51, s21, 0
	s_add_i32 s49, s43, s30
	v_lshl_add_u64 v[246:247], s[50:51], 0, v[130:131]
	s_mov_b32 m0, s49
	s_nop 0
	global_load_lds_dwordx4 v[246:247], off
	v_lshl_add_u64 v[246:247], s[50:51], 0, v[134:135]
	s_add_i32 m0, s49, 0x2000
	s_nop 0
	global_load_lds_dwordx4 v[246:247], off
	s_waitcnt vmcnt(8) lgkmcnt(0)
	s_barrier
; #define PG8_STAGE(bufoff, gbase, voff) do { _Pragma("unroll") for (int _i = 0; _i < 2; ++_i) \
;         __builtin_amdgcn_global_load_lds((const unsigned*)((const char*)(gbase) + (voff)[_i]), (PG8_LAS unsigned*)(lds + (bufoff) + ldsw + _i * 8192), 16, 0, 0); } while (0)
; #define PG8_LDA(dst, b, h) do { _Pragma("unroll") for (int m = 0; m < 4; ++m) _Pragma("unroll") for (int k = 0; k < 2; ++k) dst[m][k] = *(const PG8_LAS bf16x8*)(lds + PG8_SA(b, h) + aoff + m * 2048 + k * 1024); } while (0)
; #define PG8_LDB(dst, b, h) do { _Pragma("unroll") for (int n = 0; n < 2; ++n) _Pragma("unroll") for (int k = 0; k < 2; ++k) dst[n][k] = *(const PG8_LAS bf16x8*)(lds + PG8_SB(b, h) + boff + n * 2048 + k * 1024); } while (0)
; #define PG8_MMA(ai, bj, At, Bt) do { __builtin_amdgcn_s_setprio(1); _Pragma("unroll") for (int m = 0; m < 4; ++m) _Pragma("unroll") for (int n = 0; n < 2; ++n) _Pragma("unroll") for (int k = 0; k < 2; ++k) \
;         acc[ai][bj][m][n] = __builtin_amdgcn_mfma_f32_16x16x32_bf16(Bt[n][k], At[m][k], acc[ai][bj][m][n], 0, 0, 0); __builtin_amdgcn_s_setprio(0); } while (0)
; #define PG8_WAIT_V(n) asm volatile("s_waitcnt vmcnt(" #n ")" ::: "memory")
; #define PG8_WAIT_L(n) asm volatile("s_waitcnt lgkmcnt(" #n ")" ::: "memory")
; #define PG8_BAR __builtin_amdgcn_s_barrier()
; #define PG8_SCHED __builtin_amdgcn_sched_barrier(0)
; template <class Epi, class Sched>
; __device__ __forceinline__ void gemm_phase(PG8_LAS unsigned char* lds, const Gemm g, const Sched& S, const Epi& E) {
;     ...
;             PG8_BAR; PG8_WAIT_L(0); PG8_MMA(1, 0, At, B0); PG8_BAR; PG8_SCHED;
;             PG8_STAGE(PG8_SB(0, 1), b2 + hstep, voffB);
;             PG8_WAIT_V(6); PG8_BAR; PG8_MMA(1, 1, At, B1); PG8_BAR;
;             PG8_LDB(B0, 1, 0); PG8_SCHED; PG8_LDA(At, 1, 0); PG8_STAGE(PG8_SA(0, 1), a2 + hstep, voffA);
;             PG8_WAIT_L(8); PG8_BAR; PG8_WAIT_L(0); PG8_MMA(0, 0, At, B0); PG8_BAR; PG8_SCHED;
;             PG8_LDB(B1, 1, 1); PG8_STAGE(PG8_SB(1, 0), b3, voffB);
;             PG8_BAR; PG8_WAIT_L(0); PG8_MMA(0, 1, At, B1); PG8_BAR;
;             PG8_LDA(At, 1, 1); PG8_STAGE(PG8_SA(1, 0), a3, voffA);
;             PG8_BAR; PG8_WAIT_L(0); PG8_MMA(1, 0, At, B0); PG8_BAR; PG8_SCHED;
	v_mfma_f32_16x16x32_bf16 v[60:63], v[144:147], v[170:173], v[60:63]
	v_mfma_f32_16x16x32_bf16 v[56:59], v[160:163], v[170:173], v[56:59]
	v_mfma_f32_16x16x32_bf16 v[44:47], v[144:147], v[190:193], v[44:47]
	v_mfma_f32_16x16x32_bf16 v[40:43], v[160:163], v[190:193], v[40:43]
	v_mfma_f32_16x16x32_bf16 v[28:31], v[144:147], v[198:201], v[28:31]
	v_mfma_f32_16x16x32_bf16 v[24:27], v[160:163], v[198:201], v[24:27]
	v_mfma_f32_16x16x32_bf16 v[12:15], v[144:147], v[206:209], v[12:15]
	v_mfma_f32_16x16x32_bf16 v[8:11], v[160:163], v[206:209], v[8:11]
	v_mfma_f32_16x16x32_bf16 v[60:63], v[156:159], v[182:185], v[60:63]
	v_mfma_f32_16x16x32_bf16 v[56:59], v[166:169], v[182:185], v[56:59]
	v_mfma_f32_16x16x32_bf16 v[44:47], v[156:159], v[194:197], v[44:47]
	v_mfma_f32_16x16x32_bf16 v[40:43], v[166:169], v[194:197], v[40:43]
	v_mfma_f32_16x16x32_bf16 v[28:31], v[156:159], v[202:205], v[28:31]
	v_mfma_f32_16x16x32_bf16 v[24:27], v[166:169], v[202:205], v[24:27]
	v_mfma_f32_16x16x32_bf16 v[12:15], v[156:159], v[210:213], v[12:15]
	v_mfma_f32_16x16x32_bf16 v[8:11], v[166:169], v[210:213], v[8:11]
	v_mfma_f32_16x16x32_bf16 v[52:55], v[214:217], v[170:173], v[52:55]
	v_mfma_f32_16x16x32_bf16 v[48:51], v[222:225], v[170:173], v[48:51]
	v_mfma_f32_16x16x32_bf16 v[36:39], v[214:217], v[190:193], v[36:39]
	v_mfma_f32_16x16x32_bf16 v[32:35], v[222:225], v[190:193], v[32:35]
	v_mfma_f32_16x16x32_bf16 v[20:23], v[214:217], v[198:201], v[20:23]
	v_mfma_f32_16x16x32_bf16 v[16:19], v[222:225], v[198:201], v[16:19]
	v_mfma_f32_16x16x32_bf16 v[4:7], v[214:217], v[206:209], v[4:7]
	v_mfma_f32_16x16x32_bf16 v[0:3], v[222:225], v[206:209], v[0:3]
	v_mfma_f32_16x16x32_bf16 v[52:55], v[218:221], v[182:185], v[52:55]
	v_mfma_f32_16x16x32_bf16 v[48:51], v[226:229], v[182:185], v[48:51]
	v_mfma_f32_16x16x32_bf16 v[36:39], v[218:221], v[194:197], v[36:39]
	v_mfma_f32_16x16x32_bf16 v[32:35], v[226:229], v[194:197], v[32:35]
	v_mfma_f32_16x16x32_bf16 v[20:23], v[218:221], v[202:205], v[20:23]
	v_mfma_f32_16x16x32_bf16 v[16:19], v[226:229], v[202:205], v[16:19]
	v_mfma_f32_16x16x32_bf16 v[4:7], v[218:221], v[210:213], v[4:7]
	v_mfma_f32_16x16x32_bf16 v[0:3], v[226:229], v[210:213], v[0:3]
	s_barrier
	s_add_i32 s49, 0, 0x18000
	v_add_u32_e32 v155, s49, v149
	ds_read_b128 v[144:147], v155
	ds_read_b128 v[156:159], v155 offset:1024
	ds_read_b128 v[160:163], v155 offset:2048
	ds_read_b128 v[166:169], v155 offset:3072
	s_add_u32 s22, s22, 0x40000
	s_addc_u32 s23, s23, 0
	s_mov_b32 m0, s34
	v_lshl_add_u64 v[214:215], s[22:23], 0, v[128:129]
	ds_read_b128 v[170:173], v153 offset:32768
	ds_read_b128 v[182:185], v153 offset:33792
	ds_read_b128 v[190:193], v153 offset:34816
	ds_read_b128 v[194:197], v153 offset:35840
	ds_read_b128 v[198:201], v153 offset:36864
	ds_read_b128 v[202:205], v153 offset:37888
	ds_read_b128 v[206:209], v153 offset:38912
	ds_read_b128 v[210:213], v153 offset:39936
	global_load_lds_dwordx4 v[214:215], off
	v_lshl_add_u64 v[214:215], s[22:23], 0, v[132:133]
	s_mov_b32 m0, s35
	s_nop 0
	global_load_lds_dwordx4 v[214:215], off
	s_add_i32 s22, 0, 0x1c000
	v_add_u32_e32 v155, s22, v149
	s_waitcnt lgkmcnt(8)
	ds_read_b128 v[214:217], v155
	ds_read_b128 v[218:221], v155 offset:1024
	ds_read_b128 v[222:225], v155 offset:2048
	ds_read_b128 v[226:229], v155 offset:3072
	s_waitcnt vmcnt(8) lgkmcnt(0)
	s_barrier
	v_mfma_f32_16x16x32_bf16 v[124:127], v[144:147], v[170:173], v[124:127]
	v_mfma_f32_16x16x32_bf16 v[120:123], v[160:163], v[170:173], v[120:123]
	v_mfma_f32_16x16x32_bf16 v[108:111], v[144:147], v[190:193], v[108:111]
	v_mfma_f32_16x16x32_bf16 v[104:107], v[160:163], v[190:193], v[104:107]
	v_mfma_f32_16x16x32_bf16 v[92:95], v[144:147], v[198:201], v[92:95]
	v_mfma_f32_16x16x32_bf16 v[88:91], v[160:163], v[198:201], v[88:91]
	v_mfma_f32_16x16x32_bf16 v[76:79], v[144:147], v[206:209], v[76:79]
	v_mfma_f32_16x16x32_bf16 v[72:75], v[160:163], v[206:209], v[72:75]
	v_mfma_f32_16x16x32_bf16 v[124:127], v[156:159], v[182:185], v[124:127]
	v_mfma_f32_16x16x32_bf16 v[120:123], v[166:169], v[182:185], v[120:123]
	v_mfma_f32_16x16x32_bf16 v[108:111], v[156:159], v[194:197], v[108:111]
	v_mfma_f32_16x16x32_bf16 v[104:107], v[166:169], v[194:197], v[104:107]
	v_mfma_f32_16x16x32_bf16 v[92:95], v[156:159], v[202:205], v[92:95]
	v_mfma_f32_16x16x32_bf16 v[88:91], v[166:169], v[202:205], v[88:91]
	v_mfma_f32_16x16x32_bf16 v[76:79], v[156:159], v[210:213], v[76:79]
	v_mfma_f32_16x16x32_bf16 v[72:75], v[166:169], v[210:213], v[72:75]
	v_mfma_f32_16x16x32_bf16 v[116:119], v[214:217], v[170:173], v[116:119]
	v_mfma_f32_16x16x32_bf16 v[112:115], v[222:225], v[170:173], v[112:115]
	v_mfma_f32_16x16x32_bf16 v[100:103], v[214:217], v[190:193], v[100:103]
	v_mfma_f32_16x16x32_bf16 v[96:99], v[222:225], v[190:193], v[96:99]
	v_mfma_f32_16x16x32_bf16 v[84:87], v[214:217], v[198:201], v[84:87]
	v_mfma_f32_16x16x32_bf16 v[80:83], v[222:225], v[198:201], v[80:83]
	v_mfma_f32_16x16x32_bf16 v[68:71], v[214:217], v[206:209], v[68:71]
	v_mfma_f32_16x16x32_bf16 v[64:67], v[222:225], v[206:209], v[64:67]
	v_mfma_f32_16x16x32_bf16 v[116:119], v[218:221], v[182:185], v[116:119]
	v_mfma_f32_16x16x32_bf16 v[112:115], v[226:229], v[182:185], v[112:115]
	v_mfma_f32_16x16x32_bf16 v[100:103], v[218:221], v[194:197], v[100:103]
	v_mfma_f32_16x16x32_bf16 v[96:99], v[226:229], v[194:197], v[96:99]
	v_mfma_f32_16x16x32_bf16 v[84:87], v[218:221], v[202:205], v[84:87]
	v_mfma_f32_16x16x32_bf16 v[80:83], v[226:229], v[202:205], v[80:83]
	v_mfma_f32_16x16x32_bf16 v[68:71], v[218:221], v[210:213], v[68:71]
	v_mfma_f32_16x16x32_bf16 v[64:67], v[226:229], v[210:213], v[64:67]
	s_barrier
; #define PG8_LDA(dst, b, h) do { _Pragma("unroll") for (int m = 0; m < 4; ++m) _Pragma("unroll") for (int k = 0; k < 2; ++k) dst[m][k] = *(const PG8_LAS bf16x8*)(lds + PG8_SA(b, h) + aoff + m * 2048 + k * 1024); } while (0)
;     __device__ __forceinline__ void operator()(const f32x4 (&acc)[2][2][4][2], const Unit& u, int wr, int wc, int fr, int fq) const {
;     ...
;         if (mode == 1) { if (u.pn >= 8 && u.pn < 12) act = 1; else if (u.pn >= 12) { act = 3; bias = (u.pn >= 14) ? bias_b + (u.pn - 14) * 256 : bias_f + (u.pn - 12) * 256; } }
;         else if (mode == 2) { if (u.pn >= 6) act = 2; }
;         const int row0 = u.pm * BM + wr * 64 + fr, col0 = u.pn * BM + wc * 32 + 8 * fq, bcol0 = wc * 32 + 8 * fq;
;         f32x4 bv[2][2];
; #pragma unroll
;         for (int bj = 0; bj < 2; ++bj)
; #pragma unroll
;             for (int n = 0; n < 2; ++n) bv[bj][n] = bias ? *(const f32x4*)(bias + bcol0 + bj * HALF + 4 * n) : (f32x4){0.f, 0.f, 0.f, 0.f};
; #pragma unroll
;         for (int ai = 0; ai < 2; ++ai)
; #pragma unroll
;             for (int m = 0; m < 4; ++m) { bf16_t* rowp = O + (size_t)(row0 + ai * HALF + m * 16) * ldc + col0;
; #pragma unroll
;                 for (int bj = 0; bj < 2; ++bj) { f32x4 v0 = acc[ai][bj][m][0] + bv[bj][0], v1 = acc[ai][bj][m][1] + bv[bj][1];
;                     if (act == 1) {
; #pragma unroll
;                         for (int j = 0; j < 1; ++j) { v0 = v0 * sigmoid4(v0); v1 = v1 * sigmoid4(v1); } }
;                     else if (act == 2) {
; #pragma unroll
;                         for (int j = 0; j < 1; ++j) { v0 = sigmoid4(v0); v1 = sigmoid4(v1); } }
; template <class Epi, class Sched>
; __device__ __forceinline__ void gemm_phase(PG8_LAS unsigned char* lds, const Gemm g, const Sched& S, const Epi& E) {
;     ...
;             PG8_LDB(B0, 1, 0); PG8_SCHED; PG8_LDA(At, 1, 0); PG8_STAGE(PG8_SA(0, 1), a2 + hstep, voffA);
;             PG8_WAIT_L(8); PG8_BAR; PG8_WAIT_L(0); PG8_MMA(0, 0, At, B0); PG8_BAR; PG8_SCHED;
;             PG8_LDB(B1, 1, 1); PG8_STAGE(PG8_SB(1, 0), b3, voffB);
;             PG8_BAR; PG8_WAIT_L(0); PG8_MMA(0, 1, At, B1); PG8_BAR;
;             PG8_LDA(At, 1, 1); PG8_STAGE(PG8_SA(1, 0), a3, voffA);
;             PG8_BAR; PG8_WAIT_L(0); PG8_MMA(1, 0, At, B0); PG8_BAR; PG8_SCHED;
;             PG8_STAGE(PG8_SB(1, 1), b3 + hstep, voffB);
;             PG8_WAIT_V(6); PG8_BAR; PG8_MMA(1, 1, At, B1); PG8_BAR;
	ds_read_b128 v[170:173], v153 offset:49152
	ds_read_b128 v[182:185], v153 offset:50176
	ds_read_b128 v[190:193], v153 offset:51200
	ds_read_b128 v[194:197], v153 offset:52224
	ds_read_b128 v[198:201], v153 offset:53248
	ds_read_b128 v[202:205], v153 offset:54272
	ds_read_b128 v[206:209], v153 offset:55296
	ds_read_b128 v[210:213], v153 offset:56320
	s_add_i32 s23, s49, s30
	v_lshl_add_u64 v[174:175], v[174:175], 0, s[6:7]
	s_mov_b32 m0, s23
	s_nop 0
	global_load_lds_dwordx4 v[174:175], off
	v_lshl_add_u64 v[174:175], v[186:187], 0, s[6:7]
	s_add_i32 m0, s23, 0x2000
	s_nop 0
	global_load_lds_dwordx4 v[174:175], off
	s_nop 1
	s_mov_b32 m0, s37
	v_lshl_add_u64 v[174:175], v[230:231], 0, s[6:7]
	global_load_lds_dwordx4 v[174:175], off
	v_lshl_add_u64 v[174:175], v[232:233], 0, s[6:7]
	s_mov_b32 m0, s38
	s_nop 0
	global_load_lds_dwordx4 v[174:175], off
	s_add_u32 s20, s20, 0x40080
	s_addc_u32 s21, s21, 0
	s_add_i32 s22, s22, s30
	v_lshl_add_u64 v[246:247], s[20:21], 0, v[130:131]
	s_mov_b32 m0, s22
	s_nop 0
	global_load_lds_dwordx4 v[246:247], off
	v_lshl_add_u64 v[246:247], s[20:21], 0, v[134:135]
	s_add_i32 m0, s22, 0x2000
	s_nop 0
	global_load_lds_dwordx4 v[246:247], off
	s_waitcnt vmcnt(8) lgkmcnt(0)
	s_barrier
	v_mfma_f32_16x16x32_bf16 v[60:63], v[144:147], v[170:173], v[60:63]
	v_mfma_f32_16x16x32_bf16 v[56:59], v[160:163], v[170:173], v[56:59]
	v_mfma_f32_16x16x32_bf16 v[44:47], v[144:147], v[190:193], v[44:47]
	v_mfma_f32_16x16x32_bf16 v[40:43], v[160:163], v[190:193], v[40:43]
	v_mfma_f32_16x16x32_bf16 v[28:31], v[144:147], v[198:201], v[28:31]
	v_mfma_f32_16x16x32_bf16 v[24:27], v[160:163], v[198:201], v[24:27]
	v_mfma_f32_16x16x32_bf16 v[12:15], v[144:147], v[206:209], v[12:15]
	v_mfma_f32_16x16x32_bf16 v[8:11], v[160:163], v[206:209], v[8:11]
	v_mfma_f32_16x16x32_bf16 v[60:63], v[156:159], v[182:185], v[60:63]
	v_mfma_f32_16x16x32_bf16 v[56:59], v[166:169], v[182:185], v[56:59]
	v_mfma_f32_16x16x32_bf16 v[44:47], v[156:159], v[194:197], v[44:47]
	v_mfma_f32_16x16x32_bf16 v[40:43], v[166:169], v[194:197], v[40:43]
	v_mfma_f32_16x16x32_bf16 v[28:31], v[156:159], v[202:205], v[28:31]
	v_mfma_f32_16x16x32_bf16 v[24:27], v[166:169], v[202:205], v[24:27]
	v_mfma_f32_16x16x32_bf16 v[12:15], v[156:159], v[210:213], v[12:15]
	v_mfma_f32_16x16x32_bf16 v[8:11], v[166:169], v[210:213], v[8:11]
	v_mfma_f32_16x16x32_bf16 v[52:55], v[214:217], v[170:173], v[52:55]
	v_mfma_f32_16x16x32_bf16 v[48:51], v[222:225], v[170:173], v[48:51]
	v_mfma_f32_16x16x32_bf16 v[36:39], v[214:217], v[190:193], v[36:39]
	v_mfma_f32_16x16x32_bf16 v[32:35], v[222:225], v[190:193], v[32:35]
	v_mfma_f32_16x16x32_bf16 v[20:23], v[214:217], v[198:201], v[20:23]
	v_mfma_f32_16x16x32_bf16 v[16:19], v[222:225], v[198:201], v[16:19]
	v_mfma_f32_16x16x32_bf16 v[4:7], v[214:217], v[206:209], v[4:7]
	v_mfma_f32_16x16x32_bf16 v[0:3], v[222:225], v[206:209], v[0:3]
	v_mfma_f32_16x16x32_bf16 v[52:55], v[218:221], v[182:185], v[52:55]
	v_mfma_f32_16x16x32_bf16 v[48:51], v[226:229], v[182:185], v[48:51]
	v_mfma_f32_16x16x32_bf16 v[36:39], v[218:221], v[194:197], v[36:39]
	v_mfma_f32_16x16x32_bf16 v[32:35], v[226:229], v[194:197], v[32:35]
	v_mfma_f32_16x16x32_bf16 v[20:23], v[218:221], v[202:205], v[20:23]
	v_mfma_f32_16x16x32_bf16 v[16:19], v[226:229], v[202:205], v[16:19]
	v_mfma_f32_16x16x32_bf16 v[4:7], v[218:221], v[210:213], v[4:7]
	v_mfma_f32_16x16x32_bf16 v[0:3], v[226:229], v[210:213], v[0:3]
	s_barrier
	s_add_i32 s48, s48, 2
	s_add_u32 s18, s18, 0x100
	s_addc_u32 s19, s19, 0
	s_add_u32 s46, s46, 0x100
	s_addc_u32 s47, s47, 0
	s_cmp_gt_u32 s48, 13
	s_cbranch_scc0 .LBB0_724
	s_cmp_gt_i32 s4, 5
	s_cselect_b64 s[18:19], -1, 0
	s_cmp_lt_i32 s4, 6
	v_pk_add_f32 v[144:145], v[126:127], 0 op_sel_hi:[1,0]
	v_pk_add_f32 v[146:147], v[124:125], 0 op_sel_hi:[1,0]
	v_pk_add_f32 v[124:125], v[122:123], 0 op_sel_hi:[1,0]
	v_pk_add_f32 v[126:127], v[120:121], 0 op_sel_hi:[1,0]
	s_cbranch_scc1 .LBB0_727
	v_max_f32_e32 v122, 0xc1a00000, v144
	v_mul_f32_e32 v122, 0xbfb8aa3b, v122
	v_exp_f32_e32 v123, v122
	v_max_f32_e32 v120, 0xc1a00000, v146
	v_max_f32_e32 v121, 0xc1a00000, v147
	v_max_f32_e32 v122, 0xc1a00000, v145
	v_mul_f32_e32 v120, 0xbfb8aa3b, v120
	v_mul_f32_e32 v121, 0xbfb8aa3b, v121
	v_mul_f32_e32 v122, 0xbfb8aa3b, v122
	v_exp_f32_e32 v120, v120
	v_exp_f32_e32 v121, v121
	v_exp_f32_e32 v122, v122
	v_max_f32_e32 v124, 0xc1a00000, v124
	v_pk_add_f32 v[120:121], v[120:121], 1.0 op_sel_hi:[1,0]
	v_pk_add_f32 v[122:123], v[122:123], 1.0 op_sel_hi:[1,0]
	v_mov_b32_e32 v144, v120
	v_mov_b32_e32 v145, v123
	v_pk_mov_b32 v[146:147], v[120:121], v[122:123] op_sel:[1,0]
	v_mul_f32_e32 v124, 0xbfb8aa3b, v124
	v_pk_mul_f32 v[144:145], v[144:145], v[146:147]
	v_exp_f32_e32 v147, v124
	v_max_f32_e32 v126, 0xc1a00000, v126
	v_max_f32_e32 v127, 0xc1a00000, v127
	v_max_f32_e32 v124, 0xc1a00000, v125
	v_mul_f32_e32 v146, v144, v145
	v_mul_f32_e32 v126, 0xbfb8aa3b, v126
	v_mul_f32_e32 v127, 0xbfb8aa3b, v127
	v_mul_f32_e32 v124, 0xbfb8aa3b, v124
	v_rcp_f32_e32 v155, v146
	v_exp_f32_e32 v126, v126
	v_exp_f32_e32 v127, v127
	v_exp_f32_e32 v146, v124
	v_mul_f32_e32 v124, v145, v155
	v_mul_f32_e32 v144, v144, v155
	v_pk_add_f32 v[126:127], v[126:127], 1.0 op_sel_hi:[1,0]
	v_pk_add_f32 v[156:157], v[146:147], 1.0 op_sel_hi:[1,0]
	v_mov_b32_e32 v146, v126
	v_mov_b32_e32 v147, v157
	v_pk_mov_b32 v[158:159], v[126:127], v[156:157] op_sel:[1,0]
	v_pk_mul_f32 v[144:145], v[122:123], v[144:145] op_sel_hi:[1,0]
	v_pk_mul_f32 v[158:159], v[146:147], v[158:159]
	s_nop 0
	v_mul_f32_e32 v125, v158, v159
	v_rcp_f32_e32 v125, v125
	s_nop 0
	v_pk_mul_f32 v[146:147], v[120:121], v[124:125] op_sel:[1,0] op_sel_hi:[0,0]
	v_mul_f32_e32 v120, v159, v125
	v_mul_f32_e32 v122, v158, v125
	v_pk_mul_f32 v[124:125], v[156:157], v[122:123] op_sel_hi:[1,0]
	v_pk_mul_f32 v[126:127], v[126:127], v[120:121] op_sel:[1,0] op_sel_hi:[0,0]
; __device__ __forceinline__ unsigned cvt_pk_bf16(float lo, float hi) { unsigned r; asm volatile("v_cvt_pk_bf16_f32 %0, %1, %2" : "=v"(r) : "v"(lo), "v"(hi)); return r; }
; __device__ __forceinline__ float flogsig16(float x) { return (fminf(x, 0.f) - __logf(1.0f + __expf(-fabsf(x)))) * 0.0625f; }
; __device__ __forceinline__ f32x4 sigmoid4(f32x4 x) {
;     f32x4 d;
; #pragma unroll
;     for (int j = 0; j < 4; ++j) d[j] = 1.0f + __expf(-fmaxf(x[j], -20.0f));
;     const float p01 = d[0] * d[1], p23 = d[2] * d[3], r = __builtin_amdgcn_rcpf(p01 * p23), r01 = r * p23, r23 = r * p01;
;     return (f32x4){r01 * d[1], r01 * d[0], r23 * d[3], r23 * d[2]};
;     __device__ __forceinline__ void operator()(const f32x4 (&acc)[2][2][4][2], const Unit& u, int wr, int wc, int fr, int fq) const {
;     ...
;             for (int m = 0; m < 4; ++m) { bf16_t* rowp = O + (size_t)(row0 + ai * HALF + m * 16) * ldc + col0;
; #pragma unroll
;                 for (int bj = 0; bj < 2; ++bj) { f32x4 v0 = acc[ai][bj][m][0] + bv[bj][0], v1 = acc[ai][bj][m][1] + bv[bj][1];
;                     if (act == 1) {
; #pragma unroll
;                         for (int j = 0; j < 1; ++j) { v0 = v0 * sigmoid4(v0); v1 = v1 * sigmoid4(v1); } }
;                     else if (act == 2) {
; #pragma unroll
;                         for (int j = 0; j < 1; ++j) { v0 = sigmoid4(v0); v1 = sigmoid4(v1); } }
;                     else if (act == 3) {
; #pragma unroll
;                         for (int j = 0; j < 4; ++j) { v0[j] = flogsig16(v0[j]); v1[j] = flogsig16(v1[j]); } }
;                     u32x4 w; w.x = cvt_pk_bf16(v0[0], v0[1]); w.y = cvt_pk_bf16(v0[2], v0[3]); w.z = cvt_pk_bf16(v1[0], v1[1]); w.w = cvt_pk_bf16(v1[2], v1[3]);
;                     *(u32x4*)(rowp + bj * HALF) = w; } }
.LBB0_727:
	v_lshl_add_u32 v155, s16, 8, v148
	v_lshl_or_b32 v120, s4, 8, v150
	v_mov_b64_e32 v[122:123], s[0:1]
	v_ashrrev_i32_e32 v121, 31, v120
	v_mad_i64_i32 v[122:123], s[4:5], v155, s44, v[122:123]
	v_cvt_pk_bf16_f32 v156, v146, v147
	v_cvt_pk_bf16_f32 v157, v144, v145
	v_cvt_pk_bf16_f32 v158, v126, v127
	v_cvt_pk_bf16_f32 v159, v124, v125
	v_cndmask_b32_e64 v124, 0, 1, s[18:19]
	v_lshl_add_u64 v[122:123], v[120:121], 1, v[122:123]
	v_pk_add_f32 v[118:119], v[118:119], 0 op_sel_hi:[1,0]
	v_pk_add_f32 v[116:117], v[116:117], 0 op_sel_hi:[1,0]
	v_pk_add_f32 v[114:115], v[114:115], 0 op_sel_hi:[1,0]
	v_cmp_ne_u32_e64 s[4:5], 1, v124
	s_andn2_b64 vcc, exec, s[18:19]
	v_pk_add_f32 v[112:113], v[112:113], 0 op_sel_hi:[1,0]
	global_store_dwordx4 v[122:123], v[156:159], off
	s_cbranch_vccnz .LBB0_729
	v_max_f32_e32 v118, 0xc1a00000, v118
	v_mul_f32_e32 v118, 0xbfb8aa3b, v118
	v_exp_f32_e32 v125, v118
	v_max_f32_e32 v116, 0xc1a00000, v116
	v_max_f32_e32 v117, 0xc1a00000, v117
	v_max_f32_e32 v118, 0xc1a00000, v119
	v_mul_f32_e32 v116, 0xbfb8aa3b, v116
	v_mul_f32_e32 v117, 0xbfb8aa3b, v117
	v_mul_f32_e32 v118, 0xbfb8aa3b, v118
	v_exp_f32_e32 v116, v116
	v_exp_f32_e32 v117, v117
	v_exp_f32_e32 v124, v118
	v_max_f32_e32 v114, 0xc1a00000, v114
	v_pk_add_f32 v[116:117], v[116:117], 1.0 op_sel_hi:[1,0]
	v_pk_add_f32 v[118:119], v[124:125], 1.0 op_sel_hi:[1,0]
	v_mov_b32_e32 v124, v116
	v_mov_b32_e32 v125, v119
	v_pk_mov_b32 v[126:127], v[116:117], v[118:119] op_sel:[1,0]
	v_mul_f32_e32 v114, 0xbfb8aa3b, v114
	v_pk_mul_f32 v[124:125], v[124:125], v[126:127]
	v_exp_f32_e32 v127, v114
	v_max_f32_e32 v112, 0xc1a00000, v112
	v_max_f32_e32 v113, 0xc1a00000, v113
	v_max_f32_e32 v114, 0xc1a00000, v115
	v_mul_f32_e32 v126, v124, v125
	v_mul_f32_e32 v112, 0xbfb8aa3b, v112
	v_mul_f32_e32 v113, 0xbfb8aa3b, v113
	v_mul_f32_e32 v114, 0xbfb8aa3b, v114
	v_rcp_f32_e32 v156, v126
	v_exp_f32_e32 v112, v112
	v_exp_f32_e32 v113, v113
	v_exp_f32_e32 v126, v114
	v_mul_f32_e32 v114, v125, v156
	v_mul_f32_e32 v124, v124, v156
	v_pk_add_f32 v[112:113], v[112:113], 1.0 op_sel_hi:[1,0]
	v_pk_add_f32 v[126:127], v[126:127], 1.0 op_sel_hi:[1,0]
	v_mov_b32_e32 v144, v112
	v_mov_b32_e32 v145, v127
	v_pk_mov_b32 v[146:147], v[112:113], v[126:127] op_sel:[1,0]
	v_pk_mul_f32 v[118:119], v[118:119], v[124:125] op_sel_hi:[1,0]
	v_pk_mul_f32 v[144:145], v[144:145], v[146:147]
	s_nop 0
	v_mul_f32_e32 v115, v144, v145
	v_rcp_f32_e32 v115, v115
	s_nop 0
	v_pk_mul_f32 v[116:117], v[116:117], v[114:115] op_sel:[1,0] op_sel_hi:[0,0]
	v_mul_f32_e32 v124, v145, v115
	v_mul_f32_e32 v114, v144, v115
	v_pk_mul_f32 v[114:115], v[126:127], v[114:115] op_sel_hi:[1,0]
	v_pk_mul_f32 v[112:113], v[112:113], v[124:125] op_sel:[1,0] op_sel_hi:[0,0]
.LBB0_729:
	v_cvt_pk_bf16_f32 v116, v116, v117
	v_cvt_pk_bf16_f32 v117, v118, v119
	v_cvt_pk_bf16_f32 v118, v112, v113
	v_pk_add_f32 v[110:111], v[110:111], 0 op_sel_hi:[1,0]
	v_pk_add_f32 v[112:113], v[108:109], 0 op_sel_hi:[1,0]
	v_pk_add_f32 v[106:107], v[106:107], 0 op_sel_hi:[1,0]
	s_and_b64 vcc, exec, s[4:5]
	v_pk_add_f32 v[108:109], v[104:105], 0 op_sel_hi:[1,0]
	v_cvt_pk_bf16_f32 v119, v114, v115
	global_store_dwordx4 v[122:123], v[116:119], off offset:256
	s_cbranch_vccnz .LBB0_731
	v_max_f32_e32 v110, 0xc1a00000, v110
	v_mul_f32_e32 v110, 0xbfb8aa3b, v110
	v_max_f32_e32 v105, v113, v113
	v_exp_f32_e32 v113, v110
	v_max_f32_e32 v104, 0xc1a00000, v112
	v_max_f32_e32 v105, 0xc1a00000, v105
	v_max_f32_e32 v110, 0xc1a00000, v111
	v_mul_f32_e32 v104, 0xbfb8aa3b, v104
	v_mul_f32_e32 v105, 0xbfb8aa3b, v105
	v_mul_f32_e32 v110, 0xbfb8aa3b, v110
	v_exp_f32_e32 v104, v104
	v_exp_f32_e32 v105, v105
	v_exp_f32_e32 v112, v110
	v_max_f32_e32 v106, 0xc1a00000, v106
	v_pk_add_f32 v[104:105], v[104:105], 1.0 op_sel_hi:[1,0]
	v_pk_add_f32 v[110:111], v[112:113], 1.0 op_sel_hi:[1,0]
	v_mov_b32_e32 v112, v104
	v_mov_b32_e32 v113, v111
	v_pk_mov_b32 v[114:115], v[104:105], v[110:111] op_sel:[1,0]
	v_mul_f32_e32 v106, 0xbfb8aa3b, v106
	v_pk_mul_f32 v[112:113], v[112:113], v[114:115]
	v_exp_f32_e32 v115, v106
	v_max_f32_e32 v108, 0xc1a00000, v108
	v_max_f32_e32 v109, 0xc1a00000, v109
	v_max_f32_e32 v106, 0xc1a00000, v107
	v_mul_f32_e32 v114, v112, v113
	v_mul_f32_e32 v108, 0xbfb8aa3b, v108
	v_mul_f32_e32 v109, 0xbfb8aa3b, v109
	v_mul_f32_e32 v106, 0xbfb8aa3b, v106
	v_rcp_f32_e32 v122, v114
	v_exp_f32_e32 v108, v108
	v_exp_f32_e32 v109, v109
	v_exp_f32_e32 v114, v106
	v_mul_f32_e32 v106, v113, v122
	v_mul_f32_e32 v112, v112, v122
	v_pk_add_f32 v[108:109], v[108:109], 1.0 op_sel_hi:[1,0]
	v_pk_add_f32 v[114:115], v[114:115], 1.0 op_sel_hi:[1,0]
	v_mov_b32_e32 v116, v108
	v_mov_b32_e32 v117, v115
	v_pk_mov_b32 v[118:119], v[108:109], v[114:115] op_sel:[1,0]
	v_pk_mul_f32 v[110:111], v[110:111], v[112:113] op_sel_hi:[1,0]
	v_pk_mul_f32 v[116:117], v[116:117], v[118:119]
	s_nop 0
	v_mul_f32_e32 v107, v116, v117
	v_rcp_f32_e32 v107, v107
	s_nop 0
	v_pk_mul_f32 v[112:113], v[104:105], v[106:107] op_sel:[1,0] op_sel_hi:[0,0]
	v_mul_f32_e32 v104, v117, v107
	v_mul_f32_e32 v106, v116, v107
	v_pk_mul_f32 v[106:107], v[114:115], v[106:107] op_sel_hi:[1,0]
	v_pk_mul_f32 v[108:109], v[108:109], v[104:105] op_sel:[1,0] op_sel_hi:[0,0]
; __device__ __forceinline__ unsigned cvt_pk_bf16(float lo, float hi) { unsigned r; asm volatile("v_cvt_pk_bf16_f32 %0, %1, %2" : "=v"(r) : "v"(lo), "v"(hi)); return r; }
; __device__ __forceinline__ float flogsig16(float x) { return (fminf(x, 0.f) - __logf(1.0f + __expf(-fabsf(x)))) * 0.0625f; }
; __device__ __forceinline__ f32x4 sigmoid4(f32x4 x) {
;     f32x4 d;
; #pragma unroll
;     for (int j = 0; j < 4; ++j) d[j] = 1.0f + __expf(-fmaxf(x[j], -20.0f));
;     const float p01 = d[0] * d[1], p23 = d[2] * d[3], r = __builtin_amdgcn_rcpf(p01 * p23), r01 = r * p23, r23 = r * p01;
;     return (f32x4){r01 * d[1], r01 * d[0], r23 * d[3], r23 * d[2]};
;     __device__ __forceinline__ void operator()(const f32x4 (&acc)[2][2][4][2], const Unit& u, int wr, int wc, int fr, int fq) const {
;     ...
;             for (int m = 0; m < 4; ++m) { bf16_t* rowp = O + (size_t)(row0 + ai * HALF + m * 16) * ldc + col0;
; #pragma unroll
;                 for (int bj = 0; bj < 2; ++bj) { f32x4 v0 = acc[ai][bj][m][0] + bv[bj][0], v1 = acc[ai][bj][m][1] + bv[bj][1];
;                     if (act == 1) {
; #pragma unroll
;                         for (int j = 0; j < 1; ++j) { v0 = v0 * sigmoid4(v0); v1 = v1 * sigmoid4(v1); } }
;                     else if (act == 2) {
; #pragma unroll
;                         for (int j = 0; j < 1; ++j) { v0 = sigmoid4(v0); v1 = sigmoid4(v1); } }
;                     else if (act == 3) {
; #pragma unroll
;                         for (int j = 0; j < 4; ++j) { v0[j] = flogsig16(v0[j]); v1[j] = flogsig16(v1[j]); } }
;                     u32x4 w; w.x = cvt_pk_bf16(v0[0], v0[1]); w.y = cvt_pk_bf16(v0[2], v0[3]); w.z = cvt_pk_bf16(v1[0], v1[1]); w.w = cvt_pk_bf16(v1[2], v1[3]);
;                     *(u32x4*)(rowp + bj * HALF) = w; } }
.LBB0_731:
	v_or_b32_e32 v114, 16, v155
	v_mov_b64_e32 v[104:105], s[0:1]
	v_mad_i64_i32 v[104:105], s[18:19], v114, s44, v[104:105]
	v_lshl_add_u64 v[104:105], v[120:121], 1, v[104:105]
	v_pk_add_f32 v[102:103], v[102:103], 0 op_sel_hi:[1,0]
	v_pk_add_f32 v[100:101], v[100:101], 0 op_sel_hi:[1,0]
	v_pk_add_f32 v[98:99], v[98:99], 0 op_sel_hi:[1,0]
	s_and_b64 vcc, exec, s[4:5]
	v_pk_add_f32 v[96:97], v[96:97], 0 op_sel_hi:[1,0]
	v_cvt_pk_bf16_f32 v112, v112, v113
	v_cvt_pk_bf16_f32 v113, v110, v111
	v_cvt_pk_bf16_f32 v114, v108, v109
	v_cvt_pk_bf16_f32 v115, v106, v107
	global_store_dwordx4 v[104:105], v[112:115], off
	s_cbranch_vccnz .LBB0_733
	v_max_f32_e32 v102, 0xc1a00000, v102
	v_mul_f32_e32 v102, 0xbfb8aa3b, v102
	v_exp_f32_e32 v107, v102
	v_max_f32_e32 v100, 0xc1a00000, v100
	v_max_f32_e32 v101, 0xc1a00000, v101
	v_max_f32_e32 v102, 0xc1a00000, v103
	v_mul_f32_e32 v100, 0xbfb8aa3b, v100
	v_mul_f32_e32 v101, 0xbfb8aa3b, v101
	v_mul_f32_e32 v102, 0xbfb8aa3b, v102
	v_exp_f32_e32 v100, v100
	v_exp_f32_e32 v101, v101
	v_exp_f32_e32 v106, v102
	v_max_f32_e32 v98, 0xc1a00000, v98
	v_pk_add_f32 v[100:101], v[100:101], 1.0 op_sel_hi:[1,0]
	v_pk_add_f32 v[102:103], v[106:107], 1.0 op_sel_hi:[1,0]
	v_mov_b32_e32 v106, v100
	v_mov_b32_e32 v107, v103
	v_pk_mov_b32 v[108:109], v[100:101], v[102:103] op_sel:[1,0]
	v_mul_f32_e32 v98, 0xbfb8aa3b, v98
	v_pk_mul_f32 v[106:107], v[106:107], v[108:109]
	v_exp_f32_e32 v109, v98
	v_max_f32_e32 v96, 0xc1a00000, v96
	v_max_f32_e32 v97, 0xc1a00000, v97
	v_max_f32_e32 v98, 0xc1a00000, v99
	v_mul_f32_e32 v108, v106, v107
	v_mul_f32_e32 v96, 0xbfb8aa3b, v96
	v_mul_f32_e32 v97, 0xbfb8aa3b, v97
	v_mul_f32_e32 v98, 0xbfb8aa3b, v98
	v_rcp_f32_e32 v114, v108
	v_exp_f32_e32 v96, v96
	v_exp_f32_e32 v97, v97
	v_exp_f32_e32 v108, v98
	v_mul_f32_e32 v98, v107, v114
	v_mul_f32_e32 v106, v106, v114
	v_pk_add_f32 v[96:97], v[96:97], 1.0 op_sel_hi:[1,0]
	v_pk_add_f32 v[108:109], v[108:109], 1.0 op_sel_hi:[1,0]
	v_mov_b32_e32 v110, v96
	v_mov_b32_e32 v111, v109
	v_pk_mov_b32 v[112:113], v[96:97], v[108:109] op_sel:[1,0]
	v_pk_mul_f32 v[102:103], v[102:103], v[106:107] op_sel_hi:[1,0]
	v_pk_mul_f32 v[110:111], v[110:111], v[112:113]
	s_nop 0
	v_mul_f32_e32 v99, v110, v111
	v_rcp_f32_e32 v99, v99
	s_nop 0
	v_pk_mul_f32 v[100:101], v[100:101], v[98:99] op_sel:[1,0] op_sel_hi:[0,0]
	v_mul_f32_e32 v106, v111, v99
	v_mul_f32_e32 v98, v110, v99
	v_pk_mul_f32 v[98:99], v[108:109], v[98:99] op_sel_hi:[1,0]
	v_pk_mul_f32 v[96:97], v[96:97], v[106:107] op_sel:[1,0] op_sel_hi:[0,0]
.LBB0_733:
	v_cvt_pk_bf16_f32 v100, v100, v101
	v_cvt_pk_bf16_f32 v101, v102, v103
	v_cvt_pk_bf16_f32 v102, v96, v97
	v_pk_add_f32 v[94:95], v[94:95], 0 op_sel_hi:[1,0]
	v_pk_add_f32 v[96:97], v[92:93], 0 op_sel_hi:[1,0]
	v_pk_add_f32 v[90:91], v[90:91], 0 op_sel_hi:[1,0]
	s_and_b64 vcc, exec, s[4:5]
	v_pk_add_f32 v[92:93], v[88:89], 0 op_sel_hi:[1,0]
	v_cvt_pk_bf16_f32 v103, v98, v99
	global_store_dwordx4 v[104:105], v[100:103], off offset:256
	s_cbranch_vccnz .LBB0_735
	v_max_f32_e32 v94, 0xc1a00000, v94
	v_mul_f32_e32 v94, 0xbfb8aa3b, v94
	v_max_f32_e32 v89, v97, v97
	v_exp_f32_e32 v97, v94
	v_max_f32_e32 v88, 0xc1a00000, v96
	v_max_f32_e32 v89, 0xc1a00000, v89
	v_max_f32_e32 v94, 0xc1a00000, v95
	v_mul_f32_e32 v88, 0xbfb8aa3b, v88
	v_mul_f32_e32 v89, 0xbfb8aa3b, v89
	v_mul_f32_e32 v94, 0xbfb8aa3b, v94
	v_exp_f32_e32 v88, v88
	v_exp_f32_e32 v89, v89
	v_exp_f32_e32 v96, v94
	v_max_f32_e32 v90, 0xc1a00000, v90
	v_pk_add_f32 v[88:89], v[88:89], 1.0 op_sel_hi:[1,0]
	v_pk_add_f32 v[94:95], v[96:97], 1.0 op_sel_hi:[1,0]
	v_mov_b32_e32 v96, v88
	v_mov_b32_e32 v97, v95
	v_pk_mov_b32 v[98:99], v[88:89], v[94:95] op_sel:[1,0]
	v_mul_f32_e32 v90, 0xbfb8aa3b, v90
	v_pk_mul_f32 v[96:97], v[96:97], v[98:99]
	v_exp_f32_e32 v99, v90
	v_max_f32_e32 v92, 0xc1a00000, v92
	v_max_f32_e32 v93, 0xc1a00000, v93
	v_max_f32_e32 v90, 0xc1a00000, v91
	v_mul_f32_e32 v98, v96, v97
	v_mul_f32_e32 v92, 0xbfb8aa3b, v92
	v_mul_f32_e32 v93, 0xbfb8aa3b, v93
	v_mul_f32_e32 v90, 0xbfb8aa3b, v90
	v_rcp_f32_e32 v104, v98
	v_exp_f32_e32 v92, v92
	v_exp_f32_e32 v93, v93
	v_exp_f32_e32 v98, v90
	v_mul_f32_e32 v90, v97, v104
	v_mul_f32_e32 v96, v96, v104
	v_pk_add_f32 v[92:93], v[92:93], 1.0 op_sel_hi:[1,0]
	v_pk_add_f32 v[98:99], v[98:99], 1.0 op_sel_hi:[1,0]
	v_mov_b32_e32 v100, v92
	v_mov_b32_e32 v101, v99
	v_pk_mov_b32 v[102:103], v[92:93], v[98:99] op_sel:[1,0]
	v_pk_mul_f32 v[94:95], v[94:95], v[96:97] op_sel_hi:[1,0]
	v_pk_mul_f32 v[100:101], v[100:101], v[102:103]
	s_nop 0
	v_mul_f32_e32 v91, v100, v101
	v_rcp_f32_e32 v91, v91
	s_nop 0
	v_pk_mul_f32 v[96:97], v[88:89], v[90:91] op_sel:[1,0] op_sel_hi:[0,0]
	v_mul_f32_e32 v88, v101, v91
	v_mul_f32_e32 v90, v100, v91
	v_pk_mul_f32 v[90:91], v[98:99], v[90:91] op_sel_hi:[1,0]
	v_pk_mul_f32 v[92:93], v[92:93], v[88:89] op_sel:[1,0] op_sel_hi:[0,0]
; __device__ __forceinline__ unsigned cvt_pk_bf16(float lo, float hi) { unsigned r; asm volatile("v_cvt_pk_bf16_f32 %0, %1, %2" : "=v"(r) : "v"(lo), "v"(hi)); return r; }
; __device__ __forceinline__ float flogsig16(float x) { return (fminf(x, 0.f) - __logf(1.0f + __expf(-fabsf(x)))) * 0.0625f; }
; __device__ __forceinline__ f32x4 sigmoid4(f32x4 x) {
;     f32x4 d;
; #pragma unroll
;     for (int j = 0; j < 4; ++j) d[j] = 1.0f + __expf(-fmaxf(x[j], -20.0f));
;     const float p01 = d[0] * d[1], p23 = d[2] * d[3], r = __builtin_amdgcn_rcpf(p01 * p23), r01 = r * p23, r23 = r * p01;
;     return (f32x4){r01 * d[1], r01 * d[0], r23 * d[3], r23 * d[2]};
;     __device__ __forceinline__ void operator()(const f32x4 (&acc)[2][2][4][2], const Unit& u, int wr, int wc, int fr, int fq) const {
;     ...
;             for (int m = 0; m < 4; ++m) { bf16_t* rowp = O + (size_t)(row0 + ai * HALF + m * 16) * ldc + col0;
; #pragma unroll
;                 for (int bj = 0; bj < 2; ++bj) { f32x4 v0 = acc[ai][bj][m][0] + bv[bj][0], v1 = acc[ai][bj][m][1] + bv[bj][1];
;                     if (act == 1) {
; #pragma unroll
;                         for (int j = 0; j < 1; ++j) { v0 = v0 * sigmoid4(v0); v1 = v1 * sigmoid4(v1); } }
;                     else if (act == 2) {
; #pragma unroll
;                         for (int j = 0; j < 1; ++j) { v0 = sigmoid4(v0); v1 = sigmoid4(v1); } }
;                     else if (act == 3) {
; #pragma unroll
;                         for (int j = 0; j < 4; ++j) { v0[j] = flogsig16(v0[j]); v1[j] = flogsig16(v1[j]); } }
;                     u32x4 w; w.x = cvt_pk_bf16(v0[0], v0[1]); w.y = cvt_pk_bf16(v0[2], v0[3]); w.z = cvt_pk_bf16(v1[0], v1[1]); w.w = cvt_pk_bf16(v1[2], v1[3]);
;                     *(u32x4*)(rowp + bj * HALF) = w; } }
.LBB0_735:
	v_or_b32_e32 v98, 32, v155
	v_mov_b64_e32 v[88:89], s[0:1]
	v_mad_i64_i32 v[88:89], s[18:19], v98, s44, v[88:89]
	v_lshl_add_u64 v[88:89], v[120:121], 1, v[88:89]
	v_pk_add_f32 v[86:87], v[86:87], 0 op_sel_hi:[1,0]
	v_pk_add_f32 v[84:85], v[84:85], 0 op_sel_hi:[1,0]
	v_pk_add_f32 v[82:83], v[82:83], 0 op_sel_hi:[1,0]
	s_and_b64 vcc, exec, s[4:5]
	v_pk_add_f32 v[80:81], v[80:81], 0 op_sel_hi:[1,0]
	v_cvt_pk_bf16_f32 v96, v96, v97
	v_cvt_pk_bf16_f32 v97, v94, v95
	v_cvt_pk_bf16_f32 v98, v92, v93
	v_cvt_pk_bf16_f32 v99, v90, v91
	global_store_dwordx4 v[88:89], v[96:99], off
	s_cbranch_vccnz .LBB0_737
	v_max_f32_e32 v86, 0xc1a00000, v86
	v_mul_f32_e32 v86, 0xbfb8aa3b, v86
	v_exp_f32_e32 v91, v86
	v_max_f32_e32 v84, 0xc1a00000, v84
	v_max_f32_e32 v85, 0xc1a00000, v85
	v_max_f32_e32 v86, 0xc1a00000, v87
	v_mul_f32_e32 v84, 0xbfb8aa3b, v84
	v_mul_f32_e32 v85, 0xbfb8aa3b, v85
	v_mul_f32_e32 v86, 0xbfb8aa3b, v86
	v_exp_f32_e32 v84, v84
	v_exp_f32_e32 v85, v85
	v_exp_f32_e32 v90, v86
	v_max_f32_e32 v82, 0xc1a00000, v82
	v_pk_add_f32 v[84:85], v[84:85], 1.0 op_sel_hi:[1,0]
	v_pk_add_f32 v[86:87], v[90:91], 1.0 op_sel_hi:[1,0]
	v_mov_b32_e32 v90, v84
	v_mov_b32_e32 v91, v87
	v_pk_mov_b32 v[92:93], v[84:85], v[86:87] op_sel:[1,0]
	v_mul_f32_e32 v82, 0xbfb8aa3b, v82
	v_pk_mul_f32 v[90:91], v[90:91], v[92:93]
	v_exp_f32_e32 v93, v82
	v_max_f32_e32 v80, 0xc1a00000, v80
	v_max_f32_e32 v81, 0xc1a00000, v81
	v_max_f32_e32 v82, 0xc1a00000, v83
	v_mul_f32_e32 v92, v90, v91
	v_mul_f32_e32 v80, 0xbfb8aa3b, v80
	v_mul_f32_e32 v81, 0xbfb8aa3b, v81
	v_mul_f32_e32 v82, 0xbfb8aa3b, v82
	v_rcp_f32_e32 v98, v92
	v_exp_f32_e32 v80, v80
	v_exp_f32_e32 v81, v81
	v_exp_f32_e32 v92, v82
	v_mul_f32_e32 v82, v91, v98
	v_mul_f32_e32 v90, v90, v98
	v_pk_add_f32 v[80:81], v[80:81], 1.0 op_sel_hi:[1,0]
	v_pk_add_f32 v[92:93], v[92:93], 1.0 op_sel_hi:[1,0]
	v_mov_b32_e32 v94, v80
	v_mov_b32_e32 v95, v93
	v_pk_mov_b32 v[96:97], v[80:81], v[92:93] op_sel:[1,0]
	v_pk_mul_f32 v[86:87], v[86:87], v[90:91] op_sel_hi:[1,0]
	v_pk_mul_f32 v[94:95], v[94:95], v[96:97]
	s_nop 0
	v_mul_f32_e32 v83, v94, v95
	v_rcp_f32_e32 v83, v83
	s_nop 0
	v_pk_mul_f32 v[84:85], v[84:85], v[82:83] op_sel:[1,0] op_sel_hi:[0,0]
	v_mul_f32_e32 v90, v95, v83
	v_mul_f32_e32 v82, v94, v83
	v_pk_mul_f32 v[82:83], v[92:93], v[82:83] op_sel_hi:[1,0]
	v_pk_mul_f32 v[80:81], v[80:81], v[90:91] op_sel:[1,0] op_sel_hi:[0,0]
.LBB0_737:
	v_cvt_pk_bf16_f32 v84, v84, v85
	v_cvt_pk_bf16_f32 v85, v86, v87
	v_cvt_pk_bf16_f32 v86, v80, v81
	v_pk_add_f32 v[78:79], v[78:79], 0 op_sel_hi:[1,0]
	v_pk_add_f32 v[80:81], v[76:77], 0 op_sel_hi:[1,0]
	v_pk_add_f32 v[74:75], v[74:75], 0 op_sel_hi:[1,0]
	s_and_b64 vcc, exec, s[4:5]
	v_pk_add_f32 v[76:77], v[72:73], 0 op_sel_hi:[1,0]
	v_cvt_pk_bf16_f32 v87, v82, v83
	global_store_dwordx4 v[88:89], v[84:87], off offset:256
	s_cbranch_vccnz .LBB0_739
	v_max_f32_e32 v78, 0xc1a00000, v78
	v_mul_f32_e32 v78, 0xbfb8aa3b, v78
	v_max_f32_e32 v73, v81, v81
	v_exp_f32_e32 v81, v78
	v_max_f32_e32 v72, 0xc1a00000, v80
	v_max_f32_e32 v73, 0xc1a00000, v73
	v_max_f32_e32 v78, 0xc1a00000, v79
	v_mul_f32_e32 v72, 0xbfb8aa3b, v72
	v_mul_f32_e32 v73, 0xbfb8aa3b, v73
	v_mul_f32_e32 v78, 0xbfb8aa3b, v78
	v_exp_f32_e32 v72, v72
	v_exp_f32_e32 v73, v73
	v_exp_f32_e32 v80, v78
	v_max_f32_e32 v74, 0xc1a00000, v74
	v_pk_add_f32 v[72:73], v[72:73], 1.0 op_sel_hi:[1,0]
	v_pk_add_f32 v[78:79], v[80:81], 1.0 op_sel_hi:[1,0]
	v_mov_b32_e32 v80, v72
	v_mov_b32_e32 v81, v79
	v_pk_mov_b32 v[82:83], v[72:73], v[78:79] op_sel:[1,0]
	v_mul_f32_e32 v74, 0xbfb8aa3b, v74
	v_pk_mul_f32 v[80:81], v[80:81], v[82:83]
	v_exp_f32_e32 v83, v74
	v_max_f32_e32 v76, 0xc1a00000, v76
	v_max_f32_e32 v77, 0xc1a00000, v77
	v_max_f32_e32 v74, 0xc1a00000, v75
	v_mul_f32_e32 v82, v80, v81
	v_mul_f32_e32 v76, 0xbfb8aa3b, v76
	v_mul_f32_e32 v77, 0xbfb8aa3b, v77
	v_mul_f32_e32 v74, 0xbfb8aa3b, v74
	v_rcp_f32_e32 v88, v82
	v_exp_f32_e32 v76, v76
	v_exp_f32_e32 v77, v77
	v_exp_f32_e32 v82, v74
	v_mul_f32_e32 v74, v81, v88
	v_mul_f32_e32 v80, v80, v88
	v_pk_add_f32 v[76:77], v[76:77], 1.0 op_sel_hi:[1,0]
	v_pk_add_f32 v[82:83], v[82:83], 1.0 op_sel_hi:[1,0]
	v_mov_b32_e32 v84, v76
	v_mov_b32_e32 v85, v83
	v_pk_mov_b32 v[86:87], v[76:77], v[82:83] op_sel:[1,0]
	v_pk_mul_f32 v[78:79], v[78:79], v[80:81] op_sel_hi:[1,0]
	v_pk_mul_f32 v[84:85], v[84:85], v[86:87]
	s_nop 0
	v_mul_f32_e32 v75, v84, v85
	v_rcp_f32_e32 v75, v75
	s_nop 0
	v_pk_mul_f32 v[80:81], v[72:73], v[74:75] op_sel:[1,0] op_sel_hi:[0,0]
	v_mul_f32_e32 v72, v85, v75
	v_mul_f32_e32 v74, v84, v75
	v_pk_mul_f32 v[74:75], v[82:83], v[74:75] op_sel_hi:[1,0]
	v_pk_mul_f32 v[76:77], v[76:77], v[72:73] op_sel:[1,0] op_sel_hi:[0,0]
; __device__ __forceinline__ unsigned cvt_pk_bf16(float lo, float hi) { unsigned r; asm volatile("v_cvt_pk_bf16_f32 %0, %1, %2" : "=v"(r) : "v"(lo), "v"(hi)); return r; }
; __device__ __forceinline__ float flogsig16(float x) { return (fminf(x, 0.f) - __logf(1.0f + __expf(-fabsf(x)))) * 0.0625f; }
; __device__ __forceinline__ f32x4 sigmoid4(f32x4 x) {
;     f32x4 d;
; #pragma unroll
;     for (int j = 0; j < 4; ++j) d[j] = 1.0f + __expf(-fmaxf(x[j], -20.0f));
;     const float p01 = d[0] * d[1], p23 = d[2] * d[3], r = __builtin_amdgcn_rcpf(p01 * p23), r01 = r * p23, r23 = r * p01;
;     return (f32x4){r01 * d[1], r01 * d[0], r23 * d[3], r23 * d[2]};
;     __device__ __forceinline__ void operator()(const f32x4 (&acc)[2][2][4][2], const Unit& u, int wr, int wc, int fr, int fq) const {
;     ...
;             for (int m = 0; m < 4; ++m) { bf16_t* rowp = O + (size_t)(row0 + ai * HALF + m * 16) * ldc + col0;
; #pragma unroll
;                 for (int bj = 0; bj < 2; ++bj) { f32x4 v0 = acc[ai][bj][m][0] + bv[bj][0], v1 = acc[ai][bj][m][1] + bv[bj][1];
;                     if (act == 1) {
; #pragma unroll
;                         for (int j = 0; j < 1; ++j) { v0 = v0 * sigmoid4(v0); v1 = v1 * sigmoid4(v1); } }
;                     else if (act == 2) {
; #pragma unroll
;                         for (int j = 0; j < 1; ++j) { v0 = sigmoid4(v0); v1 = sigmoid4(v1); } }
;                     else if (act == 3) {
; #pragma unroll
;                         for (int j = 0; j < 4; ++j) { v0[j] = flogsig16(v0[j]); v1[j] = flogsig16(v1[j]); } }
;                     u32x4 w; w.x = cvt_pk_bf16(v0[0], v0[1]); w.y = cvt_pk_bf16(v0[2], v0[3]); w.z = cvt_pk_bf16(v1[0], v1[1]); w.w = cvt_pk_bf16(v1[2], v1[3]);
;                     *(u32x4*)(rowp + bj * HALF) = w; } }
.LBB0_739:
	v_or_b32_e32 v82, 48, v155
	v_mov_b64_e32 v[72:73], s[0:1]
	v_mad_i64_i32 v[72:73], s[18:19], v82, s44, v[72:73]
	v_lshl_add_u64 v[72:73], v[120:121], 1, v[72:73]
	v_pk_add_f32 v[70:71], v[70:71], 0 op_sel_hi:[1,0]
	v_pk_add_f32 v[68:69], v[68:69], 0 op_sel_hi:[1,0]
	v_pk_add_f32 v[66:67], v[66:67], 0 op_sel_hi:[1,0]
	s_and_b64 vcc, exec, s[4:5]
	v_pk_add_f32 v[64:65], v[64:65], 0 op_sel_hi:[1,0]
	v_cvt_pk_bf16_f32 v80, v80, v81
	v_cvt_pk_bf16_f32 v81, v78, v79
	v_cvt_pk_bf16_f32 v82, v76, v77
	v_cvt_pk_bf16_f32 v83, v74, v75
	global_store_dwordx4 v[72:73], v[80:83], off
	s_cbranch_vccnz .LBB0_741
	v_max_f32_e32 v70, 0xc1a00000, v70
	v_mul_f32_e32 v70, 0xbfb8aa3b, v70
	v_exp_f32_e32 v75, v70
	v_max_f32_e32 v68, 0xc1a00000, v68
	v_max_f32_e32 v69, 0xc1a00000, v69
	v_max_f32_e32 v70, 0xc1a00000, v71
	v_mul_f32_e32 v68, 0xbfb8aa3b, v68
	v_mul_f32_e32 v69, 0xbfb8aa3b, v69
	v_mul_f32_e32 v70, 0xbfb8aa3b, v70
	v_exp_f32_e32 v68, v68
	v_exp_f32_e32 v69, v69
	v_exp_f32_e32 v74, v70
	v_max_f32_e32 v66, 0xc1a00000, v66
	v_pk_add_f32 v[68:69], v[68:69], 1.0 op_sel_hi:[1,0]
	v_pk_add_f32 v[70:71], v[74:75], 1.0 op_sel_hi:[1,0]
	v_mov_b32_e32 v74, v68
	v_mov_b32_e32 v75, v71
	v_pk_mov_b32 v[76:77], v[68:69], v[70:71] op_sel:[1,0]
	v_mul_f32_e32 v66, 0xbfb8aa3b, v66
	v_pk_mul_f32 v[74:75], v[74:75], v[76:77]
	v_exp_f32_e32 v77, v66
	v_max_f32_e32 v64, 0xc1a00000, v64
	v_max_f32_e32 v65, 0xc1a00000, v65
	v_max_f32_e32 v66, 0xc1a00000, v67
	v_mul_f32_e32 v76, v74, v75
	v_mul_f32_e32 v64, 0xbfb8aa3b, v64
	v_mul_f32_e32 v65, 0xbfb8aa3b, v65
	v_mul_f32_e32 v66, 0xbfb8aa3b, v66
	v_rcp_f32_e32 v82, v76
	v_exp_f32_e32 v64, v64
	v_exp_f32_e32 v65, v65
	v_exp_f32_e32 v76, v66
	v_mul_f32_e32 v66, v75, v82
	v_mul_f32_e32 v74, v74, v82
	v_pk_add_f32 v[64:65], v[64:65], 1.0 op_sel_hi:[1,0]
	v_pk_add_f32 v[76:77], v[76:77], 1.0 op_sel_hi:[1,0]
	v_mov_b32_e32 v78, v64
	v_mov_b32_e32 v79, v77
	v_pk_mov_b32 v[80:81], v[64:65], v[76:77] op_sel:[1,0]
	v_pk_mul_f32 v[70:71], v[70:71], v[74:75] op_sel_hi:[1,0]
	v_pk_mul_f32 v[78:79], v[78:79], v[80:81]
	s_nop 0
	v_mul_f32_e32 v67, v78, v79
	v_rcp_f32_e32 v67, v67
	s_nop 0
	v_pk_mul_f32 v[68:69], v[68:69], v[66:67] op_sel:[1,0] op_sel_hi:[0,0]
	v_mul_f32_e32 v74, v79, v67
	v_mul_f32_e32 v66, v78, v67
	v_pk_mul_f32 v[66:67], v[76:77], v[66:67] op_sel_hi:[1,0]
	v_pk_mul_f32 v[64:65], v[64:65], v[74:75] op_sel:[1,0] op_sel_hi:[0,0]
.LBB0_741:
	v_cvt_pk_bf16_f32 v68, v68, v69
	v_cvt_pk_bf16_f32 v69, v70, v71
	v_cvt_pk_bf16_f32 v70, v64, v65
	v_pk_add_f32 v[62:63], v[62:63], 0 op_sel_hi:[1,0]
	v_pk_add_f32 v[64:65], v[60:61], 0 op_sel_hi:[1,0]
	v_pk_add_f32 v[58:59], v[58:59], 0 op_sel_hi:[1,0]
	s_and_b64 vcc, exec, s[4:5]
	v_pk_add_f32 v[60:61], v[56:57], 0 op_sel_hi:[1,0]
	v_cvt_pk_bf16_f32 v71, v66, v67
	global_store_dwordx4 v[72:73], v[68:71], off offset:256
	s_cbranch_vccnz .LBB0_743
	v_max_f32_e32 v62, 0xc1a00000, v62
	v_mul_f32_e32 v62, 0xbfb8aa3b, v62
	v_max_f32_e32 v57, v65, v65
	v_exp_f32_e32 v65, v62
	v_max_f32_e32 v56, 0xc1a00000, v64
	v_max_f32_e32 v57, 0xc1a00000, v57
	v_max_f32_e32 v62, 0xc1a00000, v63
	v_mul_f32_e32 v56, 0xbfb8aa3b, v56
	v_mul_f32_e32 v57, 0xbfb8aa3b, v57
	v_mul_f32_e32 v62, 0xbfb8aa3b, v62
	v_exp_f32_e32 v56, v56
	v_exp_f32_e32 v57, v57
	v_exp_f32_e32 v64, v62
	v_max_f32_e32 v58, 0xc1a00000, v58
	v_pk_add_f32 v[56:57], v[56:57], 1.0 op_sel_hi:[1,0]
	v_pk_add_f32 v[62:63], v[64:65], 1.0 op_sel_hi:[1,0]
	v_mov_b32_e32 v64, v56
	v_mov_b32_e32 v65, v63
	v_pk_mov_b32 v[66:67], v[56:57], v[62:63] op_sel:[1,0]
	v_mul_f32_e32 v58, 0xbfb8aa3b, v58
	v_pk_mul_f32 v[64:65], v[64:65], v[66:67]
	v_exp_f32_e32 v67, v58
	v_max_f32_e32 v60, 0xc1a00000, v60
	v_max_f32_e32 v61, 0xc1a00000, v61
	v_max_f32_e32 v58, 0xc1a00000, v59
	v_mul_f32_e32 v66, v64, v65
	v_mul_f32_e32 v60, 0xbfb8aa3b, v60
	v_mul_f32_e32 v61, 0xbfb8aa3b, v61
	v_mul_f32_e32 v58, 0xbfb8aa3b, v58
	v_rcp_f32_e32 v72, v66
	v_exp_f32_e32 v60, v60
	v_exp_f32_e32 v61, v61
	v_exp_f32_e32 v66, v58
	v_mul_f32_e32 v58, v65, v72
	v_mul_f32_e32 v64, v64, v72
	v_pk_add_f32 v[60:61], v[60:61], 1.0 op_sel_hi:[1,0]
	v_pk_add_f32 v[66:67], v[66:67], 1.0 op_sel_hi:[1,0]
	v_mov_b32_e32 v68, v60
	v_mov_b32_e32 v69, v67
	v_pk_mov_b32 v[70:71], v[60:61], v[66:67] op_sel:[1,0]
	v_pk_mul_f32 v[62:63], v[62:63], v[64:65] op_sel_hi:[1,0]
	v_pk_mul_f32 v[68:69], v[68:69], v[70:71]
	s_nop 0
	v_mul_f32_e32 v59, v68, v69
	v_rcp_f32_e32 v59, v59
	s_nop 0
	v_pk_mul_f32 v[64:65], v[56:57], v[58:59] op_sel:[1,0] op_sel_hi:[0,0]
	v_mul_f32_e32 v56, v69, v59
	v_mul_f32_e32 v58, v68, v59
	v_pk_mul_f32 v[58:59], v[66:67], v[58:59] op_sel_hi:[1,0]
	v_pk_mul_f32 v[60:61], v[60:61], v[56:57] op_sel:[1,0] op_sel_hi:[0,0]
; __device__ __forceinline__ unsigned cvt_pk_bf16(float lo, float hi) { unsigned r; asm volatile("v_cvt_pk_bf16_f32 %0, %1, %2" : "=v"(r) : "v"(lo), "v"(hi)); return r; }
; __device__ __forceinline__ float flogsig16(float x) { return (fminf(x, 0.f) - __logf(1.0f + __expf(-fabsf(x)))) * 0.0625f; }
; __device__ __forceinline__ f32x4 sigmoid4(f32x4 x) {
;     f32x4 d;
; #pragma unroll
;     for (int j = 0; j < 4; ++j) d[j] = 1.0f + __expf(-fmaxf(x[j], -20.0f));
;     const float p01 = d[0] * d[1], p23 = d[2] * d[3], r = __builtin_amdgcn_rcpf(p01 * p23), r01 = r * p23, r23 = r * p01;
;     return (f32x4){r01 * d[1], r01 * d[0], r23 * d[3], r23 * d[2]};
;     __device__ __forceinline__ void operator()(const f32x4 (&acc)[2][2][4][2], const Unit& u, int wr, int wc, int fr, int fq) const {
;     ...
;             for (int m = 0; m < 4; ++m) { bf16_t* rowp = O + (size_t)(row0 + ai * HALF + m * 16) * ldc + col0;
; #pragma unroll
;                 for (int bj = 0; bj < 2; ++bj) { f32x4 v0 = acc[ai][bj][m][0] + bv[bj][0], v1 = acc[ai][bj][m][1] + bv[bj][1];
;                     if (act == 1) {
; #pragma unroll
;                         for (int j = 0; j < 1; ++j) { v0 = v0 * sigmoid4(v0); v1 = v1 * sigmoid4(v1); } }
;                     else if (act == 2) {
; #pragma unroll
;                         for (int j = 0; j < 1; ++j) { v0 = sigmoid4(v0); v1 = sigmoid4(v1); } }
;                     else if (act == 3) {
; #pragma unroll
;                         for (int j = 0; j < 4; ++j) { v0[j] = flogsig16(v0[j]); v1[j] = flogsig16(v1[j]); } }
;                     u32x4 w; w.x = cvt_pk_bf16(v0[0], v0[1]); w.y = cvt_pk_bf16(v0[2], v0[3]); w.z = cvt_pk_bf16(v1[0], v1[1]); w.w = cvt_pk_bf16(v1[2], v1[3]);
;                     *(u32x4*)(rowp + bj * HALF) = w; } }
.LBB0_743:
	v_add_u32_e32 v66, 0x80, v155
	v_mov_b64_e32 v[56:57], s[0:1]
	v_mad_i64_i32 v[56:57], s[18:19], v66, s44, v[56:57]
	v_lshl_add_u64 v[56:57], v[120:121], 1, v[56:57]
	v_pk_add_f32 v[54:55], v[54:55], 0 op_sel_hi:[1,0]
	v_pk_add_f32 v[52:53], v[52:53], 0 op_sel_hi:[1,0]
	v_pk_add_f32 v[50:51], v[50:51], 0 op_sel_hi:[1,0]
	s_and_b64 vcc, exec, s[4:5]
	v_pk_add_f32 v[48:49], v[48:49], 0 op_sel_hi:[1,0]
	v_cvt_pk_bf16_f32 v64, v64, v65
	v_cvt_pk_bf16_f32 v65, v62, v63
	v_cvt_pk_bf16_f32 v66, v60, v61
	v_cvt_pk_bf16_f32 v67, v58, v59
	global_store_dwordx4 v[56:57], v[64:67], off
	s_cbranch_vccnz .LBB0_745
	v_max_f32_e32 v54, 0xc1a00000, v54
	v_mul_f32_e32 v54, 0xbfb8aa3b, v54
	v_exp_f32_e32 v59, v54
	v_max_f32_e32 v52, 0xc1a00000, v52
	v_max_f32_e32 v53, 0xc1a00000, v53
	v_max_f32_e32 v54, 0xc1a00000, v55
	v_mul_f32_e32 v52, 0xbfb8aa3b, v52
	v_mul_f32_e32 v53, 0xbfb8aa3b, v53
	v_mul_f32_e32 v54, 0xbfb8aa3b, v54
	v_exp_f32_e32 v52, v52
	v_exp_f32_e32 v53, v53
	v_exp_f32_e32 v58, v54
	v_max_f32_e32 v50, 0xc1a00000, v50
	v_pk_add_f32 v[52:53], v[52:53], 1.0 op_sel_hi:[1,0]
	v_pk_add_f32 v[54:55], v[58:59], 1.0 op_sel_hi:[1,0]
	v_mov_b32_e32 v58, v52
	v_mov_b32_e32 v59, v55
	v_pk_mov_b32 v[60:61], v[52:53], v[54:55] op_sel:[1,0]
	v_mul_f32_e32 v50, 0xbfb8aa3b, v50
	v_pk_mul_f32 v[58:59], v[58:59], v[60:61]
	v_exp_f32_e32 v61, v50
	v_max_f32_e32 v48, 0xc1a00000, v48
	v_max_f32_e32 v49, 0xc1a00000, v49
	v_max_f32_e32 v50, 0xc1a00000, v51
	v_mul_f32_e32 v60, v58, v59
	v_mul_f32_e32 v48, 0xbfb8aa3b, v48
	v_mul_f32_e32 v49, 0xbfb8aa3b, v49
	v_mul_f32_e32 v50, 0xbfb8aa3b, v50
	v_rcp_f32_e32 v66, v60
	v_exp_f32_e32 v48, v48
	v_exp_f32_e32 v49, v49
	v_exp_f32_e32 v60, v50
	v_mul_f32_e32 v50, v59, v66
	v_mul_f32_e32 v58, v58, v66
	v_pk_add_f32 v[48:49], v[48:49], 1.0 op_sel_hi:[1,0]
	v_pk_add_f32 v[60:61], v[60:61], 1.0 op_sel_hi:[1,0]
	v_mov_b32_e32 v62, v48
	v_mov_b32_e32 v63, v61
	v_pk_mov_b32 v[64:65], v[48:49], v[60:61] op_sel:[1,0]
	v_pk_mul_f32 v[54:55], v[54:55], v[58:59] op_sel_hi:[1,0]
	v_pk_mul_f32 v[62:63], v[62:63], v[64:65]
	s_nop 0
	v_mul_f32_e32 v51, v62, v63
	v_rcp_f32_e32 v51, v51
	s_nop 0
	v_pk_mul_f32 v[52:53], v[52:53], v[50:51] op_sel:[1,0] op_sel_hi:[0,0]
	v_mul_f32_e32 v58, v63, v51
	v_mul_f32_e32 v50, v62, v51
	v_pk_mul_f32 v[50:51], v[60:61], v[50:51] op_sel_hi:[1,0]
	v_pk_mul_f32 v[48:49], v[48:49], v[58:59] op_sel:[1,0] op_sel_hi:[0,0]
.LBB0_745:
	v_cvt_pk_bf16_f32 v52, v52, v53
	v_cvt_pk_bf16_f32 v53, v54, v55
	v_cvt_pk_bf16_f32 v54, v48, v49
	v_pk_add_f32 v[46:47], v[46:47], 0 op_sel_hi:[1,0]
	v_pk_add_f32 v[48:49], v[44:45], 0 op_sel_hi:[1,0]
	v_pk_add_f32 v[42:43], v[42:43], 0 op_sel_hi:[1,0]
	s_and_b64 vcc, exec, s[4:5]
	v_pk_add_f32 v[44:45], v[40:41], 0 op_sel_hi:[1,0]
	v_cvt_pk_bf16_f32 v55, v50, v51
	global_store_dwordx4 v[56:57], v[52:55], off offset:256
	s_cbranch_vccnz .LBB0_747
	v_max_f32_e32 v46, 0xc1a00000, v46
	v_mul_f32_e32 v46, 0xbfb8aa3b, v46
	v_max_f32_e32 v41, v49, v49
	v_exp_f32_e32 v49, v46
	v_max_f32_e32 v40, 0xc1a00000, v48
	v_max_f32_e32 v41, 0xc1a00000, v41
	v_max_f32_e32 v46, 0xc1a00000, v47
	v_mul_f32_e32 v40, 0xbfb8aa3b, v40
	v_mul_f32_e32 v41, 0xbfb8aa3b, v41
	v_mul_f32_e32 v46, 0xbfb8aa3b, v46
	v_exp_f32_e32 v40, v40
	v_exp_f32_e32 v41, v41
	v_exp_f32_e32 v48, v46
	v_max_f32_e32 v42, 0xc1a00000, v42
	v_pk_add_f32 v[40:41], v[40:41], 1.0 op_sel_hi:[1,0]
	v_pk_add_f32 v[46:47], v[48:49], 1.0 op_sel_hi:[1,0]
	v_mov_b32_e32 v48, v40
	v_mov_b32_e32 v49, v47
	v_pk_mov_b32 v[50:51], v[40:41], v[46:47] op_sel:[1,0]
	v_mul_f32_e32 v42, 0xbfb8aa3b, v42
	v_pk_mul_f32 v[48:49], v[48:49], v[50:51]
	v_exp_f32_e32 v51, v42
	v_max_f32_e32 v44, 0xc1a00000, v44
	v_max_f32_e32 v45, 0xc1a00000, v45
	v_max_f32_e32 v42, 0xc1a00000, v43
	v_mul_f32_e32 v50, v48, v49
	v_mul_f32_e32 v44, 0xbfb8aa3b, v44
	v_mul_f32_e32 v45, 0xbfb8aa3b, v45
	v_mul_f32_e32 v42, 0xbfb8aa3b, v42
	v_rcp_f32_e32 v56, v50
	v_exp_f32_e32 v44, v44
	v_exp_f32_e32 v45, v45
	v_exp_f32_e32 v50, v42
	v_mul_f32_e32 v42, v49, v56
	v_mul_f32_e32 v48, v48, v56
	v_pk_add_f32 v[44:45], v[44:45], 1.0 op_sel_hi:[1,0]
	v_pk_add_f32 v[50:51], v[50:51], 1.0 op_sel_hi:[1,0]
	v_mov_b32_e32 v52, v44
	v_mov_b32_e32 v53, v51
	v_pk_mov_b32 v[54:55], v[44:45], v[50:51] op_sel:[1,0]
	v_pk_mul_f32 v[46:47], v[46:47], v[48:49] op_sel_hi:[1,0]
	v_pk_mul_f32 v[52:53], v[52:53], v[54:55]
	s_nop 0
	v_mul_f32_e32 v43, v52, v53
	v_rcp_f32_e32 v43, v43
	s_nop 0
	v_pk_mul_f32 v[48:49], v[40:41], v[42:43] op_sel:[1,0] op_sel_hi:[0,0]
	v_mul_f32_e32 v40, v53, v43
	v_mul_f32_e32 v42, v52, v43
	v_pk_mul_f32 v[42:43], v[50:51], v[42:43] op_sel_hi:[1,0]
	v_pk_mul_f32 v[44:45], v[44:45], v[40:41] op_sel:[1,0] op_sel_hi:[0,0]
; __device__ __forceinline__ unsigned cvt_pk_bf16(float lo, float hi) { unsigned r; asm volatile("v_cvt_pk_bf16_f32 %0, %1, %2" : "=v"(r) : "v"(lo), "v"(hi)); return r; }
; __device__ __forceinline__ float flogsig16(float x) { return (fminf(x, 0.f) - __logf(1.0f + __expf(-fabsf(x)))) * 0.0625f; }
; __device__ __forceinline__ f32x4 sigmoid4(f32x4 x) {
;     f32x4 d;
; #pragma unroll
;     for (int j = 0; j < 4; ++j) d[j] = 1.0f + __expf(-fmaxf(x[j], -20.0f));
;     const float p01 = d[0] * d[1], p23 = d[2] * d[3], r = __builtin_amdgcn_rcpf(p01 * p23), r01 = r * p23, r23 = r * p01;
;     return (f32x4){r01 * d[1], r01 * d[0], r23 * d[3], r23 * d[2]};
; }
;     __device__ __forceinline__ void operator()(const f32x4 (&acc)[2][2][4][2], const Unit& u, int wr, int wc, int fr, int fq) const {
;     ...
;             for (int m = 0; m < 4; ++m) { bf16_t* rowp = O + (size_t)(row0 + ai * HALF + m * 16) * ldc + col0;
; #pragma unroll
;                 for (int bj = 0; bj < 2; ++bj) { f32x4 v0 = acc[ai][bj][m][0] + bv[bj][0], v1 = acc[ai][bj][m][1] + bv[bj][1];
;                     if (act == 1) {
; #pragma unroll
;                         for (int j = 0; j < 1; ++j) { v0 = v0 * sigmoid4(v0); v1 = v1 * sigmoid4(v1); } }
;                     else if (act == 2) {
; #pragma unroll
;                         for (int j = 0; j < 1; ++j) { v0 = sigmoid4(v0); v1 = sigmoid4(v1); } }
;                     else if (act == 3) {
; #pragma unroll
;                         for (int j = 0; j < 4; ++j) { v0[j] = flogsig16(v0[j]); v1[j] = flogsig16(v1[j]); } }
;                     u32x4 w; w.x = cvt_pk_bf16(v0[0], v0[1]); w.y = cvt_pk_bf16(v0[2], v0[3]); w.z = cvt_pk_bf16(v1[0], v1[1]); w.w = cvt_pk_bf16(v1[2], v1[3]);
;                     *(u32x4*)(rowp + bj * HALF) = w; } }
.LBB0_747:
	v_add_u32_e32 v50, 0x90, v155
	v_mov_b64_e32 v[40:41], s[0:1]
	v_mad_i64_i32 v[40:41], s[18:19], v50, s44, v[40:41]
	v_lshl_add_u64 v[40:41], v[120:121], 1, v[40:41]
	v_pk_add_f32 v[38:39], v[38:39], 0 op_sel_hi:[1,0]
	v_pk_add_f32 v[36:37], v[36:37], 0 op_sel_hi:[1,0]
	v_pk_add_f32 v[34:35], v[34:35], 0 op_sel_hi:[1,0]
	s_and_b64 vcc, exec, s[4:5]
	v_pk_add_f32 v[32:33], v[32:33], 0 op_sel_hi:[1,0]
	v_cvt_pk_bf16_f32 v48, v48, v49
	v_cvt_pk_bf16_f32 v49, v46, v47
	v_cvt_pk_bf16_f32 v50, v44, v45
	v_cvt_pk_bf16_f32 v51, v42, v43
	global_store_dwordx4 v[40:41], v[48:51], off
	s_cbranch_vccnz .LBB0_749
	v_max_f32_e32 v38, 0xc1a00000, v38
	v_mul_f32_e32 v38, 0xbfb8aa3b, v38
	v_exp_f32_e32 v43, v38
	v_max_f32_e32 v36, 0xc1a00000, v36
	v_max_f32_e32 v37, 0xc1a00000, v37
	v_max_f32_e32 v38, 0xc1a00000, v39
	v_mul_f32_e32 v36, 0xbfb8aa3b, v36
	v_mul_f32_e32 v37, 0xbfb8aa3b, v37
	v_mul_f32_e32 v38, 0xbfb8aa3b, v38
	v_exp_f32_e32 v36, v36
	v_exp_f32_e32 v37, v37
	v_exp_f32_e32 v42, v38
	v_max_f32_e32 v34, 0xc1a00000, v34
	v_pk_add_f32 v[36:37], v[36:37], 1.0 op_sel_hi:[1,0]
	v_pk_add_f32 v[38:39], v[42:43], 1.0 op_sel_hi:[1,0]
	v_mov_b32_e32 v42, v36
	v_mov_b32_e32 v43, v39
	v_pk_mov_b32 v[44:45], v[36:37], v[38:39] op_sel:[1,0]
	v_mul_f32_e32 v34, 0xbfb8aa3b, v34
	v_pk_mul_f32 v[42:43], v[42:43], v[44:45]
	v_exp_f32_e32 v45, v34
	v_max_f32_e32 v32, 0xc1a00000, v32
	v_max_f32_e32 v33, 0xc1a00000, v33
	v_max_f32_e32 v34, 0xc1a00000, v35
	v_mul_f32_e32 v44, v42, v43
	v_mul_f32_e32 v32, 0xbfb8aa3b, v32
	v_mul_f32_e32 v33, 0xbfb8aa3b, v33
	v_mul_f32_e32 v34, 0xbfb8aa3b, v34
	v_rcp_f32_e32 v50, v44
	v_exp_f32_e32 v32, v32
	v_exp_f32_e32 v33, v33
	v_exp_f32_e32 v44, v34
	v_mul_f32_e32 v34, v43, v50
	v_mul_f32_e32 v42, v42, v50
	v_pk_add_f32 v[32:33], v[32:33], 1.0 op_sel_hi:[1,0]
	v_pk_add_f32 v[44:45], v[44:45], 1.0 op_sel_hi:[1,0]
	v_mov_b32_e32 v46, v32
	v_mov_b32_e32 v47, v45
	v_pk_mov_b32 v[48:49], v[32:33], v[44:45] op_sel:[1,0]
	v_pk_mul_f32 v[38:39], v[38:39], v[42:43] op_sel_hi:[1,0]
	v_pk_mul_f32 v[46:47], v[46:47], v[48:49]
	s_nop 0
	v_mul_f32_e32 v35, v46, v47
	v_rcp_f32_e32 v35, v35
	s_nop 0
	v_pk_mul_f32 v[36:37], v[36:37], v[34:35] op_sel:[1,0] op_sel_hi:[0,0]
	v_mul_f32_e32 v42, v47, v35
	v_mul_f32_e32 v34, v46, v35
	v_pk_mul_f32 v[34:35], v[44:45], v[34:35] op_sel_hi:[1,0]
	v_pk_mul_f32 v[32:33], v[32:33], v[42:43] op_sel:[1,0] op_sel_hi:[0,0]
.LBB0_749:
	v_cvt_pk_bf16_f32 v36, v36, v37
	v_cvt_pk_bf16_f32 v37, v38, v39
	v_cvt_pk_bf16_f32 v38, v32, v33
	v_pk_add_f32 v[30:31], v[30:31], 0 op_sel_hi:[1,0]
	v_pk_add_f32 v[32:33], v[28:29], 0 op_sel_hi:[1,0]
	v_pk_add_f32 v[26:27], v[26:27], 0 op_sel_hi:[1,0]
	s_and_b64 vcc, exec, s[4:5]
	v_pk_add_f32 v[28:29], v[24:25], 0 op_sel_hi:[1,0]
	v_cvt_pk_bf16_f32 v39, v34, v35
	global_store_dwordx4 v[40:41], v[36:39], off offset:256
	s_cbranch_vccnz .LBB0_751
	v_max_f32_e32 v30, 0xc1a00000, v30
	v_mul_f32_e32 v30, 0xbfb8aa3b, v30
	v_max_f32_e32 v25, v33, v33
	v_exp_f32_e32 v33, v30
	v_max_f32_e32 v24, 0xc1a00000, v32
	v_max_f32_e32 v25, 0xc1a00000, v25
	v_max_f32_e32 v30, 0xc1a00000, v31
	v_mul_f32_e32 v24, 0xbfb8aa3b, v24
	v_mul_f32_e32 v25, 0xbfb8aa3b, v25
	v_mul_f32_e32 v30, 0xbfb8aa3b, v30
	v_exp_f32_e32 v24, v24
	v_exp_f32_e32 v25, v25
	v_exp_f32_e32 v32, v30
	v_max_f32_e32 v26, 0xc1a00000, v26
	v_pk_add_f32 v[24:25], v[24:25], 1.0 op_sel_hi:[1,0]
	v_pk_add_f32 v[30:31], v[32:33], 1.0 op_sel_hi:[1,0]
	v_mov_b32_e32 v32, v24
	v_mov_b32_e32 v33, v31
	v_pk_mov_b32 v[34:35], v[24:25], v[30:31] op_sel:[1,0]
	v_mul_f32_e32 v26, 0xbfb8aa3b, v26
	v_pk_mul_f32 v[32:33], v[32:33], v[34:35]
	v_exp_f32_e32 v35, v26
	v_max_f32_e32 v28, 0xc1a00000, v28
	v_max_f32_e32 v29, 0xc1a00000, v29
	v_max_f32_e32 v26, 0xc1a00000, v27
	v_mul_f32_e32 v34, v32, v33
	v_mul_f32_e32 v28, 0xbfb8aa3b, v28
	v_mul_f32_e32 v29, 0xbfb8aa3b, v29
	v_mul_f32_e32 v26, 0xbfb8aa3b, v26
	v_rcp_f32_e32 v40, v34
	v_exp_f32_e32 v28, v28
	v_exp_f32_e32 v29, v29
	v_exp_f32_e32 v34, v26
	v_mul_f32_e32 v26, v33, v40
	v_mul_f32_e32 v32, v32, v40
	v_pk_add_f32 v[28:29], v[28:29], 1.0 op_sel_hi:[1,0]
	v_pk_add_f32 v[34:35], v[34:35], 1.0 op_sel_hi:[1,0]
	v_mov_b32_e32 v36, v28
	v_mov_b32_e32 v37, v35
	v_pk_mov_b32 v[38:39], v[28:29], v[34:35] op_sel:[1,0]
	v_pk_mul_f32 v[30:31], v[30:31], v[32:33] op_sel_hi:[1,0]
	v_pk_mul_f32 v[36:37], v[36:37], v[38:39]
	s_nop 0
	v_mul_f32_e32 v27, v36, v37
	v_rcp_f32_e32 v27, v27
	s_nop 0
	v_pk_mul_f32 v[32:33], v[24:25], v[26:27] op_sel:[1,0] op_sel_hi:[0,0]
	v_mul_f32_e32 v24, v37, v27
	v_mul_f32_e32 v26, v36, v27
	v_pk_mul_f32 v[26:27], v[34:35], v[26:27] op_sel_hi:[1,0]
	v_pk_mul_f32 v[28:29], v[28:29], v[24:25] op_sel:[1,0] op_sel_hi:[0,0]
; __device__ __forceinline__ unsigned cvt_pk_bf16(float lo, float hi) { unsigned r; asm volatile("v_cvt_pk_bf16_f32 %0, %1, %2" : "=v"(r) : "v"(lo), "v"(hi)); return r; }
; __device__ __forceinline__ float flogsig16(float x) { return (fminf(x, 0.f) - __logf(1.0f + __expf(-fabsf(x)))) * 0.0625f; }
; __device__ __forceinline__ f32x4 sigmoid4(f32x4 x) {
;     f32x4 d;
; #pragma unroll
;     for (int j = 0; j < 4; ++j) d[j] = 1.0f + __expf(-fmaxf(x[j], -20.0f));
;     const float p01 = d[0] * d[1], p23 = d[2] * d[3], r = __builtin_amdgcn_rcpf(p01 * p23), r01 = r * p23, r23 = r * p01;
;     return (f32x4){r01 * d[1], r01 * d[0], r23 * d[3], r23 * d[2]};
; }
;     __device__ __forceinline__ void operator()(const f32x4 (&acc)[2][2][4][2], const Unit& u, int wr, int wc, int fr, int fq) const {
;     ...
;             for (int m = 0; m < 4; ++m) { bf16_t* rowp = O + (size_t)(row0 + ai * HALF + m * 16) * ldc + col0;
; #pragma unroll
;                 for (int bj = 0; bj < 2; ++bj) { f32x4 v0 = acc[ai][bj][m][0] + bv[bj][0], v1 = acc[ai][bj][m][1] + bv[bj][1];
;                     if (act == 1) {
; #pragma unroll
;                         for (int j = 0; j < 1; ++j) { v0 = v0 * sigmoid4(v0); v1 = v1 * sigmoid4(v1); } }
;                     else if (act == 2) {
; #pragma unroll
;                         for (int j = 0; j < 1; ++j) { v0 = sigmoid4(v0); v1 = sigmoid4(v1); } }
;                     else if (act == 3) {
; #pragma unroll
;                         for (int j = 0; j < 4; ++j) { v0[j] = flogsig16(v0[j]); v1[j] = flogsig16(v1[j]); } }
;                     u32x4 w; w.x = cvt_pk_bf16(v0[0], v0[1]); w.y = cvt_pk_bf16(v0[2], v0[3]); w.z = cvt_pk_bf16(v1[0], v1[1]); w.w = cvt_pk_bf16(v1[2], v1[3]);
;                     *(u32x4*)(rowp + bj * HALF) = w; } }
.LBB0_751:
	v_add_u32_e32 v34, 0xa0, v155
	v_mov_b64_e32 v[24:25], s[0:1]
	v_mad_i64_i32 v[24:25], s[18:19], v34, s44, v[24:25]
	v_lshl_add_u64 v[24:25], v[120:121], 1, v[24:25]
	v_pk_add_f32 v[22:23], v[22:23], 0 op_sel_hi:[1,0]
	v_pk_add_f32 v[20:21], v[20:21], 0 op_sel_hi:[1,0]
	v_pk_add_f32 v[18:19], v[18:19], 0 op_sel_hi:[1,0]
	s_and_b64 vcc, exec, s[4:5]
	v_pk_add_f32 v[16:17], v[16:17], 0 op_sel_hi:[1,0]
	v_cvt_pk_bf16_f32 v32, v32, v33
	v_cvt_pk_bf16_f32 v33, v30, v31
	v_cvt_pk_bf16_f32 v34, v28, v29
	v_cvt_pk_bf16_f32 v35, v26, v27
	global_store_dwordx4 v[24:25], v[32:35], off
	s_cbranch_vccnz .LBB0_753
	v_max_f32_e32 v22, 0xc1a00000, v22
	v_mul_f32_e32 v22, 0xbfb8aa3b, v22
	v_exp_f32_e32 v27, v22
	v_max_f32_e32 v20, 0xc1a00000, v20
	v_max_f32_e32 v21, 0xc1a00000, v21
	v_max_f32_e32 v22, 0xc1a00000, v23
	v_mul_f32_e32 v20, 0xbfb8aa3b, v20
	v_mul_f32_e32 v21, 0xbfb8aa3b, v21
	v_mul_f32_e32 v22, 0xbfb8aa3b, v22
	v_exp_f32_e32 v20, v20
	v_exp_f32_e32 v21, v21
	v_exp_f32_e32 v26, v22
	v_max_f32_e32 v18, 0xc1a00000, v18
	v_pk_add_f32 v[20:21], v[20:21], 1.0 op_sel_hi:[1,0]
	v_pk_add_f32 v[22:23], v[26:27], 1.0 op_sel_hi:[1,0]
	v_mov_b32_e32 v26, v20
	v_mov_b32_e32 v27, v23
	v_pk_mov_b32 v[28:29], v[20:21], v[22:23] op_sel:[1,0]
	v_mul_f32_e32 v18, 0xbfb8aa3b, v18
	v_pk_mul_f32 v[26:27], v[26:27], v[28:29]
	v_exp_f32_e32 v29, v18
	v_max_f32_e32 v16, 0xc1a00000, v16
	v_max_f32_e32 v17, 0xc1a00000, v17
	v_max_f32_e32 v18, 0xc1a00000, v19
	v_mul_f32_e32 v28, v26, v27
	v_mul_f32_e32 v16, 0xbfb8aa3b, v16
	v_mul_f32_e32 v17, 0xbfb8aa3b, v17
	v_mul_f32_e32 v18, 0xbfb8aa3b, v18
	v_rcp_f32_e32 v34, v28
	v_exp_f32_e32 v16, v16
	v_exp_f32_e32 v17, v17
	v_exp_f32_e32 v28, v18
	v_mul_f32_e32 v18, v27, v34
	v_mul_f32_e32 v26, v26, v34
	v_pk_add_f32 v[16:17], v[16:17], 1.0 op_sel_hi:[1,0]
	v_pk_add_f32 v[28:29], v[28:29], 1.0 op_sel_hi:[1,0]
	v_mov_b32_e32 v30, v16
	v_mov_b32_e32 v31, v29
	v_pk_mov_b32 v[32:33], v[16:17], v[28:29] op_sel:[1,0]
	v_pk_mul_f32 v[22:23], v[22:23], v[26:27] op_sel_hi:[1,0]
	v_pk_mul_f32 v[30:31], v[30:31], v[32:33]
	s_nop 0
	v_mul_f32_e32 v19, v30, v31
	v_rcp_f32_e32 v19, v19
	s_nop 0
	v_pk_mul_f32 v[20:21], v[20:21], v[18:19] op_sel:[1,0] op_sel_hi:[0,0]
	v_mul_f32_e32 v26, v31, v19
	v_mul_f32_e32 v18, v30, v19
	v_pk_mul_f32 v[18:19], v[28:29], v[18:19] op_sel_hi:[1,0]
	v_pk_mul_f32 v[16:17], v[16:17], v[26:27] op_sel:[1,0] op_sel_hi:[0,0]
.LBB0_753:
	v_cvt_pk_bf16_f32 v20, v20, v21
	v_cvt_pk_bf16_f32 v21, v22, v23
	v_cvt_pk_bf16_f32 v22, v16, v17
	v_pk_add_f32 v[14:15], v[14:15], 0 op_sel_hi:[1,0]
	v_pk_add_f32 v[16:17], v[12:13], 0 op_sel_hi:[1,0]
	v_pk_add_f32 v[10:11], v[10:11], 0 op_sel_hi:[1,0]
	s_and_b64 vcc, exec, s[4:5]
	v_pk_add_f32 v[12:13], v[8:9], 0 op_sel_hi:[1,0]
	v_cvt_pk_bf16_f32 v23, v18, v19
	global_store_dwordx4 v[24:25], v[20:23], off offset:256
	s_cbranch_vccnz .LBB0_755
	v_max_f32_e32 v14, 0xc1a00000, v14
	v_mul_f32_e32 v14, 0xbfb8aa3b, v14
	v_max_f32_e32 v9, v17, v17
	v_exp_f32_e32 v17, v14
	v_max_f32_e32 v8, 0xc1a00000, v16
	v_max_f32_e32 v9, 0xc1a00000, v9
	v_max_f32_e32 v14, 0xc1a00000, v15
	v_mul_f32_e32 v8, 0xbfb8aa3b, v8
	v_mul_f32_e32 v9, 0xbfb8aa3b, v9
	v_mul_f32_e32 v14, 0xbfb8aa3b, v14
	v_exp_f32_e32 v8, v8
	v_exp_f32_e32 v9, v9
	v_exp_f32_e32 v16, v14
	v_max_f32_e32 v10, 0xc1a00000, v10
	v_pk_add_f32 v[8:9], v[8:9], 1.0 op_sel_hi:[1,0]
	v_pk_add_f32 v[14:15], v[16:17], 1.0 op_sel_hi:[1,0]
	v_mov_b32_e32 v16, v8
	v_mov_b32_e32 v17, v15
	v_pk_mov_b32 v[18:19], v[8:9], v[14:15] op_sel:[1,0]
	v_mul_f32_e32 v10, 0xbfb8aa3b, v10
	v_pk_mul_f32 v[16:17], v[16:17], v[18:19]
	v_exp_f32_e32 v19, v10
	v_max_f32_e32 v12, 0xc1a00000, v12
	v_max_f32_e32 v13, 0xc1a00000, v13
	v_max_f32_e32 v10, 0xc1a00000, v11
	v_mul_f32_e32 v18, v16, v17
	v_mul_f32_e32 v12, 0xbfb8aa3b, v12
	v_mul_f32_e32 v13, 0xbfb8aa3b, v13
	v_mul_f32_e32 v10, 0xbfb8aa3b, v10
	v_rcp_f32_e32 v24, v18
	v_exp_f32_e32 v12, v12
	v_exp_f32_e32 v13, v13
	v_exp_f32_e32 v18, v10
	v_mul_f32_e32 v10, v17, v24
	v_mul_f32_e32 v16, v16, v24
	v_pk_add_f32 v[12:13], v[12:13], 1.0 op_sel_hi:[1,0]
	v_pk_add_f32 v[18:19], v[18:19], 1.0 op_sel_hi:[1,0]
	v_mov_b32_e32 v20, v12
	v_mov_b32_e32 v21, v19
	v_pk_mov_b32 v[22:23], v[12:13], v[18:19] op_sel:[1,0]
	v_pk_mul_f32 v[14:15], v[14:15], v[16:17] op_sel_hi:[1,0]
	v_pk_mul_f32 v[20:21], v[20:21], v[22:23]
	s_nop 0
	v_mul_f32_e32 v11, v20, v21
	v_rcp_f32_e32 v11, v11
	s_nop 0
	v_pk_mul_f32 v[16:17], v[8:9], v[10:11] op_sel:[1,0] op_sel_hi:[0,0]
	v_mul_f32_e32 v8, v21, v11
	v_mul_f32_e32 v10, v20, v11
	v_pk_mul_f32 v[10:11], v[18:19], v[10:11] op_sel_hi:[1,0]
	v_pk_mul_f32 v[12:13], v[12:13], v[8:9] op_sel:[1,0] op_sel_hi:[0,0]
.LBB0_755:
	v_add_u32_e32 v18, 0xb0, v155
	v_mov_b64_e32 v[8:9], s[0:1]
	v_mad_i64_i32 v[8:9], s[18:19], v18, s44, v[8:9]
	v_lshl_add_u64 v[8:9], v[120:121], 1, v[8:9]
	v_pk_add_f32 v[6:7], v[6:7], 0 op_sel_hi:[1,0]
	v_pk_add_f32 v[4:5], v[4:5], 0 op_sel_hi:[1,0]
	v_pk_add_f32 v[2:3], v[2:3], 0 op_sel_hi:[1,0]
	s_and_b64 vcc, exec, s[4:5]
	v_pk_add_f32 v[0:1], v[0:1], 0 op_sel_hi:[1,0]
	v_cvt_pk_bf16_f32 v16, v16, v17
	v_cvt_pk_bf16_f32 v17, v14, v15
	v_cvt_pk_bf16_f32 v18, v12, v13
	v_cvt_pk_bf16_f32 v19, v10, v11
	global_store_dwordx4 v[8:9], v[16:19], off
	s_cbranch_vccnz .LBB0_720
	v_max_f32_e32 v6, 0xc1a00000, v6
	v_mul_f32_e32 v6, 0xbfb8aa3b, v6
	v_exp_f32_e32 v11, v6
	v_max_f32_e32 v4, 0xc1a00000, v4
	v_max_f32_e32 v5, 0xc1a00000, v5
	v_max_f32_e32 v6, 0xc1a00000, v7
	v_mul_f32_e32 v4, 0xbfb8aa3b, v4
	v_mul_f32_e32 v5, 0xbfb8aa3b, v5
	v_mul_f32_e32 v6, 0xbfb8aa3b, v6
	v_exp_f32_e32 v4, v4
	v_exp_f32_e32 v5, v5
	v_exp_f32_e32 v10, v6
	v_max_f32_e32 v2, 0xc1a00000, v2
	v_pk_add_f32 v[4:5], v[4:5], 1.0 op_sel_hi:[1,0]
	v_pk_add_f32 v[6:7], v[10:11], 1.0 op_sel_hi:[1,0]
	v_mov_b32_e32 v10, v4
	v_mov_b32_e32 v11, v7
	v_pk_mov_b32 v[12:13], v[4:5], v[6:7] op_sel:[1,0]
	v_mul_f32_e32 v2, 0xbfb8aa3b, v2
	v_pk_mul_f32 v[10:11], v[10:11], v[12:13]
	v_exp_f32_e32 v13, v2
	v_max_f32_e32 v0, 0xc1a00000, v0
	v_max_f32_e32 v1, 0xc1a00000, v1
	v_max_f32_e32 v2, 0xc1a00000, v3
	v_mul_f32_e32 v12, v10, v11
	v_mul_f32_e32 v0, 0xbfb8aa3b, v0
	v_mul_f32_e32 v1, 0xbfb8aa3b, v1
	v_mul_f32_e32 v2, 0xbfb8aa3b, v2
	v_rcp_f32_e32 v18, v12
	v_exp_f32_e32 v0, v0
	v_exp_f32_e32 v1, v1
	v_exp_f32_e32 v12, v2
	v_mul_f32_e32 v2, v11, v18
	v_mul_f32_e32 v10, v10, v18
	v_pk_add_f32 v[0:1], v[0:1], 1.0 op_sel_hi:[1,0]
	v_pk_add_f32 v[12:13], v[12:13], 1.0 op_sel_hi:[1,0]
	v_mov_b32_e32 v14, v0
	v_mov_b32_e32 v15, v13
	v_pk_mov_b32 v[16:17], v[0:1], v[12:13] op_sel:[1,0]
	v_pk_mul_f32 v[6:7], v[6:7], v[10:11] op_sel_hi:[1,0]
	v_pk_mul_f32 v[14:15], v[14:15], v[16:17]
	s_nop 0
	v_mul_f32_e32 v3, v14, v15
	v_rcp_f32_e32 v3, v3
	s_nop 0
	v_pk_mul_f32 v[4:5], v[4:5], v[2:3] op_sel:[1,0] op_sel_hi:[0,0]
	v_mul_f32_e32 v10, v15, v3
	v_mul_f32_e32 v2, v14, v3
	v_pk_mul_f32 v[2:3], v[12:13], v[2:3] op_sel_hi:[1,0]
	v_pk_mul_f32 v[0:1], v[0:1], v[10:11] op_sel:[1,0] op_sel_hi:[0,0]
	s_branch .LBB0_720

; #define PG8_STAGE(bufoff, gbase, voff) do { _Pragma("unroll") for (int _i = 0; _i < 2; ++_i) \
;         __builtin_amdgcn_global_load_lds((const unsigned*)((const char*)(gbase) + (voff)[_i]), (PG8_LAS unsigned*)(lds + (bufoff) + ldsw + _i * 8192), 16, 0, 0); } while (0)
; #define PG8_LDA(dst, b, h) do { _Pragma("unroll") for (int m = 0; m < 4; ++m) _Pragma("unroll") for (int k = 0; k < 2; ++k) dst[m][k] = *(const PG8_LAS bf16x8*)(lds + PG8_SA(b, h) + aoff + m * 2048 + k * 1024); } while (0)
; #define PG8_LDB(dst, b, h) do { _Pragma("unroll") for (int n = 0; n < 2; ++n) _Pragma("unroll") for (int k = 0; k < 2; ++k) dst[n][k] = *(const PG8_LAS bf16x8*)(lds + PG8_SB(b, h) + boff + n * 2048 + k * 1024); } while (0)
; #define PG8_MMA(ai, bj, At, Bt) do { __builtin_amdgcn_s_setprio(1); _Pragma("unroll") for (int m = 0; m < 4; ++m) _Pragma("unroll") for (int n = 0; n < 2; ++n) _Pragma("unroll") for (int k = 0; k < 2; ++k) \
;         acc[ai][bj][m][n] = __builtin_amdgcn_mfma_f32_16x16x32_bf16(Bt[n][k], At[m][k], acc[ai][bj][m][n], 0, 0, 0); __builtin_amdgcn_s_setprio(0); } while (0)
; #define PG8_WAIT_V(n) asm volatile("s_waitcnt vmcnt(" #n ")" ::: "memory")
; #define PG8_WAIT_L(n) asm volatile("s_waitcnt lgkmcnt(" #n ")" ::: "memory")
; #define PG8_BAR __builtin_amdgcn_s_barrier()
; #define PG8_SCHED __builtin_amdgcn_sched_barrier(0)
; template <class Epi, class Sched>
; __device__ __forceinline__ void gemm_phase(PG8_LAS unsigned char* lds, const Gemm g, const Sched& S, const Epi& E) {
;     ...
;             PG8_LDB(B0, 0, 0); PG8_SCHED; PG8_LDA(At, 0, 0); PG8_STAGE(PG8_SA(1, 1), a1 + hstep, voffA);
;             PG8_WAIT_L(8); PG8_BAR; PG8_WAIT_L(0); PG8_MMA(0, 0, At, B0); PG8_BAR; PG8_SCHED;
;             PG8_LDB(B1, 0, 1); PG8_STAGE(PG8_SB(0, 0), b2, voffB);
;             PG8_BAR; PG8_WAIT_L(0); PG8_MMA(0, 1, At, B1); PG8_BAR;
;             PG8_LDA(At, 0, 1); PG8_STAGE(PG8_SA(0, 0), a2, voffA);
;             PG8_BAR; PG8_WAIT_L(0); PG8_MMA(1, 0, At, B0); PG8_BAR; PG8_SCHED;
;             PG8_STAGE(PG8_SB(0, 1), b2 + hstep, voffB);
;             PG8_WAIT_V(6); PG8_BAR; PG8_MMA(1, 1, At, B1); PG8_BAR;
.LBB0_1202:
	ds_read_b128 v[144:147], v151
	ds_read_b128 v[154:157], v151 offset:1024
	ds_read_b128 v[158:161], v151 offset:2048
	ds_read_b128 v[162:165], v151 offset:3072
	s_add_u32 s18, s16, 0xfffc0080
	s_addc_u32 s19, s17, -1
	s_cmp_eq_u32 s46, 12
	s_cselect_b32 s21, s9, s19
	s_cselect_b32 s20, s42, s18
	s_cselect_b32 s19, s7, s45
	s_cselect_b32 s18, s43, s44
	v_lshl_add_u64 v[174:175], s[16:17], 0, v[136:137]
	s_add_i32 m0, s15, 0xc000
	ds_read_b128 v[166:169], v152
	ds_read_b128 v[170:173], v152 offset:1024
	ds_read_b128 v[182:185], v152 offset:2048
	ds_read_b128 v[190:193], v152 offset:3072
	ds_read_b128 v[194:197], v152 offset:4096
	ds_read_b128 v[198:201], v152 offset:5120
	ds_read_b128 v[202:205], v152 offset:6144
	ds_read_b128 v[206:209], v152 offset:7168
	global_load_lds_dwordx4 v[174:175], off
	v_lshl_add_u64 v[174:175], s[16:17], 0, v[138:139]
	s_add_i32 m0, s15, 0xe000
	s_nop 0
	global_load_lds_dwordx4 v[174:175], off
	s_waitcnt lgkmcnt(8)
	ds_read_b128 v[210:213], v153
	ds_read_b128 v[214:217], v153 offset:1024
	ds_read_b128 v[218:221], v153 offset:2048
	ds_read_b128 v[222:225], v153 offset:3072
	s_waitcnt vmcnt(8) lgkmcnt(0)
	s_barrier
	v_mfma_f32_16x16x32_bf16 v[124:127], v[144:147], v[166:169], v[124:127]
	v_mfma_f32_16x16x32_bf16 v[120:123], v[158:161], v[166:169], v[120:123]
	v_mfma_f32_16x16x32_bf16 v[108:111], v[144:147], v[182:185], v[108:111]
	v_mfma_f32_16x16x32_bf16 v[104:107], v[158:161], v[182:185], v[104:107]
	v_mfma_f32_16x16x32_bf16 v[92:95], v[144:147], v[194:197], v[92:95]
	v_mfma_f32_16x16x32_bf16 v[88:91], v[158:161], v[194:197], v[88:91]
	v_mfma_f32_16x16x32_bf16 v[76:79], v[144:147], v[202:205], v[76:79]
	v_mfma_f32_16x16x32_bf16 v[72:75], v[158:161], v[202:205], v[72:75]
	v_mfma_f32_16x16x32_bf16 v[124:127], v[154:157], v[170:173], v[124:127]
	v_mfma_f32_16x16x32_bf16 v[120:123], v[162:165], v[170:173], v[120:123]
	v_mfma_f32_16x16x32_bf16 v[108:111], v[154:157], v[190:193], v[108:111]
	v_mfma_f32_16x16x32_bf16 v[104:107], v[162:165], v[190:193], v[104:107]
	v_mfma_f32_16x16x32_bf16 v[92:95], v[154:157], v[198:201], v[92:95]
	v_mfma_f32_16x16x32_bf16 v[88:91], v[162:165], v[198:201], v[88:91]
	v_mfma_f32_16x16x32_bf16 v[76:79], v[154:157], v[206:209], v[76:79]
	v_mfma_f32_16x16x32_bf16 v[72:75], v[162:165], v[206:209], v[72:75]
	v_mfma_f32_16x16x32_bf16 v[116:119], v[210:213], v[166:169], v[116:119]
	v_mfma_f32_16x16x32_bf16 v[112:115], v[218:221], v[166:169], v[112:115]
	v_mfma_f32_16x16x32_bf16 v[100:103], v[210:213], v[182:185], v[100:103]
	v_mfma_f32_16x16x32_bf16 v[96:99], v[218:221], v[182:185], v[96:99]
	v_mfma_f32_16x16x32_bf16 v[84:87], v[210:213], v[194:197], v[84:87]
	v_mfma_f32_16x16x32_bf16 v[80:83], v[218:221], v[194:197], v[80:83]
	v_mfma_f32_16x16x32_bf16 v[68:71], v[210:213], v[202:205], v[68:71]
	v_mfma_f32_16x16x32_bf16 v[64:67], v[218:221], v[202:205], v[64:67]
	v_mfma_f32_16x16x32_bf16 v[116:119], v[214:217], v[170:173], v[116:119]
	v_mfma_f32_16x16x32_bf16 v[112:115], v[222:225], v[170:173], v[112:115]
	v_mfma_f32_16x16x32_bf16 v[100:103], v[214:217], v[190:193], v[100:103]
	v_mfma_f32_16x16x32_bf16 v[96:99], v[222:225], v[190:193], v[96:99]
	v_mfma_f32_16x16x32_bf16 v[84:87], v[214:217], v[198:201], v[84:87]
	v_mfma_f32_16x16x32_bf16 v[80:83], v[222:225], v[198:201], v[80:83]
	v_mfma_f32_16x16x32_bf16 v[68:71], v[214:217], v[206:209], v[68:71]
	v_mfma_f32_16x16x32_bf16 v[64:67], v[222:225], v[206:209], v[64:67]
	s_barrier
	ds_read_b128 v[166:169], v152 offset:16384
	ds_read_b128 v[170:173], v152 offset:17408
	ds_read_b128 v[182:185], v152 offset:18432
	ds_read_b128 v[190:193], v152 offset:19456
	ds_read_b128 v[194:197], v152 offset:20480
	ds_read_b128 v[198:201], v152 offset:21504
	ds_read_b128 v[202:205], v152 offset:22528
	ds_read_b128 v[206:209], v152 offset:23552
	s_add_i32 s47, s38, s26
	v_lshl_add_u64 v[174:175], s[18:19], 0, v[132:133]
	s_mov_b32 m0, s47
	s_nop 0
	global_load_lds_dwordx4 v[174:175], off
	v_lshl_add_u64 v[186:187], s[18:19], 0, v[128:129]
	s_add_i32 m0, s47, 0x2000
	s_nop 0
	global_load_lds_dwordx4 v[186:187], off
	s_nop 1
	s_mov_b32 m0, s15
	v_lshl_add_u64 v[226:227], s[20:21], 0, v[134:135]
	global_load_lds_dwordx4 v[226:227], off
	v_lshl_add_u64 v[228:229], s[20:21], 0, v[130:131]
	s_mov_b32 m0, s29
	s_nop 0
	global_load_lds_dwordx4 v[228:229], off
	s_add_u32 s48, s18, 0x40000
	s_addc_u32 s49, s19, 0
	s_add_i32 s47, s39, s26
	v_lshl_add_u64 v[246:247], s[48:49], 0, v[132:133]
	s_mov_b32 m0, s47
	s_nop 0
	global_load_lds_dwordx4 v[246:247], off
	v_lshl_add_u64 v[246:247], s[48:49], 0, v[128:129]
	s_add_i32 m0, s47, 0x2000
	s_nop 0
	global_load_lds_dwordx4 v[246:247], off
	s_waitcnt vmcnt(8) lgkmcnt(0)
	s_barrier
; #define PG8_STAGE(bufoff, gbase, voff) do { _Pragma("unroll") for (int _i = 0; _i < 2; ++_i) \
;         __builtin_amdgcn_global_load_lds((const unsigned*)((const char*)(gbase) + (voff)[_i]), (PG8_LAS unsigned*)(lds + (bufoff) + ldsw + _i * 8192), 16, 0, 0); } while (0)
; #define PG8_LDA(dst, b, h) do { _Pragma("unroll") for (int m = 0; m < 4; ++m) _Pragma("unroll") for (int k = 0; k < 2; ++k) dst[m][k] = *(const PG8_LAS bf16x8*)(lds + PG8_SA(b, h) + aoff + m * 2048 + k * 1024); } while (0)
; #define PG8_LDB(dst, b, h) do { _Pragma("unroll") for (int n = 0; n < 2; ++n) _Pragma("unroll") for (int k = 0; k < 2; ++k) dst[n][k] = *(const PG8_LAS bf16x8*)(lds + PG8_SB(b, h) + boff + n * 2048 + k * 1024); } while (0)
; #define PG8_MMA(ai, bj, At, Bt) do { __builtin_amdgcn_s_setprio(1); _Pragma("unroll") for (int m = 0; m < 4; ++m) _Pragma("unroll") for (int n = 0; n < 2; ++n) _Pragma("unroll") for (int k = 0; k < 2; ++k) \
;         acc[ai][bj][m][n] = __builtin_amdgcn_mfma_f32_16x16x32_bf16(Bt[n][k], At[m][k], acc[ai][bj][m][n], 0, 0, 0); __builtin_amdgcn_s_setprio(0); } while (0)
; #define PG8_WAIT_V(n) asm volatile("s_waitcnt vmcnt(" #n ")" ::: "memory")
; #define PG8_WAIT_L(n) asm volatile("s_waitcnt lgkmcnt(" #n ")" ::: "memory")
; #define PG8_BAR __builtin_amdgcn_s_barrier()
; #define PG8_SCHED __builtin_amdgcn_sched_barrier(0)
; template <class Epi, class Sched>
; __device__ __forceinline__ void gemm_phase(PG8_LAS unsigned char* lds, const Gemm g, const Sched& S, const Epi& E) {
;     ...
;             PG8_BAR; PG8_WAIT_L(0); PG8_MMA(1, 0, At, B0); PG8_BAR; PG8_SCHED;
;             PG8_STAGE(PG8_SB(0, 1), b2 + hstep, voffB);
;             PG8_WAIT_V(6); PG8_BAR; PG8_MMA(1, 1, At, B1); PG8_BAR;
;             PG8_LDB(B0, 1, 0); PG8_SCHED; PG8_LDA(At, 1, 0); PG8_STAGE(PG8_SA(0, 1), a2 + hstep, voffA);
;             PG8_WAIT_L(8); PG8_BAR; PG8_WAIT_L(0); PG8_MMA(0, 0, At, B0); PG8_BAR; PG8_SCHED;
;             PG8_LDB(B1, 1, 1); PG8_STAGE(PG8_SB(1, 0), b3, voffB);
;             PG8_BAR; PG8_WAIT_L(0); PG8_MMA(0, 1, At, B1); PG8_BAR;
	v_mfma_f32_16x16x32_bf16 v[60:63], v[144:147], v[166:169], v[60:63]
	v_mfma_f32_16x16x32_bf16 v[56:59], v[158:161], v[166:169], v[56:59]
	v_mfma_f32_16x16x32_bf16 v[44:47], v[144:147], v[182:185], v[44:47]
	v_mfma_f32_16x16x32_bf16 v[40:43], v[158:161], v[182:185], v[40:43]
	v_mfma_f32_16x16x32_bf16 v[28:31], v[144:147], v[194:197], v[28:31]
	v_mfma_f32_16x16x32_bf16 v[24:27], v[158:161], v[194:197], v[24:27]
	v_mfma_f32_16x16x32_bf16 v[12:15], v[144:147], v[202:205], v[12:15]
	v_mfma_f32_16x16x32_bf16 v[8:11], v[158:161], v[202:205], v[8:11]
	v_mfma_f32_16x16x32_bf16 v[60:63], v[154:157], v[170:173], v[60:63]
	v_mfma_f32_16x16x32_bf16 v[56:59], v[162:165], v[170:173], v[56:59]
	v_mfma_f32_16x16x32_bf16 v[44:47], v[154:157], v[190:193], v[44:47]
	v_mfma_f32_16x16x32_bf16 v[40:43], v[162:165], v[190:193], v[40:43]
	v_mfma_f32_16x16x32_bf16 v[28:31], v[154:157], v[198:201], v[28:31]
	v_mfma_f32_16x16x32_bf16 v[24:27], v[162:165], v[198:201], v[24:27]
	v_mfma_f32_16x16x32_bf16 v[12:15], v[154:157], v[206:209], v[12:15]
	v_mfma_f32_16x16x32_bf16 v[8:11], v[162:165], v[206:209], v[8:11]
	v_mfma_f32_16x16x32_bf16 v[52:55], v[210:213], v[166:169], v[52:55]
	v_mfma_f32_16x16x32_bf16 v[48:51], v[218:221], v[166:169], v[48:51]
	v_mfma_f32_16x16x32_bf16 v[36:39], v[210:213], v[182:185], v[36:39]
	v_mfma_f32_16x16x32_bf16 v[32:35], v[218:221], v[182:185], v[32:35]
	v_mfma_f32_16x16x32_bf16 v[20:23], v[210:213], v[194:197], v[20:23]
	v_mfma_f32_16x16x32_bf16 v[16:19], v[218:221], v[194:197], v[16:19]
	v_mfma_f32_16x16x32_bf16 v[4:7], v[210:213], v[202:205], v[4:7]
	v_mfma_f32_16x16x32_bf16 v[0:3], v[218:221], v[202:205], v[0:3]
	v_mfma_f32_16x16x32_bf16 v[52:55], v[214:217], v[170:173], v[52:55]
	v_mfma_f32_16x16x32_bf16 v[48:51], v[222:225], v[170:173], v[48:51]
	v_mfma_f32_16x16x32_bf16 v[36:39], v[214:217], v[190:193], v[36:39]
	v_mfma_f32_16x16x32_bf16 v[32:35], v[222:225], v[190:193], v[32:35]
	v_mfma_f32_16x16x32_bf16 v[20:23], v[214:217], v[198:201], v[20:23]
	v_mfma_f32_16x16x32_bf16 v[16:19], v[222:225], v[198:201], v[16:19]
	v_mfma_f32_16x16x32_bf16 v[4:7], v[214:217], v[206:209], v[4:7]
	v_mfma_f32_16x16x32_bf16 v[0:3], v[222:225], v[206:209], v[0:3]
	s_barrier
	s_add_i32 s47, 0, 0x18000
	v_add_u32_e32 v162, s47, v149
	ds_read_b128 v[144:147], v162
	ds_read_b128 v[154:157], v162 offset:1024
	ds_read_b128 v[158:161], v162 offset:2048
	ds_read_b128 v[162:165], v162 offset:3072
	s_add_u32 s20, s20, 0x40000
	s_addc_u32 s21, s21, 0
	s_mov_b32 m0, s30
	v_lshl_add_u64 v[210:211], s[20:21], 0, v[134:135]
	ds_read_b128 v[166:169], v152 offset:32768
	ds_read_b128 v[170:173], v152 offset:33792
	ds_read_b128 v[182:185], v152 offset:34816
	ds_read_b128 v[190:193], v152 offset:35840
	ds_read_b128 v[194:197], v152 offset:36864
	ds_read_b128 v[198:201], v152 offset:37888
	ds_read_b128 v[202:205], v152 offset:38912
	ds_read_b128 v[206:209], v152 offset:39936
	global_load_lds_dwordx4 v[210:211], off
	v_lshl_add_u64 v[210:211], s[20:21], 0, v[130:131]
	s_mov_b32 m0, s31
	s_nop 0
	global_load_lds_dwordx4 v[210:211], off
	s_add_i32 s20, 0, 0x1c000
	v_add_u32_e32 v179, s20, v149
	s_waitcnt lgkmcnt(8)
	ds_read_b128 v[210:213], v179
	ds_read_b128 v[214:217], v179 offset:1024
	ds_read_b128 v[218:221], v179 offset:2048
	ds_read_b128 v[222:225], v179 offset:3072
	s_waitcnt vmcnt(8) lgkmcnt(0)
	s_barrier
	v_mfma_f32_16x16x32_bf16 v[124:127], v[144:147], v[166:169], v[124:127]
	v_mfma_f32_16x16x32_bf16 v[120:123], v[158:161], v[166:169], v[120:123]
	v_mfma_f32_16x16x32_bf16 v[108:111], v[144:147], v[182:185], v[108:111]
	v_mfma_f32_16x16x32_bf16 v[104:107], v[158:161], v[182:185], v[104:107]
	v_mfma_f32_16x16x32_bf16 v[92:95], v[144:147], v[194:197], v[92:95]
	v_mfma_f32_16x16x32_bf16 v[88:91], v[158:161], v[194:197], v[88:91]
	v_mfma_f32_16x16x32_bf16 v[76:79], v[144:147], v[202:205], v[76:79]
	v_mfma_f32_16x16x32_bf16 v[72:75], v[158:161], v[202:205], v[72:75]
	v_mfma_f32_16x16x32_bf16 v[124:127], v[154:157], v[170:173], v[124:127]
	v_mfma_f32_16x16x32_bf16 v[120:123], v[162:165], v[170:173], v[120:123]
	v_mfma_f32_16x16x32_bf16 v[108:111], v[154:157], v[190:193], v[108:111]
	v_mfma_f32_16x16x32_bf16 v[104:107], v[162:165], v[190:193], v[104:107]
	v_mfma_f32_16x16x32_bf16 v[92:95], v[154:157], v[198:201], v[92:95]
	v_mfma_f32_16x16x32_bf16 v[88:91], v[162:165], v[198:201], v[88:91]
	v_mfma_f32_16x16x32_bf16 v[76:79], v[154:157], v[206:209], v[76:79]
	v_mfma_f32_16x16x32_bf16 v[72:75], v[162:165], v[206:209], v[72:75]
	v_mfma_f32_16x16x32_bf16 v[116:119], v[210:213], v[166:169], v[116:119]
	v_mfma_f32_16x16x32_bf16 v[112:115], v[218:221], v[166:169], v[112:115]
	v_mfma_f32_16x16x32_bf16 v[100:103], v[210:213], v[182:185], v[100:103]
	v_mfma_f32_16x16x32_bf16 v[96:99], v[218:221], v[182:185], v[96:99]
	v_mfma_f32_16x16x32_bf16 v[84:87], v[210:213], v[194:197], v[84:87]
	v_mfma_f32_16x16x32_bf16 v[80:83], v[218:221], v[194:197], v[80:83]
	v_mfma_f32_16x16x32_bf16 v[68:71], v[210:213], v[202:205], v[68:71]
	v_mfma_f32_16x16x32_bf16 v[64:67], v[218:221], v[202:205], v[64:67]
	v_mfma_f32_16x16x32_bf16 v[116:119], v[214:217], v[170:173], v[116:119]
	v_mfma_f32_16x16x32_bf16 v[112:115], v[222:225], v[170:173], v[112:115]
	v_mfma_f32_16x16x32_bf16 v[100:103], v[214:217], v[190:193], v[100:103]
	v_mfma_f32_16x16x32_bf16 v[96:99], v[222:225], v[190:193], v[96:99]
	v_mfma_f32_16x16x32_bf16 v[84:87], v[214:217], v[198:201], v[84:87]
	v_mfma_f32_16x16x32_bf16 v[80:83], v[222:225], v[198:201], v[80:83]
	v_mfma_f32_16x16x32_bf16 v[68:71], v[214:217], v[206:209], v[68:71]
	v_mfma_f32_16x16x32_bf16 v[64:67], v[222:225], v[206:209], v[64:67]
	s_barrier
; #define PG8_STAGE(bufoff, gbase, voff) do { _Pragma("unroll") for (int _i = 0; _i < 2; ++_i) \
;         __builtin_amdgcn_global_load_lds((const unsigned*)((const char*)(gbase) + (voff)[_i]), (PG8_LAS unsigned*)(lds + (bufoff) + ldsw + _i * 8192), 16, 0, 0); } while (0)
; #define PG8_LDA(dst, b, h) do { _Pragma("unroll") for (int m = 0; m < 4; ++m) _Pragma("unroll") for (int k = 0; k < 2; ++k) dst[m][k] = *(const PG8_LAS bf16x8*)(lds + PG8_SA(b, h) + aoff + m * 2048 + k * 1024); } while (0)
; #define PG8_LDB(dst, b, h) do { _Pragma("unroll") for (int n = 0; n < 2; ++n) _Pragma("unroll") for (int k = 0; k < 2; ++k) dst[n][k] = *(const PG8_LAS bf16x8*)(lds + PG8_SB(b, h) + boff + n * 2048 + k * 1024); } while (0)
; #define PG8_BAR __builtin_amdgcn_s_barrier()
; __device__ __forceinline__ f32x4 sigmoid4(f32x4 x) {
;     f32x4 d;
; #pragma unroll
;     for (int j = 0; j < 4; ++j) d[j] = 1.0f + __expf(-fmaxf(x[j], -20.0f));
;     const float p01 = d[0] * d[1], p23 = d[2] * d[3], r = __builtin_amdgcn_rcpf(p01 * p23), r01 = r * p23, r23 = r * p01;
;     return (f32x4){r01 * d[1], r01 * d[0], r23 * d[3], r23 * d[2]};
; }
;     __device__ __forceinline__ void operator()(const f32x4 (&acc)[2][2][4][2], const Unit& u, int wr, int wc, int fr, int fq) const {
;     ...
;             for (int m = 0; m < 4; ++m) { bf16_t* rowp = O + (size_t)(row0 + ai * HALF + m * 16) * ldc + col0;
;                 f32x4 v0, v1;
; #pragma unroll
;                 for (int j = 0; j < 1; ++j) { v0 = acc[ai][0][m][0] * sigmoid4(acc[ai][0][m][0]) * acc[ai][1][m][0]; v1 = acc[ai][0][m][1] * sigmoid4(acc[ai][0][m][1]) * acc[ai][1][m][1]; }
; template <class Epi, class Sched>
; __device__ __forceinline__ void gemm_phase(PG8_LAS unsigned char* lds, const Gemm g, const Sched& S, const Epi& E) {
;     ...
;             PG8_LDB(B0, 1, 0); PG8_SCHED; PG8_LDA(At, 1, 0); PG8_STAGE(PG8_SA(0, 1), a2 + hstep, voffA);
;             PG8_WAIT_L(8); PG8_BAR; PG8_WAIT_L(0); PG8_MMA(0, 0, At, B0); PG8_BAR; PG8_SCHED;
;             PG8_LDB(B1, 1, 1); PG8_STAGE(PG8_SB(1, 0), b3, voffB);
;             PG8_BAR; PG8_WAIT_L(0); PG8_MMA(0, 1, At, B1); PG8_BAR;
;             PG8_LDA(At, 1, 1); PG8_STAGE(PG8_SA(1, 0), a3, voffA);
;             PG8_BAR; PG8_WAIT_L(0); PG8_MMA(1, 0, At, B0); PG8_BAR; PG8_SCHED;
;             PG8_STAGE(PG8_SB(1, 1), b3 + hstep, voffB);
;             PG8_WAIT_V(6); PG8_BAR; PG8_MMA(1, 1, At, B1); PG8_BAR;
	ds_read_b128 v[166:169], v152 offset:49152
	ds_read_b128 v[170:173], v152 offset:50176
	ds_read_b128 v[182:185], v152 offset:51200
	ds_read_b128 v[190:193], v152 offset:52224
	ds_read_b128 v[194:197], v152 offset:53248
	ds_read_b128 v[198:201], v152 offset:54272
	ds_read_b128 v[202:205], v152 offset:55296
	ds_read_b128 v[206:209], v152 offset:56320
	s_add_i32 s21, s47, s26
	v_lshl_add_u64 v[174:175], v[174:175], 0, s[4:5]
	s_mov_b32 m0, s21
	s_nop 0
	global_load_lds_dwordx4 v[174:175], off
	v_lshl_add_u64 v[174:175], v[186:187], 0, s[4:5]
	s_add_i32 m0, s21, 0x2000
	s_nop 0
	global_load_lds_dwordx4 v[174:175], off
	s_nop 1
	s_mov_b32 m0, s35
	v_lshl_add_u64 v[174:175], v[226:227], 0, s[4:5]
	global_load_lds_dwordx4 v[174:175], off
	v_lshl_add_u64 v[174:175], v[228:229], 0, s[4:5]
	s_mov_b32 m0, s36
	s_nop 0
	global_load_lds_dwordx4 v[174:175], off
	s_add_u32 s18, s18, 0x40080
	s_addc_u32 s19, s19, 0
	s_add_i32 s20, s20, s26
	v_lshl_add_u64 v[246:247], s[18:19], 0, v[132:133]
	s_mov_b32 m0, s20
	s_nop 0
	global_load_lds_dwordx4 v[246:247], off
	v_lshl_add_u64 v[246:247], s[18:19], 0, v[128:129]
	s_add_i32 m0, s20, 0x2000
	s_nop 0
	global_load_lds_dwordx4 v[246:247], off
	s_waitcnt vmcnt(8) lgkmcnt(0)
	s_barrier
	v_mfma_f32_16x16x32_bf16 v[60:63], v[144:147], v[166:169], v[60:63]
	v_mfma_f32_16x16x32_bf16 v[56:59], v[158:161], v[166:169], v[56:59]
	v_mfma_f32_16x16x32_bf16 v[44:47], v[144:147], v[182:185], v[44:47]
	v_mfma_f32_16x16x32_bf16 v[40:43], v[158:161], v[182:185], v[40:43]
	v_mfma_f32_16x16x32_bf16 v[28:31], v[144:147], v[194:197], v[28:31]
	v_mfma_f32_16x16x32_bf16 v[24:27], v[158:161], v[194:197], v[24:27]
	v_mfma_f32_16x16x32_bf16 v[12:15], v[144:147], v[202:205], v[12:15]
	v_mfma_f32_16x16x32_bf16 v[8:11], v[158:161], v[202:205], v[8:11]
	v_mfma_f32_16x16x32_bf16 v[60:63], v[154:157], v[170:173], v[60:63]
	v_mfma_f32_16x16x32_bf16 v[56:59], v[162:165], v[170:173], v[56:59]
	v_mfma_f32_16x16x32_bf16 v[44:47], v[154:157], v[190:193], v[44:47]
	v_mfma_f32_16x16x32_bf16 v[40:43], v[162:165], v[190:193], v[40:43]
	v_mfma_f32_16x16x32_bf16 v[28:31], v[154:157], v[198:201], v[28:31]
	v_mfma_f32_16x16x32_bf16 v[24:27], v[162:165], v[198:201], v[24:27]
	v_mfma_f32_16x16x32_bf16 v[12:15], v[154:157], v[206:209], v[12:15]
	v_mfma_f32_16x16x32_bf16 v[8:11], v[162:165], v[206:209], v[8:11]
	v_mfma_f32_16x16x32_bf16 v[52:55], v[210:213], v[166:169], v[52:55]
	v_mfma_f32_16x16x32_bf16 v[48:51], v[218:221], v[166:169], v[48:51]
	v_mfma_f32_16x16x32_bf16 v[36:39], v[210:213], v[182:185], v[36:39]
	v_mfma_f32_16x16x32_bf16 v[32:35], v[218:221], v[182:185], v[32:35]
	v_mfma_f32_16x16x32_bf16 v[20:23], v[210:213], v[194:197], v[20:23]
	v_mfma_f32_16x16x32_bf16 v[16:19], v[218:221], v[194:197], v[16:19]
	v_mfma_f32_16x16x32_bf16 v[4:7], v[210:213], v[202:205], v[4:7]
	v_mfma_f32_16x16x32_bf16 v[0:3], v[218:221], v[202:205], v[0:3]
	v_mfma_f32_16x16x32_bf16 v[52:55], v[214:217], v[170:173], v[52:55]
	v_mfma_f32_16x16x32_bf16 v[48:51], v[222:225], v[170:173], v[48:51]
	v_mfma_f32_16x16x32_bf16 v[36:39], v[214:217], v[190:193], v[36:39]
	v_mfma_f32_16x16x32_bf16 v[32:35], v[222:225], v[190:193], v[32:35]
	v_mfma_f32_16x16x32_bf16 v[20:23], v[214:217], v[198:201], v[20:23]
	v_mfma_f32_16x16x32_bf16 v[16:19], v[222:225], v[198:201], v[16:19]
	v_mfma_f32_16x16x32_bf16 v[4:7], v[214:217], v[206:209], v[4:7]
	v_mfma_f32_16x16x32_bf16 v[0:3], v[222:225], v[206:209], v[0:3]
	s_barrier
	s_add_i32 s46, s46, 2
	s_add_u32 s16, s16, 0x100
	s_addc_u32 s17, s17, 0
	s_add_u32 s44, s44, 0x100
	s_addc_u32 s45, s45, 0
	s_cmp_gt_u32 s46, 13
	s_cbranch_scc0 .LBB0_1202
	v_max_f32_e32 v144, 0xc1a00000, v124
	v_mul_f32_e32 v144, 0xbfb8aa3b, v144
	v_exp_f32_e32 v157, v144
	v_max_f32_e32 v144, 0xc1a00000, v125
	v_mul_f32_e32 v144, 0xbfb8aa3b, v144
	v_exp_f32_e32 v156, v144
	v_max_f32_e32 v144, 0xc1a00000, v126
	v_mul_f32_e32 v144, 0xbfb8aa3b, v144
	v_exp_f32_e32 v159, v144
	v_max_f32_e32 v144, 0xc1a00000, v127
	v_mul_f32_e32 v144, 0xbfb8aa3b, v144
	v_exp_f32_e32 v158, v144
	v_pk_add_f32 v[156:157], v[156:157], 1.0 op_sel_hi:[1,0]
	v_lshl_or_b32 v146, s41, 7, v150
	v_mov_b32_e32 v160, v157
	v_pk_add_f32 v[158:159], v[158:159], 1.0 op_sel_hi:[1,0]
	v_mov_b32_e32 v162, v156
	v_mov_b32_e32 v161, v159
	v_mov_b32_e32 v163, v158
	v_pk_mul_f32 v[160:161], v[160:161], v[162:163]
	v_lshl_add_u32 v154, s14, 8, v148
	v_mul_f32_e32 v155, v160, v161
	v_rcp_f32_e32 v155, v155
	v_ashrrev_i32_e32 v147, 31, v146
	v_mov_b64_e32 v[144:145], s[0:1]
	v_mad_i64_i32 v[162:163], s[16:17], v154, s40, v[144:145]
	v_mul_f32_e32 v164, v161, v155
	v_mul_f32_e32 v160, v160, v155
	v_max_f32_e32 v155, 0xc1a00000, v120
	v_mul_f32_e32 v155, 0xbfb8aa3b, v155
	v_pk_mul_f32 v[158:159], v[158:159], v[160:161] op_sel_hi:[1,0]
	v_exp_f32_e32 v161, v155
	v_max_f32_e32 v155, 0xc1a00000, v121
	v_mul_f32_e32 v155, 0xbfb8aa3b, v155
	v_exp_f32_e32 v160, v155
	v_max_f32_e32 v155, 0xc1a00000, v122
	v_mul_f32_e32 v155, 0xbfb8aa3b, v155
	v_exp_f32_e32 v167, v155
	v_max_f32_e32 v155, 0xc1a00000, v123
	v_mul_f32_e32 v155, 0xbfb8aa3b, v155
	v_exp_f32_e32 v166, v155
	v_pk_mul_f32 v[156:157], v[156:157], v[164:165] op_sel_hi:[1,0]
	v_pk_mul_f32 v[126:127], v[126:127], v[158:159]
	v_pk_mul_f32 v[124:125], v[124:125], v[156:157]
	v_pk_add_f32 v[156:157], v[160:161], 1.0 op_sel_hi:[1,0]
	v_pk_add_f32 v[160:161], v[166:167], 1.0 op_sel_hi:[1,0]
	v_mov_b32_e32 v164, v157
	v_mov_b32_e32 v165, v161
	v_mov_b32_e32 v166, v156
	v_mov_b32_e32 v167, v160
	v_pk_mul_f32 v[164:165], v[164:165], v[166:167]
	v_pk_mul_f32 v[118:119], v[126:127], v[118:119]
	v_mul_f32_e32 v155, v164, v165
	v_rcp_f32_e32 v155, v155
	v_pk_mul_f32 v[116:117], v[124:125], v[116:117]
; __device__ __forceinline__ unsigned cvt_pk_bf16(float lo, float hi) { unsigned r; asm volatile("v_cvt_pk_bf16_f32 %0, %1, %2" : "=v"(r) : "v"(lo), "v"(hi)); return r; }
; __device__ __forceinline__ f32x4 sigmoid4(f32x4 x) {
;     f32x4 d;
; #pragma unroll
;     for (int j = 0; j < 4; ++j) d[j] = 1.0f + __expf(-fmaxf(x[j], -20.0f));
;     const float p01 = d[0] * d[1], p23 = d[2] * d[3], r = __builtin_amdgcn_rcpf(p01 * p23), r01 = r * p23, r23 = r * p01;
;     return (f32x4){r01 * d[1], r01 * d[0], r23 * d[3], r23 * d[2]};
; }
;     __device__ __forceinline__ void operator()(const f32x4 (&acc)[2][2][4][2], const Unit& u, int wr, int wc, int fr, int fq) const {
;         const int row0 = u.pm * BM + wr * 64 + fr, col0 = u.pn * HALF + wc * 32 + 8 * fq;
; #pragma unroll
;         for (int ai = 0; ai < 2; ++ai)
; #pragma unroll
;             for (int m = 0; m < 4; ++m) { bf16_t* rowp = O + (size_t)(row0 + ai * HALF + m * 16) * ldc + col0;
;                 f32x4 v0, v1;
; #pragma unroll
;                 for (int j = 0; j < 1; ++j) { v0 = acc[ai][0][m][0] * sigmoid4(acc[ai][0][m][0]) * acc[ai][1][m][0]; v1 = acc[ai][0][m][1] * sigmoid4(acc[ai][0][m][1]) * acc[ai][1][m][1]; }
;                 u32x4 w; w.x = cvt_pk_bf16(v0[0], v0[1]); w.y = cvt_pk_bf16(v0[2], v0[3]); w.z = cvt_pk_bf16(v1[0], v1[1]); w.w = cvt_pk_bf16(v1[2], v1[3]);
;                 *(u32x4*)rowp = w; }
	v_lshlrev_b64 v[146:147], 1, v[146:147]
	v_lshl_add_u64 v[162:163], v[162:163], 0, v[146:147]
	v_mul_f32_e32 v124, v165, v155
	v_mul_f32_e32 v126, v164, v155
	v_pk_mul_f32 v[126:127], v[160:161], v[126:127] op_sel_hi:[1,0]
	v_pk_mul_f32 v[124:125], v[156:157], v[124:125] op_sel_hi:[1,0]
	v_pk_mul_f32 v[122:123], v[122:123], v[126:127]
	v_pk_mul_f32 v[120:121], v[120:121], v[124:125]
	v_pk_mul_f32 v[122:123], v[122:123], v[114:115]
	v_pk_mul_f32 v[114:115], v[120:121], v[112:113]
	v_cvt_pk_bf16_f32 v112, v116, v117
	v_cvt_pk_bf16_f32 v113, v118, v119
	v_max_f32_e32 v116, 0xc1a00000, v108
	v_max_f32_e32 v118, 0xc1a00000, v110
	v_mul_f32_e32 v116, 0xbfb8aa3b, v116
	v_mul_f32_e32 v118, 0xbfb8aa3b, v118
	v_exp_f32_e32 v117, v116
	v_exp_f32_e32 v119, v118
	v_max_f32_e32 v116, 0xc1a00000, v109
	v_max_f32_e32 v118, 0xc1a00000, v111
	v_mul_f32_e32 v116, 0xbfb8aa3b, v116
	v_mul_f32_e32 v118, 0xbfb8aa3b, v118
	v_exp_f32_e32 v116, v116
	v_exp_f32_e32 v118, v118
	v_cvt_pk_bf16_f32 v114, v114, v115
	v_cvt_pk_bf16_f32 v115, v122, v123
	global_store_dwordx4 v[162:163], v[112:115], off
	v_or_b32_e32 v120, 16, v154
	s_and_b64 vcc, exec, s[2:3]
	v_pk_add_f32 v[112:113], v[116:117], 1.0 op_sel_hi:[1,0]
	v_pk_add_f32 v[114:115], v[118:119], 1.0 op_sel_hi:[1,0]
	v_mov_b32_e32 v116, v113
	v_mov_b32_e32 v117, v115
	v_mov_b32_e32 v118, v112
	v_mov_b32_e32 v119, v114
	v_pk_mul_f32 v[116:117], v[116:117], v[118:119]
	s_mov_b32 s41, s6
	v_mul_f32_e32 v118, v116, v117
	v_rcp_f32_e32 v121, v118
	v_mad_i64_i32 v[118:119], s[16:17], v120, s40, v[144:145]
	v_lshl_add_u64 v[118:119], v[118:119], 0, v[146:147]
	v_mul_f32_e32 v116, v116, v121
	v_mul_f32_e32 v120, v117, v121
	v_pk_mul_f32 v[114:115], v[114:115], v[116:117] op_sel_hi:[1,0]
	v_max_f32_e32 v116, 0xc1a00000, v104
	v_max_f32_e32 v121, 0xc1a00000, v106
	v_mul_f32_e32 v116, 0xbfb8aa3b, v116
	v_mul_f32_e32 v121, 0xbfb8aa3b, v121
	v_exp_f32_e32 v117, v116
	v_exp_f32_e32 v123, v121
	v_max_f32_e32 v116, 0xc1a00000, v105
	v_max_f32_e32 v121, 0xc1a00000, v107
	v_mul_f32_e32 v116, 0xbfb8aa3b, v116
	v_mul_f32_e32 v121, 0xbfb8aa3b, v121
	v_exp_f32_e32 v116, v116
	v_exp_f32_e32 v122, v121
	v_pk_mul_f32 v[112:113], v[112:113], v[120:121] op_sel_hi:[1,0]
	v_pk_mul_f32 v[110:111], v[110:111], v[114:115]
	v_pk_mul_f32 v[108:109], v[108:109], v[112:113]
	v_pk_add_f32 v[112:113], v[116:117], 1.0 op_sel_hi:[1,0]
	v_pk_add_f32 v[116:117], v[122:123], 1.0 op_sel_hi:[1,0]
	v_mov_b32_e32 v120, v113
	v_mov_b32_e32 v121, v117
	v_mov_b32_e32 v122, v112
	v_mov_b32_e32 v123, v116
	v_pk_mul_f32 v[120:121], v[120:121], v[122:123]
	v_pk_mul_f32 v[102:103], v[110:111], v[102:103]
	v_mul_f32_e32 v122, v120, v121
	v_rcp_f32_e32 v122, v122
	v_pk_mul_f32 v[100:101], v[108:109], v[100:101]
	s_mov_b32 s14, s8
	s_mov_b64 s[18:19], s[12:13]
	v_mul_f32_e32 v108, v121, v122
	v_mul_f32_e32 v110, v120, v122
	v_pk_mul_f32 v[110:111], v[116:117], v[110:111] op_sel_hi:[1,0]
	v_pk_mul_f32 v[108:109], v[112:113], v[108:109] op_sel_hi:[1,0]
	v_pk_mul_f32 v[106:107], v[106:107], v[110:111]
	v_pk_mul_f32 v[104:105], v[104:105], v[108:109]
	v_pk_mul_f32 v[106:107], v[106:107], v[98:99]
	v_pk_mul_f32 v[98:99], v[104:105], v[96:97]
	v_cvt_pk_bf16_f32 v96, v100, v101
	v_cvt_pk_bf16_f32 v97, v102, v103
	v_max_f32_e32 v100, 0xc1a00000, v92
	v_max_f32_e32 v102, 0xc1a00000, v94
	v_mul_f32_e32 v100, 0xbfb8aa3b, v100
	v_mul_f32_e32 v102, 0xbfb8aa3b, v102
	v_exp_f32_e32 v101, v100
	v_exp_f32_e32 v103, v102
	v_max_f32_e32 v100, 0xc1a00000, v93
	v_max_f32_e32 v102, 0xc1a00000, v95
	v_mul_f32_e32 v100, 0xbfb8aa3b, v100
	v_mul_f32_e32 v102, 0xbfb8aa3b, v102
	v_exp_f32_e32 v100, v100
	v_exp_f32_e32 v102, v102
	v_cvt_pk_bf16_f32 v98, v98, v99
	v_cvt_pk_bf16_f32 v99, v106, v107
	global_store_dwordx4 v[118:119], v[96:99], off
	v_or_b32_e32 v104, 32, v154
	s_nop 0
	v_pk_add_f32 v[96:97], v[100:101], 1.0 op_sel_hi:[1,0]
	v_pk_add_f32 v[98:99], v[102:103], 1.0 op_sel_hi:[1,0]
	v_mov_b32_e32 v100, v97
	v_mov_b32_e32 v101, v99
	v_mov_b32_e32 v102, v96
	v_mov_b32_e32 v103, v98
	v_pk_mul_f32 v[100:101], v[100:101], v[102:103]
	s_nop 0
	v_mul_f32_e32 v102, v100, v101
	v_rcp_f32_e32 v105, v102
	v_mad_i64_i32 v[102:103], s[16:17], v104, s40, v[144:145]
	v_lshl_add_u64 v[102:103], v[102:103], 0, v[146:147]
	v_mul_f32_e32 v100, v100, v105
	v_mul_f32_e32 v104, v101, v105
	v_pk_mul_f32 v[98:99], v[98:99], v[100:101] op_sel_hi:[1,0]
	v_max_f32_e32 v100, 0xc1a00000, v88
	v_max_f32_e32 v105, 0xc1a00000, v90
	v_mul_f32_e32 v100, 0xbfb8aa3b, v100
	v_mul_f32_e32 v105, 0xbfb8aa3b, v105
	v_exp_f32_e32 v101, v100
	v_exp_f32_e32 v107, v105
	v_max_f32_e32 v100, 0xc1a00000, v89
	v_max_f32_e32 v105, 0xc1a00000, v91
	v_mul_f32_e32 v100, 0xbfb8aa3b, v100
	v_mul_f32_e32 v105, 0xbfb8aa3b, v105
	v_exp_f32_e32 v100, v100
	v_exp_f32_e32 v106, v105
	v_pk_mul_f32 v[96:97], v[96:97], v[104:105] op_sel_hi:[1,0]
	v_pk_mul_f32 v[94:95], v[94:95], v[98:99]
	v_pk_mul_f32 v[92:93], v[92:93], v[96:97]
	v_pk_add_f32 v[96:97], v[100:101], 1.0 op_sel_hi:[1,0]
	v_pk_add_f32 v[100:101], v[106:107], 1.0 op_sel_hi:[1,0]
	v_mov_b32_e32 v104, v97
	v_mov_b32_e32 v105, v101
	v_mov_b32_e32 v106, v96
	v_mov_b32_e32 v107, v100
	v_pk_mul_f32 v[104:105], v[104:105], v[106:107]
	v_pk_mul_f32 v[86:87], v[94:95], v[86:87]
	v_mul_f32_e32 v106, v104, v105
	v_rcp_f32_e32 v106, v106
	v_pk_mul_f32 v[84:85], v[92:93], v[84:85]
	v_mul_f32_e32 v92, v105, v106
	v_mul_f32_e32 v94, v104, v106
	v_pk_mul_f32 v[94:95], v[100:101], v[94:95] op_sel_hi:[1,0]
	v_pk_mul_f32 v[92:93], v[96:97], v[92:93] op_sel_hi:[1,0]
	v_pk_mul_f32 v[90:91], v[90:91], v[94:95]
	v_pk_mul_f32 v[88:89], v[88:89], v[92:93]
	v_pk_mul_f32 v[90:91], v[90:91], v[82:83]
; __device__ __forceinline__ unsigned cvt_pk_bf16(float lo, float hi) { unsigned r; asm volatile("v_cvt_pk_bf16_f32 %0, %1, %2" : "=v"(r) : "v"(lo), "v"(hi)); return r; }
; __device__ __forceinline__ f32x4 sigmoid4(f32x4 x) {
;     f32x4 d;
; #pragma unroll
;     for (int j = 0; j < 4; ++j) d[j] = 1.0f + __expf(-fmaxf(x[j], -20.0f));
;     const float p01 = d[0] * d[1], p23 = d[2] * d[3], r = __builtin_amdgcn_rcpf(p01 * p23), r01 = r * p23, r23 = r * p01;
;     return (f32x4){r01 * d[1], r01 * d[0], r23 * d[3], r23 * d[2]};
; }
;     __device__ __forceinline__ void operator()(const f32x4 (&acc)[2][2][4][2], const Unit& u, int wr, int wc, int fr, int fq) const {
;         const int row0 = u.pm * BM + wr * 64 + fr, col0 = u.pn * HALF + wc * 32 + 8 * fq;
; #pragma unroll
;         for (int ai = 0; ai < 2; ++ai)
; #pragma unroll
;             for (int m = 0; m < 4; ++m) { bf16_t* rowp = O + (size_t)(row0 + ai * HALF + m * 16) * ldc + col0;
;                 f32x4 v0, v1;
; #pragma unroll
;                 for (int j = 0; j < 1; ++j) { v0 = acc[ai][0][m][0] * sigmoid4(acc[ai][0][m][0]) * acc[ai][1][m][0]; v1 = acc[ai][0][m][1] * sigmoid4(acc[ai][0][m][1]) * acc[ai][1][m][1]; }
;                 u32x4 w; w.x = cvt_pk_bf16(v0[0], v0[1]); w.y = cvt_pk_bf16(v0[2], v0[3]); w.z = cvt_pk_bf16(v1[0], v1[1]); w.w = cvt_pk_bf16(v1[2], v1[3]);
;                 *(u32x4*)rowp = w; }
	v_pk_mul_f32 v[82:83], v[88:89], v[80:81]
	v_cvt_pk_bf16_f32 v80, v84, v85
	v_cvt_pk_bf16_f32 v81, v86, v87
	v_max_f32_e32 v84, 0xc1a00000, v76
	v_max_f32_e32 v86, 0xc1a00000, v78
	v_mul_f32_e32 v84, 0xbfb8aa3b, v84
	v_mul_f32_e32 v86, 0xbfb8aa3b, v86
	v_exp_f32_e32 v85, v84
	v_exp_f32_e32 v87, v86
	v_max_f32_e32 v84, 0xc1a00000, v77
	v_max_f32_e32 v86, 0xc1a00000, v79
	v_mul_f32_e32 v84, 0xbfb8aa3b, v84
	v_mul_f32_e32 v86, 0xbfb8aa3b, v86
	v_exp_f32_e32 v84, v84
	v_exp_f32_e32 v86, v86
	v_cvt_pk_bf16_f32 v82, v82, v83
	v_cvt_pk_bf16_f32 v83, v90, v91
	global_store_dwordx4 v[102:103], v[80:83], off
	v_or_b32_e32 v88, 48, v154
	s_nop 0
	v_pk_add_f32 v[80:81], v[84:85], 1.0 op_sel_hi:[1,0]
	v_pk_add_f32 v[82:83], v[86:87], 1.0 op_sel_hi:[1,0]
	v_mov_b32_e32 v84, v81
	v_mov_b32_e32 v85, v83
	v_mov_b32_e32 v86, v80
	v_mov_b32_e32 v87, v82
	v_pk_mul_f32 v[84:85], v[84:85], v[86:87]
	s_nop 0
	v_mul_f32_e32 v86, v84, v85
	v_rcp_f32_e32 v89, v86
	v_mad_i64_i32 v[86:87], s[16:17], v88, s40, v[144:145]
	v_lshl_add_u64 v[86:87], v[86:87], 0, v[146:147]
	v_mul_f32_e32 v84, v84, v89
	v_mul_f32_e32 v88, v85, v89
	v_pk_mul_f32 v[82:83], v[82:83], v[84:85] op_sel_hi:[1,0]
	v_max_f32_e32 v84, 0xc1a00000, v72
	v_max_f32_e32 v89, 0xc1a00000, v74
	v_mul_f32_e32 v84, 0xbfb8aa3b, v84
	v_mul_f32_e32 v89, 0xbfb8aa3b, v89
	v_exp_f32_e32 v85, v84
	v_exp_f32_e32 v91, v89
	v_max_f32_e32 v84, 0xc1a00000, v73
	v_max_f32_e32 v89, 0xc1a00000, v75
	v_mul_f32_e32 v84, 0xbfb8aa3b, v84
	v_mul_f32_e32 v89, 0xbfb8aa3b, v89
	v_exp_f32_e32 v84, v84
	v_exp_f32_e32 v90, v89
	v_pk_mul_f32 v[80:81], v[80:81], v[88:89] op_sel_hi:[1,0]
	v_pk_mul_f32 v[78:79], v[78:79], v[82:83]
	v_pk_mul_f32 v[76:77], v[76:77], v[80:81]
	v_pk_add_f32 v[80:81], v[84:85], 1.0 op_sel_hi:[1,0]
	v_pk_add_f32 v[84:85], v[90:91], 1.0 op_sel_hi:[1,0]
	v_mov_b32_e32 v88, v81
	v_mov_b32_e32 v89, v85
	v_mov_b32_e32 v90, v80
	v_mov_b32_e32 v91, v84
	v_pk_mul_f32 v[88:89], v[88:89], v[90:91]
	v_pk_mul_f32 v[70:71], v[78:79], v[70:71]
	v_mul_f32_e32 v90, v88, v89
	v_rcp_f32_e32 v90, v90
	v_pk_mul_f32 v[68:69], v[76:77], v[68:69]
	v_mul_f32_e32 v76, v89, v90
	v_mul_f32_e32 v78, v88, v90
	v_pk_mul_f32 v[78:79], v[84:85], v[78:79] op_sel_hi:[1,0]
	v_pk_mul_f32 v[76:77], v[80:81], v[76:77] op_sel_hi:[1,0]
	v_pk_mul_f32 v[74:75], v[74:75], v[78:79]
	v_pk_mul_f32 v[72:73], v[72:73], v[76:77]
	v_pk_mul_f32 v[74:75], v[74:75], v[66:67]
	v_pk_mul_f32 v[66:67], v[72:73], v[64:65]
	v_cvt_pk_bf16_f32 v64, v68, v69
	v_cvt_pk_bf16_f32 v65, v70, v71
	v_max_f32_e32 v68, 0xc1a00000, v60
	v_max_f32_e32 v70, 0xc1a00000, v62
	v_mul_f32_e32 v68, 0xbfb8aa3b, v68
	v_mul_f32_e32 v70, 0xbfb8aa3b, v70
	v_exp_f32_e32 v69, v68
	v_exp_f32_e32 v71, v70
	v_max_f32_e32 v68, 0xc1a00000, v61
	v_max_f32_e32 v70, 0xc1a00000, v63
	v_mul_f32_e32 v68, 0xbfb8aa3b, v68
	v_mul_f32_e32 v70, 0xbfb8aa3b, v70
	v_exp_f32_e32 v68, v68
	v_exp_f32_e32 v70, v70
	v_cvt_pk_bf16_f32 v66, v66, v67
	v_cvt_pk_bf16_f32 v67, v74, v75
	global_store_dwordx4 v[86:87], v[64:67], off
	v_add_u32_e32 v72, 0x80, v154
	s_nop 0
	v_pk_add_f32 v[64:65], v[68:69], 1.0 op_sel_hi:[1,0]
	v_pk_add_f32 v[66:67], v[70:71], 1.0 op_sel_hi:[1,0]
	v_mov_b32_e32 v68, v65
	v_mov_b32_e32 v69, v67
	v_mov_b32_e32 v70, v64
	v_mov_b32_e32 v71, v66
	v_pk_mul_f32 v[68:69], v[68:69], v[70:71]
	s_nop 0
	v_mul_f32_e32 v70, v68, v69
	v_rcp_f32_e32 v73, v70
	v_mad_i64_i32 v[70:71], s[16:17], v72, s40, v[144:145]
	v_lshl_add_u64 v[70:71], v[70:71], 0, v[146:147]
	v_mul_f32_e32 v68, v68, v73
	v_mul_f32_e32 v72, v69, v73
	v_pk_mul_f32 v[66:67], v[66:67], v[68:69] op_sel_hi:[1,0]
	v_max_f32_e32 v68, 0xc1a00000, v56
	v_max_f32_e32 v73, 0xc1a00000, v58
	v_mul_f32_e32 v68, 0xbfb8aa3b, v68
	v_mul_f32_e32 v73, 0xbfb8aa3b, v73
	v_exp_f32_e32 v69, v68
	v_exp_f32_e32 v75, v73
	v_max_f32_e32 v68, 0xc1a00000, v57
	v_max_f32_e32 v73, 0xc1a00000, v59
	v_mul_f32_e32 v68, 0xbfb8aa3b, v68
	v_mul_f32_e32 v73, 0xbfb8aa3b, v73
	v_exp_f32_e32 v68, v68
	v_exp_f32_e32 v74, v73
	v_pk_mul_f32 v[64:65], v[64:65], v[72:73] op_sel_hi:[1,0]
	v_pk_mul_f32 v[62:63], v[62:63], v[66:67]
	v_pk_mul_f32 v[60:61], v[60:61], v[64:65]
	v_pk_add_f32 v[64:65], v[68:69], 1.0 op_sel_hi:[1,0]
	v_pk_add_f32 v[68:69], v[74:75], 1.0 op_sel_hi:[1,0]
	v_mov_b32_e32 v72, v65
	v_mov_b32_e32 v73, v69
	v_mov_b32_e32 v74, v64
	v_mov_b32_e32 v75, v68
	v_pk_mul_f32 v[72:73], v[72:73], v[74:75]
	v_pk_mul_f32 v[54:55], v[62:63], v[54:55]
	v_mul_f32_e32 v74, v72, v73
	v_rcp_f32_e32 v74, v74
	v_pk_mul_f32 v[52:53], v[60:61], v[52:53]
	v_mul_f32_e32 v60, v73, v74
	v_mul_f32_e32 v62, v72, v74
	v_pk_mul_f32 v[62:63], v[68:69], v[62:63] op_sel_hi:[1,0]
	v_pk_mul_f32 v[60:61], v[64:65], v[60:61] op_sel_hi:[1,0]
	v_pk_mul_f32 v[58:59], v[58:59], v[62:63]
	v_pk_mul_f32 v[56:57], v[56:57], v[60:61]
	v_pk_mul_f32 v[58:59], v[58:59], v[50:51]
	v_pk_mul_f32 v[50:51], v[56:57], v[48:49]
	v_cvt_pk_bf16_f32 v48, v52, v53
	v_cvt_pk_bf16_f32 v49, v54, v55
	v_max_f32_e32 v52, 0xc1a00000, v44
	v_max_f32_e32 v54, 0xc1a00000, v46
	v_mul_f32_e32 v52, 0xbfb8aa3b, v52
	v_mul_f32_e32 v54, 0xbfb8aa3b, v54
	v_exp_f32_e32 v53, v52
	v_exp_f32_e32 v55, v54
	v_max_f32_e32 v52, 0xc1a00000, v45
	v_max_f32_e32 v54, 0xc1a00000, v47
	v_mul_f32_e32 v52, 0xbfb8aa3b, v52
	v_mul_f32_e32 v54, 0xbfb8aa3b, v54
	v_exp_f32_e32 v52, v52
	v_exp_f32_e32 v54, v54
	v_cvt_pk_bf16_f32 v50, v50, v51
	v_cvt_pk_bf16_f32 v51, v58, v59
	global_store_dwordx4 v[70:71], v[48:51], off
	v_add_u32_e32 v56, 0x90, v154
	s_nop 0
	v_pk_add_f32 v[48:49], v[52:53], 1.0 op_sel_hi:[1,0]
	v_pk_add_f32 v[50:51], v[54:55], 1.0 op_sel_hi:[1,0]
	v_mov_b32_e32 v52, v49
	v_mov_b32_e32 v53, v51
	v_mov_b32_e32 v54, v48
	v_mov_b32_e32 v55, v50
; __device__ __forceinline__ unsigned cvt_pk_bf16(float lo, float hi) { unsigned r; asm volatile("v_cvt_pk_bf16_f32 %0, %1, %2" : "=v"(r) : "v"(lo), "v"(hi)); return r; }
; __device__ __forceinline__ f32x4 sigmoid4(f32x4 x) {
;     f32x4 d;
; #pragma unroll
;     for (int j = 0; j < 4; ++j) d[j] = 1.0f + __expf(-fmaxf(x[j], -20.0f));
;     const float p01 = d[0] * d[1], p23 = d[2] * d[3], r = __builtin_amdgcn_rcpf(p01 * p23), r01 = r * p23, r23 = r * p01;
;     return (f32x4){r01 * d[1], r01 * d[0], r23 * d[3], r23 * d[2]};
; }
;     __device__ __forceinline__ void operator()(const f32x4 (&acc)[2][2][4][2], const Unit& u, int wr, int wc, int fr, int fq) const {
;         const int row0 = u.pm * BM + wr * 64 + fr, col0 = u.pn * HALF + wc * 32 + 8 * fq;
; #pragma unroll
;         for (int ai = 0; ai < 2; ++ai)
; #pragma unroll
;             for (int m = 0; m < 4; ++m) { bf16_t* rowp = O + (size_t)(row0 + ai * HALF + m * 16) * ldc + col0;
;                 f32x4 v0, v1;
; #pragma unroll
;                 for (int j = 0; j < 1; ++j) { v0 = acc[ai][0][m][0] * sigmoid4(acc[ai][0][m][0]) * acc[ai][1][m][0]; v1 = acc[ai][0][m][1] * sigmoid4(acc[ai][0][m][1]) * acc[ai][1][m][1]; }
;                 u32x4 w; w.x = cvt_pk_bf16(v0[0], v0[1]); w.y = cvt_pk_bf16(v0[2], v0[3]); w.z = cvt_pk_bf16(v1[0], v1[1]); w.w = cvt_pk_bf16(v1[2], v1[3]);
;                 *(u32x4*)rowp = w; }
	v_pk_mul_f32 v[52:53], v[52:53], v[54:55]
	s_nop 0
	v_mul_f32_e32 v54, v52, v53
	v_rcp_f32_e32 v57, v54
	v_mad_i64_i32 v[54:55], s[16:17], v56, s40, v[144:145]
	v_lshl_add_u64 v[54:55], v[54:55], 0, v[146:147]
	v_mul_f32_e32 v52, v52, v57
	v_mul_f32_e32 v56, v53, v57
	v_pk_mul_f32 v[50:51], v[50:51], v[52:53] op_sel_hi:[1,0]
	v_max_f32_e32 v52, 0xc1a00000, v40
	v_max_f32_e32 v57, 0xc1a00000, v42
	v_mul_f32_e32 v52, 0xbfb8aa3b, v52
	v_mul_f32_e32 v57, 0xbfb8aa3b, v57
	v_exp_f32_e32 v53, v52
	v_exp_f32_e32 v59, v57
	v_max_f32_e32 v52, 0xc1a00000, v41
	v_max_f32_e32 v57, 0xc1a00000, v43
	v_mul_f32_e32 v52, 0xbfb8aa3b, v52
	v_mul_f32_e32 v57, 0xbfb8aa3b, v57
	v_exp_f32_e32 v52, v52
	v_exp_f32_e32 v58, v57
	v_pk_mul_f32 v[48:49], v[48:49], v[56:57] op_sel_hi:[1,0]
	v_pk_mul_f32 v[46:47], v[46:47], v[50:51]
	v_pk_mul_f32 v[44:45], v[44:45], v[48:49]
	v_pk_add_f32 v[48:49], v[52:53], 1.0 op_sel_hi:[1,0]
	v_pk_add_f32 v[52:53], v[58:59], 1.0 op_sel_hi:[1,0]
	v_mov_b32_e32 v56, v49
	v_mov_b32_e32 v57, v53
	v_mov_b32_e32 v58, v48
	v_mov_b32_e32 v59, v52
	v_pk_mul_f32 v[56:57], v[56:57], v[58:59]
	v_pk_mul_f32 v[38:39], v[46:47], v[38:39]
	v_mul_f32_e32 v58, v56, v57
	v_rcp_f32_e32 v58, v58
	v_pk_mul_f32 v[36:37], v[44:45], v[36:37]
	v_mul_f32_e32 v44, v57, v58
	v_mul_f32_e32 v46, v56, v58
	v_pk_mul_f32 v[46:47], v[52:53], v[46:47] op_sel_hi:[1,0]
	v_pk_mul_f32 v[44:45], v[48:49], v[44:45] op_sel_hi:[1,0]
	v_pk_mul_f32 v[42:43], v[42:43], v[46:47]
	v_pk_mul_f32 v[40:41], v[40:41], v[44:45]
	v_pk_mul_f32 v[42:43], v[42:43], v[34:35]
	v_pk_mul_f32 v[34:35], v[40:41], v[32:33]
	v_cvt_pk_bf16_f32 v32, v36, v37
	v_cvt_pk_bf16_f32 v33, v38, v39
	v_max_f32_e32 v36, 0xc1a00000, v28
	v_max_f32_e32 v38, 0xc1a00000, v30
	v_mul_f32_e32 v36, 0xbfb8aa3b, v36
	v_mul_f32_e32 v38, 0xbfb8aa3b, v38
	v_exp_f32_e32 v37, v36
	v_exp_f32_e32 v39, v38
	v_max_f32_e32 v36, 0xc1a00000, v29
	v_max_f32_e32 v38, 0xc1a00000, v31
	v_mul_f32_e32 v36, 0xbfb8aa3b, v36
	v_mul_f32_e32 v38, 0xbfb8aa3b, v38
	v_exp_f32_e32 v36, v36
	v_exp_f32_e32 v38, v38
	v_cvt_pk_bf16_f32 v34, v34, v35
	v_cvt_pk_bf16_f32 v35, v42, v43
	global_store_dwordx4 v[54:55], v[32:35], off
	v_add_u32_e32 v40, 0xa0, v154
	s_nop 0
	v_pk_add_f32 v[32:33], v[36:37], 1.0 op_sel_hi:[1,0]
	v_pk_add_f32 v[34:35], v[38:39], 1.0 op_sel_hi:[1,0]
	v_mov_b32_e32 v36, v33
	v_mov_b32_e32 v37, v35
	v_mov_b32_e32 v38, v32
	v_mov_b32_e32 v39, v34
	v_pk_mul_f32 v[36:37], v[36:37], v[38:39]
	s_nop 0
	v_mul_f32_e32 v38, v36, v37
	v_rcp_f32_e32 v41, v38
	v_mad_i64_i32 v[38:39], s[16:17], v40, s40, v[144:145]
	v_lshl_add_u64 v[38:39], v[38:39], 0, v[146:147]
	v_mul_f32_e32 v36, v36, v41
	v_mul_f32_e32 v40, v37, v41
	v_pk_mul_f32 v[34:35], v[34:35], v[36:37] op_sel_hi:[1,0]
	v_max_f32_e32 v36, 0xc1a00000, v24
	v_max_f32_e32 v41, 0xc1a00000, v26
	v_mul_f32_e32 v36, 0xbfb8aa3b, v36
	v_mul_f32_e32 v41, 0xbfb8aa3b, v41
	v_exp_f32_e32 v37, v36
	v_exp_f32_e32 v43, v41
	v_max_f32_e32 v36, 0xc1a00000, v25
	v_max_f32_e32 v41, 0xc1a00000, v27
	v_mul_f32_e32 v36, 0xbfb8aa3b, v36
	v_mul_f32_e32 v41, 0xbfb8aa3b, v41
	v_exp_f32_e32 v36, v36
	v_exp_f32_e32 v42, v41
	v_pk_mul_f32 v[32:33], v[32:33], v[40:41] op_sel_hi:[1,0]
	v_pk_mul_f32 v[30:31], v[30:31], v[34:35]
	v_pk_mul_f32 v[28:29], v[28:29], v[32:33]
	v_pk_add_f32 v[32:33], v[36:37], 1.0 op_sel_hi:[1,0]
	v_pk_add_f32 v[36:37], v[42:43], 1.0 op_sel_hi:[1,0]
	v_mov_b32_e32 v40, v33
	v_mov_b32_e32 v41, v37
	v_mov_b32_e32 v42, v32
	v_mov_b32_e32 v43, v36
	v_pk_mul_f32 v[40:41], v[40:41], v[42:43]
	v_pk_mul_f32 v[22:23], v[30:31], v[22:23]
	v_mul_f32_e32 v42, v40, v41
	v_rcp_f32_e32 v42, v42
	v_pk_mul_f32 v[20:21], v[28:29], v[20:21]
	v_mul_f32_e32 v28, v41, v42
	v_mul_f32_e32 v30, v40, v42
	v_pk_mul_f32 v[30:31], v[36:37], v[30:31] op_sel_hi:[1,0]
	v_pk_mul_f32 v[28:29], v[32:33], v[28:29] op_sel_hi:[1,0]
	v_pk_mul_f32 v[26:27], v[26:27], v[30:31]
	v_pk_mul_f32 v[24:25], v[24:25], v[28:29]
	v_pk_mul_f32 v[26:27], v[26:27], v[18:19]
	v_pk_mul_f32 v[18:19], v[24:25], v[16:17]
	v_cvt_pk_bf16_f32 v16, v20, v21
	v_cvt_pk_bf16_f32 v17, v22, v23
	v_max_f32_e32 v20, 0xc1a00000, v12
	v_max_f32_e32 v22, 0xc1a00000, v14
	v_mul_f32_e32 v20, 0xbfb8aa3b, v20
	v_mul_f32_e32 v22, 0xbfb8aa3b, v22
	v_exp_f32_e32 v21, v20
	v_exp_f32_e32 v23, v22
	v_max_f32_e32 v20, 0xc1a00000, v13
	v_max_f32_e32 v22, 0xc1a00000, v15
	v_mul_f32_e32 v20, 0xbfb8aa3b, v20
	v_mul_f32_e32 v22, 0xbfb8aa3b, v22
	v_exp_f32_e32 v20, v20
	v_exp_f32_e32 v22, v22
	v_cvt_pk_bf16_f32 v18, v18, v19
	v_cvt_pk_bf16_f32 v19, v26, v27
	global_store_dwordx4 v[38:39], v[16:19], off
	v_add_u32_e32 v24, 0xb0, v154
	s_nop 0
	v_pk_add_f32 v[16:17], v[20:21], 1.0 op_sel_hi:[1,0]
	v_pk_add_f32 v[18:19], v[22:23], 1.0 op_sel_hi:[1,0]
	v_mov_b32_e32 v20, v17
	v_mov_b32_e32 v21, v19
	v_mov_b32_e32 v22, v16
	v_mov_b32_e32 v23, v18
	v_pk_mul_f32 v[20:21], v[20:21], v[22:23]
	s_nop 0
	v_mul_f32_e32 v22, v20, v21
	v_rcp_f32_e32 v25, v22
	v_mad_i64_i32 v[22:23], s[16:17], v24, s40, v[144:145]
	v_lshl_add_u64 v[22:23], v[22:23], 0, v[146:147]
	v_mul_f32_e32 v20, v20, v25
	v_mul_f32_e32 v24, v21, v25
	v_pk_mul_f32 v[18:19], v[18:19], v[20:21] op_sel_hi:[1,0]
	v_max_f32_e32 v20, 0xc1a00000, v8
	v_max_f32_e32 v25, 0xc1a00000, v10
	v_mul_f32_e32 v20, 0xbfb8aa3b, v20
	v_mul_f32_e32 v25, 0xbfb8aa3b, v25
	v_exp_f32_e32 v21, v20
	v_exp_f32_e32 v27, v25
	v_max_f32_e32 v20, 0xc1a00000, v9
	v_max_f32_e32 v25, 0xc1a00000, v11
	v_mul_f32_e32 v20, 0xbfb8aa3b, v20
	v_mul_f32_e32 v25, 0xbfb8aa3b, v25
	v_exp_f32_e32 v20, v20
	v_exp_f32_e32 v26, v25
	v_pk_mul_f32 v[16:17], v[16:17], v[24:25] op_sel_hi:[1,0]
	v_pk_mul_f32 v[14:15], v[14:15], v[18:19]
	v_pk_mul_f32 v[12:13], v[12:13], v[16:17]
	v_pk_add_f32 v[16:17], v[20:21], 1.0 op_sel_hi:[1,0]
	v_pk_add_f32 v[20:21], v[26:27], 1.0 op_sel_hi:[1,0]
	v_mov_b32_e32 v24, v17
	v_mov_b32_e32 v25, v21
	v_mov_b32_e32 v26, v16
	v_mov_b32_e32 v27, v20
	v_pk_mul_f32 v[24:25], v[24:25], v[26:27]
	v_pk_mul_f32 v[6:7], v[14:15], v[6:7]
	v_mul_f32_e32 v26, v24, v25
	v_rcp_f32_e32 v26, v26
	v_pk_mul_f32 v[4:5], v[12:13], v[4:5]
	s_mov_b64 s[16:17], s[10:11]
	v_mul_f32_e32 v12, v25, v26
	v_mul_f32_e32 v14, v24, v26
	v_pk_mul_f32 v[14:15], v[20:21], v[14:15] op_sel_hi:[1,0]
	v_pk_mul_f32 v[12:13], v[16:17], v[12:13] op_sel_hi:[1,0]
	v_pk_mul_f32 v[10:11], v[10:11], v[14:15]
	v_pk_mul_f32 v[8:9], v[8:9], v[12:13]
	v_pk_mul_f32 v[10:11], v[10:11], v[2:3]
	v_pk_mul_f32 v[2:3], v[8:9], v[0:1]
	v_cvt_pk_bf16_f32 v0, v4, v5
	v_cvt_pk_bf16_f32 v1, v6, v7
	s_nop 0
	v_cvt_pk_bf16_f32 v2, v2, v3
	v_cvt_pk_bf16_f32 v3, v10, v11
	global_store_dwordx4 v[22:23], v[0:3], off
	s_cbranch_vccz .LBB0_1199
	s_waitcnt vmcnt(0)
	s_cmpk_gt_u32 s23, 0xff
	s_cbranch_scc1 .LBB0_1206
	s_barrier
